# v36: v34 + alias drains removed in sample-chain gemm_tile loops; G1 start stagger removed
# speedup vs baseline: 1.0365x; 1.0039x over previous
; template <class FL, class FS>
; DI void gemm_dispatch(const Sub& s, char* lds_all, const bf16_t* A, const bf16_t* Bt, const int nN256, FL fl, FS fs) {
;   if (!s.samp) {
;     const int nM = 256;
;     for (int L = blockIdx.x; L < nM * nN256; L += gridDim.x) {
;       int pm, pn; tile8_order(L, nM, nN256, pm, pn);
;       gemm8_tile(lds_all, A, Bt, D, pm * 256, pn * 256, fl, fs);
; DI void phase_g1(const Params& p, const Sub& s, char* lds_all) {
;   const bf16_t* A = (const bf16_t*)(p.ws + W_SLOT0);
;   const bf16_t* Bt = (const bf16_t*)(p.ws + W_S5IN);
;   bf16_t* ugm = (bf16_t*)(p.ws + W_SLOT1);
;   bf16_t* z = (bf16_t*)(p.ws + W_SLOT2);
;   float* us = (float*)(p.ws + W_USAMP);
;   {
;     gemm_dispatch(s, lds_all, A, Bt, 8,
.LBB0_195:
	s_or_b64 exec, exec, s[4:5]
	v_readlane_b32 s0, v251, 0
	s_cmpk_gt_i32 s0, 0x7ff
	s_mov_b32 s33, 0
	s_mov_b32 s0, 0
	s_waitcnt lgkmcnt(0)
	v_mov_b32_e32 v0, v182
	s_barrier
	s_cbranch_scc1 .LBB0_460
	s_ashr_i32 s1, s0, 31
	v_readlane_b32 s2, v251, 3
	v_readlane_b32 s3, v251, 4
	s_add_u32 s0, s2, s0
	s_addc_u32 s1, s3, s1
	s_load_dwordx2 s[12:13], s[0:1], 0xf8
	s_mov_b32 s42, 0x10000
	s_mov_b32 s43, 0x14000
	s_mov_b64 s[14:15], 0x80
	s_mov_b32 s46, 0x18000
	s_waitcnt lgkmcnt(0)
	s_add_u32 s44, s12, 0x1800000
	s_addc_u32 s45, s13, 0
	s_add_u32 s16, s12, 0x9880000
	s_addc_u32 s17, s13, 0
	s_add_u32 s18, s12, 0x11900000
	s_addc_u32 s19, s13, 0
	s_add_u32 s20, s12, 0x1514000
	s_addc_u32 s21, s13, 0
	s_mov_b32 s47, 0x1c000
	s_mov_b64 s[22:23], 0x1840080
	s_mov_b64 s[24:25], 0x100
	s_mov_b64 s[26:27], 0x1800100
	s_mov_b64 s[28:29], 0x40100
	s_mov_b64 s[30:31], 0x1840100
	s_mov_b64 s[34:35], 0x180
	s_mov_b64 s[36:37], 0x1800180
	s_mov_b64 s[38:39], 0x40180
	s_mov_b64 s[40:41], 0x780
	s_movk_i32 s48, 0x100
	s_mov_b32 s49, 0xffff
	v_mov_b32_e32 v129, 0
	s_movk_i32 s50, 0x3ff
	v_mov_b32_e32 v142, 1
	v_readlane_b32 s51, v251, 0
	s_waitcnt vmcnt(0)
	s_mov_b32 s98, 0
	s_branch .LBB0_199

; #define MFMA16(a, b, c) __builtin_amdgcn_mfma_f32_16x16x32_bf16((a), (b), (c), 0, 0, 0)
; #define LAS __attribute__((address_space(3)))
; template <class FA, class FB, class FL, class FS>
; DI void gemm_tile(char* lds, int ksteps, int rot, FA fa, FB fb, FL fl, FS fs) {
;     ...
;   for (int ks = 0; ks < ksteps; ++ks) {
;     const int cur = ks & 1;
;     if (ks + 1 < ksteps) {
;       int kn = ks + 1 + rot; if (kn >= ksteps) kn -= ksteps;
;       LAS char* dst = l3 + (cur ^ 1) * 32768;
; #pragma unroll
;       for (int i = 0; i < 4; ++i) {
;         const int id = tid + i * 256, r = id >> 3, c = (id & 7) ^ (r & 7);
;         __builtin_amdgcn_global_load_lds((const unsigned*)fa(r, kn * 8 + c), (LAS unsigned*)(dst + id * 16), 16, 0, 0);
;         __builtin_amdgcn_global_load_lds((const unsigned*)fb(r, kn * 8 + c), (LAS unsigned*)(dst + 16384 + id * 16), 16, 0, 0);
;       }
;     }
;     const char* A = lds + cur * 32768;
;     const char* B = A + 16384;
; #pragma unroll
;     for (int kk = 0; kk < 2; ++kk) {
;       bf16x8 af[4], bq[4];
; #pragma unroll
;       for (int m = 0; m < 4; ++m) af[m] = ldfrag(A, 128, wr * 64 + m * 16 + fr, kk * 4 + fq);
; #pragma unroll
;       for (int n = 0; n < 4; ++n) bq[n] = ldfrag(B, 128, wc * 64 + n * 16 + fr, kk * 4 + fq);
; #pragma unroll
;       for (int m = 0; m < 4; ++m)
; #pragma unroll
;         for (int n = 0; n < 4; ++n) acc[m][n] = MFMA16(bq[n], af[m], acc[m][n]);
;     }
;     asm volatile("s_waitcnt vmcnt(0)" ::: "memory");
;     __syncthreads();
.LBB0_1349:
	s_and_b32 s3, s2, 0x8000
	s_xor_b32 s4, s3, 0x8000
	v_add_u32_e32 v120, s3, v85
	v_add_u32_e32 v112, s4, v85
	v_add_u32_e32 v113, v120, v95
	v_add_u32_e32 v114, v112, v86
	v_add_u32_e32 v121, v113, v91
	v_add_u32_e32 v117, v113, v92
	v_readfirstlane_b32 s3, v114
	v_add_u32_e32 v113, 0x4000, v114
	v_lshl_add_u64 v[96:97], v[76:77], 0, s[0:1]
	v_add_u32_e32 v115, v112, v89
	v_readfirstlane_b32 s9, v113
	s_mov_b32 m0, s3
	v_lshl_add_u64 v[98:99], v[78:79], 0, s[0:1]
	v_readfirstlane_b32 s4, v115
	v_add_u32_e32 v114, 0x4000, v115
	global_load_lds_dwordx4 v[96:97], off
	s_mov_b32 m0, s9
	v_lshl_add_u64 v[100:101], v[72:73], 0, s[0:1]
	v_add_u32_e32 v116, v112, v90
	v_readfirstlane_b32 s10, v114
	global_load_lds_dwordx4 v[98:99], off
	s_mov_b32 m0, s4
	v_lshl_add_u64 v[102:103], v[74:75], 0, s[0:1]
	v_readfirstlane_b32 s5, v116
	v_add_u32_e32 v115, 0x4000, v116
	global_load_lds_dwordx4 v[100:101], off
	s_mov_b32 m0, s10
	v_lshl_add_u64 v[104:105], v[68:69], 0, s[0:1]
	v_add_u32_e32 v112, v112, v94
	v_readfirstlane_b32 s11, v115
	global_load_lds_dwordx4 v[102:103], off
	s_mov_b32 m0, s5
	v_lshl_add_u64 v[106:107], v[70:71], 0, s[0:1]
	v_readfirstlane_b32 s8, v112
	v_add_u32_e32 v112, 0x4000, v112
	global_load_lds_dwordx4 v[104:105], off
	s_mov_b32 m0, s11
	v_lshl_add_u64 v[108:109], v[64:65], 0, s[0:1]
	v_readfirstlane_b32 s12, v112
	global_load_lds_dwordx4 v[106:107], off
	s_mov_b32 m0, s8
	v_lshl_add_u64 v[110:111], v[66:67], 0, s[0:1]
	global_load_lds_dwordx4 v[108:109], off
	s_mov_b32 m0, s12
	s_add_i32 s2, s2, 0x8000
	global_load_lds_dwordx4 v[110:111], off
	ds_read_b128 v[96:99], v117 offset:16384
	ds_read_b128 v[100:103], v117 offset:18432
	ds_read_b128 v[104:107], v121
	ds_read_b128 v[108:111], v121 offset:2048
	ds_read_b128 v[112:115], v117 offset:20480
	ds_read_b128 v[116:119], v117 offset:22528
	s_waitcnt lgkmcnt(0)
	v_mfma_f32_16x16x32_bf16 v[60:63], v[96:99], v[104:107], v[60:63]
	s_add_u32 s0, s0, 0x80
	s_addc_u32 s1, s1, 0
	s_cmpk_lg_i32 s0, 0x780
	v_mfma_f32_16x16x32_bf16 v[56:59], v[100:103], v[104:107], v[56:59]
	v_mfma_f32_16x16x32_bf16 v[52:55], v[112:115], v[104:107], v[52:55]
	v_mfma_f32_16x16x32_bf16 v[44:47], v[116:119], v[104:107], v[44:47]
	v_mfma_f32_16x16x32_bf16 v[40:43], v[96:99], v[108:111], v[40:43]
	v_mfma_f32_16x16x32_bf16 v[36:39], v[100:103], v[108:111], v[36:39]
	v_mfma_f32_16x16x32_bf16 v[32:35], v[112:115], v[108:111], v[32:35]
	v_mfma_f32_16x16x32_bf16 v[28:31], v[116:119], v[108:111], v[28:31]
	ds_read_b128 v[104:107], v121 offset:4096
	ds_read_b128 v[108:111], v121 offset:6144
	s_waitcnt lgkmcnt(1)
	v_mfma_f32_16x16x32_bf16 v[24:27], v[96:99], v[104:107], v[24:27]
	s_waitcnt lgkmcnt(0)
	v_mfma_f32_16x16x32_bf16 v[8:11], v[96:99], v[108:111], v[8:11]
	v_add_u32_e32 v96, v120, v93
	v_add_u32_e32 v120, v96, v91
	v_add_u32_e32 v121, v96, v92
	v_mfma_f32_16x16x32_bf16 v[20:23], v[100:103], v[104:107], v[20:23]
	v_mfma_f32_16x16x32_bf16 v[16:19], v[112:115], v[104:107], v[16:19]
	v_mfma_f32_16x16x32_bf16 v[12:15], v[116:119], v[104:107], v[12:15]
	v_mfma_f32_16x16x32_bf16 v[4:7], v[100:103], v[108:111], v[4:7]
	ds_read_b128 v[96:99], v121 offset:16384
	ds_read_b128 v[100:103], v121 offset:18432
	v_mfma_f32_16x16x32_bf16 v[48:51], v[112:115], v[108:111], v[48:51]
	v_mfma_f32_16x16x32_bf16 v[0:3], v[116:119], v[108:111], v[0:3]
	ds_read_b128 v[104:107], v120
	ds_read_b128 v[108:111], v120 offset:2048
	ds_read_b128 v[112:115], v121 offset:20480
	ds_read_b128 v[116:119], v121 offset:22528
	s_waitcnt lgkmcnt(3)
	v_mfma_f32_16x16x32_bf16 v[60:63], v[96:99], v[104:107], v[60:63]
	v_mfma_f32_16x16x32_bf16 v[56:59], v[100:103], v[104:107], v[56:59]
	s_waitcnt lgkmcnt(1)
	v_mfma_f32_16x16x32_bf16 v[52:55], v[112:115], v[104:107], v[52:55]
	s_waitcnt lgkmcnt(0)
	v_mfma_f32_16x16x32_bf16 v[44:47], v[116:119], v[104:107], v[44:47]
	v_mfma_f32_16x16x32_bf16 v[40:43], v[96:99], v[108:111], v[40:43]
	v_mfma_f32_16x16x32_bf16 v[36:39], v[100:103], v[108:111], v[36:39]
	v_mfma_f32_16x16x32_bf16 v[32:35], v[112:115], v[108:111], v[32:35]
	v_mfma_f32_16x16x32_bf16 v[28:31], v[116:119], v[108:111], v[28:31]
	ds_read_b128 v[104:107], v120 offset:4096
	ds_read_b128 v[108:111], v120 offset:6144
	s_waitcnt vmcnt(0)
	s_waitcnt lgkmcnt(0)
	v_mfma_f32_16x16x32_bf16 v[24:27], v[96:99], v[104:107], v[24:27]
	s_barrier
; #define MFMA16(a, b, c) __builtin_amdgcn_mfma_f32_16x16x32_bf16((a), (b), (c), 0, 0, 0)
; DI void st_bf4(bf16_t* p, float a, float b, float c, float d) { uint2 v; v.x = pack2(a, b); v.y = pack2(c, d); *(uint2*)p = v; }
; template <class FA, class FB, class FL, class FS>
; DI void gemm_tile(char* lds, int ksteps, int rot, FA fa, FB fb, FL fl, FS fs) {
;     ...
; #pragma unroll
;     for (int kk = 0; kk < 2; ++kk) {
;       bf16x8 af[4], bq[4];
; #pragma unroll
;       for (int m = 0; m < 4; ++m) af[m] = ldfrag(A, 128, wr * 64 + m * 16 + fr, kk * 4 + fq);
; #pragma unroll
;       for (int n = 0; n < 4; ++n) bq[n] = ldfrag(B, 128, wc * 64 + n * 16 + fr, kk * 4 + fq);
; #pragma unroll
;       for (int m = 0; m < 4; ++m)
; #pragma unroll
;         for (int n = 0; n < 4; ++n) acc[m][n] = MFMA16(bq[n], af[m], acc[m][n]);
;     }
;     asm volatile("s_waitcnt vmcnt(0)" ::: "memory");
;     __syncthreads();
; DI void phase_g1(const Params& p, const Sub& s, char* lds_all) {
;     ...
;       [&](int row, int col, f32x4 v, const NoLoad&) {
;         if (col < 1024) {
;           if (row < MP) st_bf4(ugm + ((size_t)(col >> 4) * MP + row) * 16 + (col & 15), v[0], v[1], v[2], v[3]);
;           else *(f32x4*)(us + (size_t)(row - MP) * D + col) = v;
;         } else st_bf4(z + (size_t)row * D + (col - 1024), v[0], v[1], v[2], v[3]);
	v_mfma_f32_16x16x32_bf16 v[20:23], v[100:103], v[104:107], v[20:23]
	v_mfma_f32_16x16x32_bf16 v[16:19], v[112:115], v[104:107], v[16:19]
	v_mfma_f32_16x16x32_bf16 v[12:15], v[116:119], v[104:107], v[12:15]
	v_mfma_f32_16x16x32_bf16 v[8:11], v[96:99], v[108:111], v[8:11]
	v_mfma_f32_16x16x32_bf16 v[4:7], v[100:103], v[108:111], v[4:7]
	v_mfma_f32_16x16x32_bf16 v[48:51], v[112:115], v[108:111], v[48:51]
	v_mfma_f32_16x16x32_bf16 v[0:3], v[116:119], v[108:111], v[0:3]
	s_cbranch_scc1 .LBB0_1349
	v_add_u32_e32 v68, v85, v95
	v_add_u32_e32 v86, v68, v92
	ds_read_b128 v[64:67], v86 offset:49152
	ds_read_b128 v[72:75], v86 offset:51200
	ds_read_b128 v[76:79], v86 offset:53248
	ds_read_b128 v[94:97], v86 offset:55296
	v_add_u32_e32 v89, v68, v91
	ds_read_b128 v[68:71], v89 offset:32768
	v_add_u32_e32 v85, v85, v93
	v_add_u32_e32 v86, v85, v92
	v_add_u32_e32 v85, v85, v91
	s_waitcnt lgkmcnt(0)
	v_mfma_f32_16x16x32_bf16 v[60:63], v[64:67], v[68:71], v[60:63]
	s_add_u32 s16, s6, 0x9880000
	s_addc_u32 s17, s7, 0
	s_add_u32 s20, s6, 0x11900000
	v_mfma_f32_16x16x32_bf16 v[56:59], v[72:75], v[68:71], v[56:59]
	s_addc_u32 s21, s7, 0
	s_add_u32 s18, s6, 0x1514000
	s_movk_i32 s0, 0x3ff
	v_mfma_f32_16x16x32_bf16 v[52:55], v[76:79], v[68:71], v[52:55]
	s_addc_u32 s19, s7, 0
	ds_read_b128 v[90:93], v86 offset:55296
	ds_read_b128 v[98:101], v85 offset:38912
	v_mfma_f32_16x16x32_bf16 v[44:47], v[94:97], v[68:71], v[44:47]
	ds_read_b128 v[68:71], v89 offset:34816
	s_waitcnt lgkmcnt(0)
	v_mfma_f32_16x16x32_bf16 v[40:43], v[64:67], v[68:71], v[40:43]
	v_mfma_f32_16x16x32_bf16 v[36:39], v[72:75], v[68:71], v[36:39]
	v_mfma_f32_16x16x32_bf16 v[32:35], v[76:79], v[68:71], v[32:35]
	v_mfma_f32_16x16x32_bf16 v[28:31], v[94:97], v[68:71], v[28:31]
	ds_read_b128 v[68:71], v89 offset:36864
	s_waitcnt lgkmcnt(0)
	v_mfma_f32_16x16x32_bf16 v[24:27], v[64:67], v[68:71], v[24:27]
	v_mfma_f32_16x16x32_bf16 v[20:23], v[72:75], v[68:71], v[20:23]
	v_mfma_f32_16x16x32_bf16 v[16:19], v[76:79], v[68:71], v[16:19]
	v_mfma_f32_16x16x32_bf16 v[12:15], v[94:97], v[68:71], v[12:15]
	ds_read_b128 v[68:71], v89 offset:38912
	s_waitcnt lgkmcnt(0)
	v_mfma_f32_16x16x32_bf16 v[8:11], v[64:67], v[68:71], v[8:11]
	v_mfma_f32_16x16x32_bf16 v[4:7], v[72:75], v[68:71], v[4:7]
	ds_read_b128 v[72:75], v86 offset:49152
	v_mfma_f32_16x16x32_bf16 v[64:67], v[76:79], v[68:71], v[48:51]
	ds_read_b128 v[76:79], v86 offset:53248
	v_mfma_f32_16x16x32_bf16 v[0:3], v[94:97], v[68:71], v[0:3]
	ds_read_b128 v[68:71], v86 offset:51200
	ds_read_b128 v[48:51], v85 offset:32768
	ds_read_b128 v[94:97], v85 offset:34816
	s_waitcnt lgkmcnt(1)
	v_mfma_f32_16x16x32_bf16 v[60:63], v[72:75], v[48:51], v[60:63]
	v_mfma_f32_16x16x32_bf16 v[56:59], v[68:71], v[48:51], v[56:59]
	v_mfma_f32_16x16x32_bf16 v[52:55], v[76:79], v[48:51], v[52:55]
	v_mfma_f32_16x16x32_bf16 v[48:51], v[90:93], v[48:51], v[44:47]
	s_waitcnt lgkmcnt(0)
	v_mfma_f32_16x16x32_bf16 v[44:47], v[72:75], v[94:97], v[40:43]
	v_mfma_f32_16x16x32_bf16 v[40:43], v[68:71], v[94:97], v[36:39]
	v_mfma_f32_16x16x32_bf16 v[36:39], v[76:79], v[94:97], v[32:35]
	v_mfma_f32_16x16x32_bf16 v[32:35], v[90:93], v[94:97], v[28:31]
	ds_read_b128 v[94:97], v85 offset:36864
	s_waitcnt vmcnt(0)
	s_waitcnt lgkmcnt(0)
	v_mfma_f32_16x16x32_bf16 v[28:31], v[72:75], v[94:97], v[24:27]
	s_barrier
	v_mfma_f32_16x16x32_bf16 v[24:27], v[68:71], v[94:97], v[20:23]
	v_mfma_f32_16x16x32_bf16 v[20:23], v[76:79], v[94:97], v[16:19]
	v_mfma_f32_16x16x32_bf16 v[16:19], v[90:93], v[94:97], v[12:15]
	v_mfma_f32_16x16x32_bf16 v[12:15], v[72:75], v[98:101], v[8:11]
	v_mfma_f32_16x16x32_bf16 v[8:11], v[68:71], v[98:101], v[4:7]
	v_lshlrev_b32_e32 v70, 6, v84
	v_lshlrev_b32_e32 v68, 2, v87
	v_lshlrev_b32_e32 v69, 6, v88
	v_mfma_f32_16x16x32_bf16 v[4:7], v[76:79], v[98:101], v[64:67]
	v_mfma_f32_16x16x32_bf16 v[0:3], v[90:93], v[98:101], v[0:3]
	s_nop 1
	v_or3_b32 v64, v68, v70, v82
	v_or3_b32 v66, v69, v83, v81
	v_cmp_lt_i32_e32 vcc, s0, v64
	s_and_saveexec_b64 s[0:1], vcc
	s_xor_b64 s[0:1], exec, s[0:1]
	s_cbranch_execz .LBB0_1352
	v_ashrrev_i32_e32 v67, 31, v66
	v_lshlrev_b64 v[70:71], 11, v[66:67]
	v_lshl_add_u64 v[70:71], s[20:21], 0, v[70:71]
	v_mov_b32_e32 v65, 0
	v_lshl_add_u64 v[70:71], v[64:65], 1, v[70:71]
	v_cvt_pk_bf16_f32 v60, v60, v61
	v_cvt_pk_bf16_f32 v61, v62, v63
	global_store_dwordx2 v[70:71], v[60:61], off offset:-2048

; #define MFMA16(a, b, c) __builtin_amdgcn_mfma_f32_16x16x32_bf16((a), (b), (c), 0, 0, 0)
; #define LAS __attribute__((address_space(3)))
; template <class FA, class FB, class FL, class FS>
; DI void gemm_tile(char* lds, int ksteps, int rot, FA fa, FB fb, FL fl, FS fs) {
;     ...
;   for (int ks = 0; ks < ksteps; ++ks) {
;     const int cur = ks & 1;
;     if (ks + 1 < ksteps) {
;       int kn = ks + 1 + rot; if (kn >= ksteps) kn -= ksteps;
;       LAS char* dst = l3 + (cur ^ 1) * 32768;
; #pragma unroll
;       for (int i = 0; i < 4; ++i) {
;         const int id = tid + i * 256, r = id >> 3, c = (id & 7) ^ (r & 7);
;         __builtin_amdgcn_global_load_lds((const unsigned*)fa(r, kn * 8 + c), (LAS unsigned*)(dst + id * 16), 16, 0, 0);
;         __builtin_amdgcn_global_load_lds((const unsigned*)fb(r, kn * 8 + c), (LAS unsigned*)(dst + 16384 + id * 16), 16, 0, 0);
;       }
;     }
;     const char* A = lds + cur * 32768;
;     const char* B = A + 16384;
; #pragma unroll
;     for (int kk = 0; kk < 2; ++kk) {
;       bf16x8 af[4], bq[4];
; #pragma unroll
;       for (int m = 0; m < 4; ++m) af[m] = ldfrag(A, 128, wr * 64 + m * 16 + fr, kk * 4 + fq);
; #pragma unroll
;       for (int n = 0; n < 4; ++n) bq[n] = ldfrag(B, 128, wc * 64 + n * 16 + fr, kk * 4 + fq);
; #pragma unroll
;       for (int m = 0; m < 4; ++m)
; #pragma unroll
;         for (int n = 0; n < 4; ++n) acc[m][n] = MFMA16(bq[n], af[m], acc[m][n]);
;     }
;     asm volatile("s_waitcnt vmcnt(0)" ::: "memory");
;     __syncthreads();
.LBB0_1520:
	s_and_b32 s3, s2, 0x8000
	s_xor_b32 s4, s3, 0x8000
	v_add_u32_e32 v77, s3, v40
	v_add_u32_e32 v72, s4, v40
	v_add_u32_e32 v73, v77, v41
	v_add_u32_e32 v74, v72, v36
	v_add_u32_e32 v116, v73, v76
	v_add_u32_e32 v79, v73, v42
	v_readfirstlane_b32 s3, v74
	v_add_u32_e32 v73, 0x4000, v74
	v_lshl_add_u64 v[44:45], v[28:29], 0, s[0:1]
	v_add_u32_e32 v75, v72, v37
	v_readfirstlane_b32 s7, v73
	s_mov_b32 m0, s3
	v_lshl_add_u64 v[46:47], v[30:31], 0, s[0:1]
	v_readfirstlane_b32 s4, v75
	v_add_u32_e32 v74, 0x4000, v75
	global_load_lds_dwordx4 v[44:45], off
	s_mov_b32 m0, s7
	v_lshl_add_u64 v[52:53], v[24:25], 0, s[0:1]
	v_add_u32_e32 v78, v72, v38
	v_readfirstlane_b32 s16, v74
	global_load_lds_dwordx4 v[46:47], off
	s_mov_b32 m0, s4
	v_lshl_add_u64 v[54:55], v[26:27], 0, s[0:1]
	v_readfirstlane_b32 s5, v78
	v_add_u32_e32 v75, 0x4000, v78
	global_load_lds_dwordx4 v[52:53], off
	s_mov_b32 m0, s16
	v_lshl_add_u64 v[56:57], v[20:21], 0, s[0:1]
	v_add_u32_e32 v72, v72, v39
	v_readfirstlane_b32 s17, v75
	global_load_lds_dwordx4 v[54:55], off
	s_mov_b32 m0, s5
	v_lshl_add_u64 v[58:59], v[22:23], 0, s[0:1]
	v_readfirstlane_b32 s6, v72
	v_add_u32_e32 v72, 0x4000, v72
	global_load_lds_dwordx4 v[56:57], off
	s_mov_b32 m0, s17
	v_lshl_add_u64 v[60:61], v[16:17], 0, s[0:1]
	v_readfirstlane_b32 s18, v72
	global_load_lds_dwordx4 v[58:59], off
	s_mov_b32 m0, s6
	v_lshl_add_u64 v[62:63], v[18:19], 0, s[0:1]
	global_load_lds_dwordx4 v[60:61], off
	s_mov_b32 m0, s18
	s_add_i32 s2, s2, 0x8000
	global_load_lds_dwordx4 v[62:63], off
	ds_read_b128 v[44:47], v79 offset:16384
	ds_read_b128 v[52:55], v79 offset:18432
	ds_read_b128 v[56:59], v116
	ds_read_b128 v[60:63], v116 offset:2048
	ds_read_b128 v[96:99], v79 offset:20480
	s_waitcnt lgkmcnt(0)
	v_mfma_f32_16x16x32_bf16 v[100:103], v[52:55], v[56:59], v[112:115]
	s_add_u32 s0, s0, 0x80
	s_nop 1
	ds_read_b128 v[112:115], v79 offset:22528
	s_addc_u32 s1, s1, 0
	v_mfma_f32_16x16x32_bf16 v[72:75], v[44:47], v[56:59], v[124:127]
	s_cmpk_lg_i32 s0, 0x780
	v_mfma_f32_16x16x32_bf16 v[108:111], v[96:99], v[56:59], v[108:111]
	s_waitcnt lgkmcnt(0)
	v_mfma_f32_16x16x32_bf16 v[56:59], v[112:115], v[56:59], v[104:107]
	v_mfma_f32_16x16x32_bf16 v[92:95], v[44:47], v[60:63], v[92:95]
	v_mfma_f32_16x16x32_bf16 v[88:91], v[52:55], v[60:63], v[88:91]
	v_mfma_f32_16x16x32_bf16 v[84:87], v[96:99], v[60:63], v[84:87]
	v_mfma_f32_16x16x32_bf16 v[60:63], v[112:115], v[60:63], v[80:83]
	s_nop 2
	ds_read_b128 v[78:81], v116 offset:4096
	ds_read_b128 v[104:107], v116 offset:6144
	s_waitcnt lgkmcnt(1)
	v_mfma_f32_16x16x32_bf16 v[68:71], v[44:47], v[78:81], v[68:71]
	s_waitcnt lgkmcnt(0)
	v_mfma_f32_16x16x32_bf16 v[12:15], v[44:47], v[104:107], v[12:15]
	v_add_u32_e32 v44, v77, v43
	v_add_u32_e32 v82, v44, v42
	v_add_u32_e32 v77, v44, v76
	v_mfma_f32_16x16x32_bf16 v[64:67], v[52:55], v[78:81], v[64:67]
	v_mfma_f32_16x16x32_bf16 v[8:11], v[52:55], v[104:107], v[8:11]
	ds_read_b128 v[44:47], v82 offset:16384
	ds_read_b128 v[52:55], v82 offset:18432
	v_mfma_f32_16x16x32_bf16 v[48:51], v[96:99], v[78:81], v[48:51]
	v_mfma_f32_16x16x32_bf16 v[32:35], v[112:115], v[78:81], v[32:35]
	v_mfma_f32_16x16x32_bf16 v[4:7], v[96:99], v[104:107], v[4:7]
	ds_read_b128 v[78:81], v77
	ds_read_b128 v[96:99], v77 offset:2048
	v_mfma_f32_16x16x32_bf16 v[0:3], v[112:115], v[104:107], v[0:3]
	s_waitcnt lgkmcnt(1)
	v_mfma_f32_16x16x32_bf16 v[124:127], v[44:47], v[78:81], v[72:75]
	s_nop 2
	ds_read_b128 v[72:75], v82 offset:20480
	v_mfma_f32_16x16x32_bf16 v[112:115], v[52:55], v[78:81], v[100:103]
	s_nop 2
	ds_read_b128 v[100:103], v82 offset:22528
	s_waitcnt lgkmcnt(1)
	v_mfma_f32_16x16x32_bf16 v[108:111], v[72:75], v[78:81], v[108:111]
	s_waitcnt lgkmcnt(0)
	v_mfma_f32_16x16x32_bf16 v[104:107], v[100:103], v[78:81], v[56:59]
	v_mfma_f32_16x16x32_bf16 v[80:83], v[100:103], v[96:99], v[60:63]
	s_nop 1
	ds_read_b128 v[56:59], v77 offset:4096
	ds_read_b128 v[60:63], v77 offset:6144
	s_waitcnt vmcnt(0)
	s_waitcnt lgkmcnt(0)
	v_mfma_f32_16x16x32_bf16 v[92:95], v[44:47], v[96:99], v[92:95]
	s_barrier
	v_mfma_f32_16x16x32_bf16 v[88:91], v[52:55], v[96:99], v[88:91]
	v_mfma_f32_16x16x32_bf16 v[84:87], v[72:75], v[96:99], v[84:87]
	v_mfma_f32_16x16x32_bf16 v[68:71], v[44:47], v[56:59], v[68:71]
	v_mfma_f32_16x16x32_bf16 v[64:67], v[52:55], v[56:59], v[64:67]
	v_mfma_f32_16x16x32_bf16 v[48:51], v[72:75], v[56:59], v[48:51]
	v_mfma_f32_16x16x32_bf16 v[32:35], v[100:103], v[56:59], v[32:35]
	v_mfma_f32_16x16x32_bf16 v[12:15], v[44:47], v[60:63], v[12:15]
	v_mfma_f32_16x16x32_bf16 v[8:11], v[52:55], v[60:63], v[8:11]
	v_mfma_f32_16x16x32_bf16 v[4:7], v[72:75], v[60:63], v[4:7]
	v_mfma_f32_16x16x32_bf16 v[0:3], v[100:103], v[60:63], v[0:3]
	s_cbranch_scc1 .LBB0_1520
	v_lshlrev_b32_e32 v134, 6, v134
	v_lshlrev_b32_e32 v129, 6, v129
	v_lshlrev_b32_e32 v130, 2, v130
	v_or3_b32 v134, v134, v133, v132
	v_or3_b32 v130, v130, v129, v128
	v_ashrrev_i32_e32 v135, 31, v134
	v_ashrrev_i32_e32 v131, 31, v130
	v_lshlrev_b64 v[138:139], 10, v[134:135]
	v_add_u32_e32 v20, v40, v43
	v_add_u32_e32 v28, v40, v41
	v_lshl_add_u64 v[128:129], v[130:131], 2, s[12:13]
	v_lshl_add_u64 v[132:133], v[138:139], 0, v[130:131]
	s_add_u32 s12, s14, 0x11900000
	v_add_u32_e32 v21, v20, v42
	v_add_u32_e32 v24, v20, v76
	v_add_u32_e32 v29, v28, v42
	v_add_u32_e32 v120, v28, v76
	v_lshlrev_b64 v[132:133], 1, v[132:133]
	s_addc_u32 s13, s15, 0
	ds_read_b128 v[16:19], v21 offset:55296
	ds_read_b128 v[36:39], v21 offset:53248
	ds_read_b128 v[44:47], v21 offset:51200
	ds_read_b128 v[56:59], v21 offset:49152
	ds_read_b128 v[20:23], v24 offset:38912
	ds_read_b128 v[72:75], v24 offset:36864
	ds_read_b128 v[96:99], v24 offset:34816
	ds_read_b128 v[116:119], v24 offset:32768
	ds_read_b128 v[24:27], v29 offset:55296
	ds_read_b128 v[40:43], v29 offset:53248
	ds_read_b128 v[52:55], v29 offset:51200
	ds_read_b128 v[60:63], v29 offset:49152
	ds_read_b128 v[28:31], v120 offset:38912
	ds_read_b128 v[76:79], v120 offset:36864
	ds_read_b128 v[100:103], v120 offset:34816
	ds_read_b128 v[120:123], v120 offset:32768
	s_waitcnt vmcnt(0)
	s_waitcnt lgkmcnt(0)
	s_barrier
; DI void st_bf4(bf16_t* p, float a, float b, float c, float d) { uint2 v; v.x = pack2(a, b); v.y = pack2(c, d); *(uint2*)p = v; }
; DI float sigmoidf_(float x) { return __builtin_amdgcn_rcpf(1.0f + __expf(-x)); }
; DI float siluf_(float x) { return x * sigmoidf_(x); }
; DI void phase_g2(const Params& p, const Sub& s, char* lds_all) {
;     ...
;       [&](int row, int col) { const size_t o = (size_t)row * D + col; Ld2 r; const uint2 a = *(const uint2*)(A + o), b = *(const uint2*)(z + o);
;         r.a.x = __uint_as_float(a.x); r.a.y = __uint_as_float(a.y); r.a.z = __uint_as_float(b.x); r.a.w = __uint_as_float(b.y); r.b = *(const float4*)(p.s5_b_glu + col); return r; },
;       [&](int row, int col, f32x4 v, const Ld2& l2) {
;         uint4 ld; ld.x = __float_as_uint(l2.a.x); ld.y = __float_as_uint(l2.a.y); ld.z = __float_as_uint(l2.a.z); ld.w = __float_as_uint(l2.a.w);
;         const size_t o = (size_t)row * D + col;
;         const float y0 = __uint_as_float(ld.x << 16), y1 = __uint_as_float(ld.x & 0xffff0000u), y2_ = __uint_as_float(ld.y << 16), y3 = __uint_as_float(ld.y & 0xffff0000u);
;         const float z0 = __uint_as_float(ld.z << 16), z1 = __uint_as_float(ld.z & 0xffff0000u), z2 = __uint_as_float(ld.w << 16), z3 = __uint_as_float(ld.w & 0xffff0000u);
;         const float4 b4 = l2.b;
;         st_bf4(y2 + o, y0 * sigmoidf_(v[0] + b4.x) * siluf_(z0), y1 * sigmoidf_(v[1] + b4.y) * siluf_(z1),
;                y2_ * sigmoidf_(v[2] + b4.z) * siluf_(z2), y3 * sigmoidf_(v[3] + b4.w) * siluf_(z3));
	global_load_dwordx4 v[156:159], v[128:129], off
	v_lshl_add_u64 v[136:137], s[10:11], 0, v[132:133]
	v_lshl_add_u64 v[132:133], s[12:13], 0, v[132:133]
	global_load_dwordx2 v[164:165], v[136:137], off
	v_mfma_f32_16x16x32_bf16 v[160:163], v[60:63], v[120:123], v[124:127]
	global_load_dwordx2 v[132:133], v[132:133], off
	s_add_u32 s14, s14, 0x1800000
	s_addc_u32 s15, s15, 0
	v_mfma_f32_16x16x32_bf16 v[160:163], v[56:59], v[116:119], v[160:163]
	v_lshlrev_b64 v[136:137], 11, v[134:135]
	v_lshlrev_b64 v[124:125], 1, v[130:131]
	v_lshl_add_u64 v[126:127], s[14:15], 0, v[136:137]
	v_lshl_add_u64 v[136:137], v[126:127], 0, v[124:125]
	v_mfma_f32_16x16x32_bf16 v[112:115], v[52:55], v[120:123], v[112:115]
	s_waitcnt vmcnt(2)
	s_nop 1
	v_add_f32_e32 v126, v160, v156
	v_add_f32_e32 v127, v161, v157
	v_add_f32_e32 v135, v162, v158
	v_add_f32_e32 v156, v163, v159
	v_mul_f32_e32 v126, 0xbfb8aa3b, v126
	v_mul_f32_e32 v127, 0xbfb8aa3b, v127
	v_mul_f32_e32 v135, 0xbfb8aa3b, v135
	v_mul_f32_e32 v156, 0xbfb8aa3b, v156
	s_waitcnt vmcnt(0)
	v_lshlrev_b32_e32 v158, 16, v132
	v_and_b32_e32 v159, 0xffff0000, v132
	v_lshlrev_b32_e32 v132, 16, v133
	v_and_b32_e32 v133, 0xffff0000, v133
	v_exp_f32_e32 v160, v126
	v_exp_f32_e32 v161, v127
	v_exp_f32_e32 v135, v135
	v_exp_f32_e32 v162, v156
	v_lshlrev_b32_e32 v126, 16, v164
	v_and_b32_e32 v127, 0xffff0000, v164
	v_lshlrev_b32_e32 v156, 16, v165
	v_and_b32_e32 v157, 0xffff0000, v165
	v_mul_f32_e32 v163, 0xbfb8aa3b, v158
	v_mul_f32_e32 v164, 0xbfb8aa3b, v159
	v_mul_f32_e32 v165, 0xbfb8aa3b, v132
	v_mul_f32_e32 v166, 0xbfb8aa3b, v133
	v_exp_f32_e32 v167, v163
	v_exp_f32_e32 v164, v164
	v_exp_f32_e32 v165, v165
	v_exp_f32_e32 v166, v166
	v_add_f32_e32 v135, 1.0, v135
	v_add_f32_e32 v160, 1.0, v160
	v_add_f32_e32 v161, 1.0, v161
	v_add_f32_e32 v163, 1.0, v162
	v_rcp_f32_e32 v162, v135
	v_add_f32_e32 v135, 1.0, v167
	v_add_f32_e32 v167, 1.0, v164
	v_add_f32_e32 v168, 1.0, v165
	v_add_f32_e32 v169, 1.0, v166
	v_rcp_f32_e32 v160, v160
	v_rcp_f32_e32 v161, v161
	v_rcp_f32_e32 v163, v163
	v_rcp_f32_e32 v164, v135
	v_rcp_f32_e32 v165, v167
	v_rcp_f32_e32 v166, v168
	v_rcp_f32_e32 v167, v169
	v_pk_mul_f32 v[126:127], v[160:161], v[126:127]
	v_pk_mul_f32 v[156:157], v[162:163], v[156:157]
	v_pk_mul_f32 v[158:159], v[164:165], v[158:159]
	v_pk_mul_f32 v[132:133], v[166:167], v[132:133]
	v_pk_mul_f32 v[126:127], v[158:159], v[126:127]
	v_pk_mul_f32 v[132:133], v[132:133], v[156:157]
	v_cvt_pk_bf16_f32 v126, v126, v127
	v_cvt_pk_bf16_f32 v127, v132, v133
	v_or_b32_e32 v132, 16, v130
	v_ashrrev_i32_e32 v133, 31, v132
	global_store_dwordx2 v[136:137], v[126:127], off
	v_lshl_add_u64 v[126:127], v[138:139], 0, v[132:133]
	v_lshlrev_b64 v[126:127], 1, v[126:127]
	v_lshl_add_u64 v[156:157], s[10:11], 0, v[126:127]
	v_lshl_add_u64 v[126:127], s[12:13], 0, v[126:127]
	global_load_dwordx2 v[160:161], v[156:157], off
	global_load_dwordx2 v[162:163], v[126:127], off
	s_nop 0
	global_load_dwordx4 v[156:159], v[128:129], off offset:64
	v_mfma_f32_16x16x32_bf16 v[112:115], v[44:47], v[116:119], v[112:115]
	v_or_b32_e32 v126, 32, v130
	v_ashrrev_i32_e32 v127, 31, v126
	v_lshl_add_u64 v[164:165], v[138:139], 0, v[126:127]
	v_lshlrev_b64 v[164:165], 1, v[164:165]
	v_lshl_add_u64 v[166:167], s[10:11], 0, v[164:165]
	v_mfma_f32_16x16x32_bf16 v[108:111], v[40:43], v[120:123], v[108:111]
	s_waitcnt vmcnt(1)
	v_lshlrev_b32_e32 v170, 16, v162
	v_and_b32_e32 v171, 0xffff0000, v162
	v_lshlrev_b32_e32 v162, 16, v163
	v_and_b32_e32 v163, 0xffff0000, v163
	s_waitcnt vmcnt(0)
	v_add_f32_e32 v112, v112, v156
	v_add_f32_e32 v113, v113, v157
	v_add_f32_e32 v114, v114, v158
	v_add_f32_e32 v115, v115, v159
	v_mul_f32_e32 v112, 0xbfb8aa3b, v112
	v_mul_f32_e32 v113, 0xbfb8aa3b, v113
	v_mul_f32_e32 v135, 0xbfb8aa3b, v170
	v_mul_f32_e32 v156, 0xbfb8aa3b, v171
	v_mul_f32_e32 v114, 0xbfb8aa3b, v114
	v_mul_f32_e32 v115, 0xbfb8aa3b, v115
	v_mul_f32_e32 v157, 0xbfb8aa3b, v162
	v_mul_f32_e32 v158, 0xbfb8aa3b, v163
	v_exp_f32_e32 v112, v112
	v_exp_f32_e32 v113, v113
	v_exp_f32_e32 v135, v135
	v_exp_f32_e32 v156, v156
	v_exp_f32_e32 v114, v114
	v_exp_f32_e32 v115, v115
	v_exp_f32_e32 v157, v157
	v_exp_f32_e32 v158, v158
	v_add_f32_e32 v112, 1.0, v112
	v_add_f32_e32 v113, 1.0, v113
	v_add_f32_e32 v135, 1.0, v135
	v_add_f32_e32 v156, 1.0, v156
	v_add_f32_e32 v159, 1.0, v114
	v_add_f32_e32 v172, 1.0, v115
	v_add_f32_e32 v173, 1.0, v157
	v_add_f32_e32 v174, 1.0, v158
	v_rcp_f32_e32 v112, v112
	v_rcp_f32_e32 v113, v113
	v_rcp_f32_e32 v114, v135
	v_rcp_f32_e32 v115, v156
	v_rcp_f32_e32 v156, v159
	v_rcp_f32_e32 v157, v172
	v_rcp_f32_e32 v158, v173
	v_rcp_f32_e32 v159, v174
	v_lshlrev_b32_e32 v168, 16, v160
	v_and_b32_e32 v169, 0xffff0000, v160
	v_lshlrev_b32_e32 v160, 16, v161
	v_and_b32_e32 v161, 0xffff0000, v161
	v_pk_mul_f32 v[112:113], v[112:113], v[168:169]
	v_pk_mul_f32 v[114:115], v[114:115], v[170:171]
	v_pk_mul_f32 v[156:157], v[156:157], v[160:161]
	v_pk_mul_f32 v[158:159], v[158:159], v[162:163]
	v_pk_mul_f32 v[112:113], v[114:115], v[112:113]
	v_pk_mul_f32 v[114:115], v[158:159], v[156:157]
	v_cvt_pk_bf16_f32 v112, v112, v113
	v_cvt_pk_bf16_f32 v113, v114, v115
	global_store_dwordx2 v[136:137], v[112:113], off offset:32
	v_lshl_add_u64 v[112:113], s[12:13], 0, v[164:165]
	global_load_dwordx2 v[114:115], v[166:167], off
	global_load_dwordx2 v[160:161], v[112:113], off
	global_load_dwordx4 v[156:159], v[128:129], off offset:128
	v_mfma_f32_16x16x32_bf16 v[108:111], v[36:39], v[116:119], v[108:111]
	v_or_b32_e32 v112, 48, v130
	v_ashrrev_i32_e32 v113, 31, v112
	v_lshl_add_u64 v[138:139], v[138:139], 0, v[112:113]
	v_lshlrev_b64 v[138:139], 1, v[138:139]
	v_lshl_add_u64 v[162:163], s[10:11], 0, v[138:139]
	v_mfma_f32_16x16x32_bf16 v[104:107], v[24:27], v[120:123], v[104:107]
	s_waitcnt vmcnt(1)
; DI void st_bf4(bf16_t* p, float a, float b, float c, float d) { uint2 v; v.x = pack2(a, b); v.y = pack2(c, d); *(uint2*)p = v; }
; DI float sigmoidf_(float x) { return __builtin_amdgcn_rcpf(1.0f + __expf(-x)); }
; DI float siluf_(float x) { return x * sigmoidf_(x); }
; DI void phase_g2(const Params& p, const Sub& s, char* lds_all) {
;     ...
;       [&](int row, int col) { const size_t o = (size_t)row * D + col; Ld2 r; const uint2 a = *(const uint2*)(A + o), b = *(const uint2*)(z + o);
;         r.a.x = __uint_as_float(a.x); r.a.y = __uint_as_float(a.y); r.a.z = __uint_as_float(b.x); r.a.w = __uint_as_float(b.y); r.b = *(const float4*)(p.s5_b_glu + col); return r; },
;       [&](int row, int col, f32x4 v, const Ld2& l2) {
;         uint4 ld; ld.x = __float_as_uint(l2.a.x); ld.y = __float_as_uint(l2.a.y); ld.z = __float_as_uint(l2.a.z); ld.w = __float_as_uint(l2.a.w);
;         const size_t o = (size_t)row * D + col;
;         const float y0 = __uint_as_float(ld.x << 16), y1 = __uint_as_float(ld.x & 0xffff0000u), y2_ = __uint_as_float(ld.y << 16), y3 = __uint_as_float(ld.y & 0xffff0000u);
;         const float z0 = __uint_as_float(ld.z << 16), z1 = __uint_as_float(ld.z & 0xffff0000u), z2 = __uint_as_float(ld.w << 16), z3 = __uint_as_float(ld.w & 0xffff0000u);
;         const float4 b4 = l2.b;
;         st_bf4(y2 + o, y0 * sigmoidf_(v[0] + b4.x) * siluf_(z0), y1 * sigmoidf_(v[1] + b4.y) * siluf_(z1),
;                y2_ * sigmoidf_(v[2] + b4.z) * siluf_(z2), y3 * sigmoidf_(v[3] + b4.w) * siluf_(z3));
	v_lshlrev_b32_e32 v166, 16, v160
	v_and_b32_e32 v167, 0xffff0000, v160
	v_lshlrev_b32_e32 v160, 16, v161
	v_and_b32_e32 v161, 0xffff0000, v161
	s_waitcnt vmcnt(0)
	v_add_f32_e32 v108, v108, v156
	v_add_f32_e32 v109, v109, v157
	v_add_f32_e32 v110, v110, v158
	v_add_f32_e32 v111, v111, v159
	v_mul_f32_e32 v108, 0xbfb8aa3b, v108
	v_mul_f32_e32 v109, 0xbfb8aa3b, v109
	v_mul_f32_e32 v135, 0xbfb8aa3b, v166
	v_mul_f32_e32 v156, 0xbfb8aa3b, v167
	v_mul_f32_e32 v110, 0xbfb8aa3b, v110
	v_mul_f32_e32 v111, 0xbfb8aa3b, v111
	v_mul_f32_e32 v157, 0xbfb8aa3b, v160
	v_mul_f32_e32 v158, 0xbfb8aa3b, v161
	v_exp_f32_e32 v108, v108
	v_exp_f32_e32 v109, v109
	v_exp_f32_e32 v135, v135
	v_exp_f32_e32 v156, v156
	v_exp_f32_e32 v110, v110
	v_exp_f32_e32 v111, v111
	v_exp_f32_e32 v157, v157
	v_exp_f32_e32 v158, v158
	v_add_f32_e32 v108, 1.0, v108
	v_add_f32_e32 v109, 1.0, v109
	v_add_f32_e32 v135, 1.0, v135
	v_add_f32_e32 v156, 1.0, v156
	v_add_f32_e32 v159, 1.0, v110
	v_add_f32_e32 v168, 1.0, v111
	v_add_f32_e32 v169, 1.0, v157
	v_add_f32_e32 v170, 1.0, v158
	v_rcp_f32_e32 v108, v108
	v_rcp_f32_e32 v109, v109
	v_rcp_f32_e32 v110, v135
	v_rcp_f32_e32 v111, v156
	v_rcp_f32_e32 v156, v159
	v_rcp_f32_e32 v157, v168
	v_rcp_f32_e32 v158, v169
	v_rcp_f32_e32 v159, v170
	v_lshlrev_b32_e32 v164, 16, v114
	v_and_b32_e32 v165, 0xffff0000, v114
	v_lshlrev_b32_e32 v114, 16, v115
	v_and_b32_e32 v115, 0xffff0000, v115
	v_pk_mul_f32 v[108:109], v[108:109], v[164:165]
	v_pk_mul_f32 v[110:111], v[110:111], v[166:167]
	v_pk_mul_f32 v[114:115], v[156:157], v[114:115]
	v_pk_mul_f32 v[156:157], v[158:159], v[160:161]
	v_pk_mul_f32 v[108:109], v[110:111], v[108:109]
	v_pk_mul_f32 v[110:111], v[156:157], v[114:115]
	v_cvt_pk_bf16_f32 v108, v108, v109
	v_cvt_pk_bf16_f32 v109, v110, v111
	global_store_dwordx2 v[136:137], v[108:109], off offset:64
	v_lshl_add_u64 v[108:109], s[12:13], 0, v[138:139]
	global_load_dwordx2 v[110:111], v[162:163], off
	global_load_dwordx2 v[114:115], v[108:109], off
	global_load_dwordx4 v[156:159], v[128:129], off offset:192
	v_mfma_f32_16x16x32_bf16 v[104:107], v[16:19], v[116:119], v[104:107]
	v_or_b32_e32 v138, 16, v134
	v_ashrrev_i32_e32 v139, 31, v138
	v_lshlrev_b64 v[108:109], 10, v[138:139]
	v_lshl_add_u64 v[120:121], v[108:109], 0, v[130:131]
	v_lshlrev_b64 v[120:121], 1, v[120:121]
	v_lshl_add_u64 v[122:123], s[10:11], 0, v[120:121]
	v_mfma_f32_16x16x32_bf16 v[88:91], v[52:55], v[100:103], v[88:91]
	s_waitcnt vmcnt(1)
	v_lshlrev_b32_e32 v118, 16, v114
	v_and_b32_e32 v119, 0xffff0000, v114
	v_lshlrev_b32_e32 v114, 16, v115
	v_and_b32_e32 v115, 0xffff0000, v115
	s_waitcnt vmcnt(0)
	v_add_f32_e32 v104, v104, v156
	v_add_f32_e32 v105, v105, v157
	v_add_f32_e32 v106, v106, v158
	v_add_f32_e32 v107, v107, v159
	v_mul_f32_e32 v104, 0xbfb8aa3b, v104
	v_mul_f32_e32 v105, 0xbfb8aa3b, v105
	v_mul_f32_e32 v135, 0xbfb8aa3b, v118
	v_mul_f32_e32 v156, 0xbfb8aa3b, v119
	v_mul_f32_e32 v106, 0xbfb8aa3b, v106
	v_mul_f32_e32 v107, 0xbfb8aa3b, v107
	v_mul_f32_e32 v157, 0xbfb8aa3b, v114
	v_mul_f32_e32 v158, 0xbfb8aa3b, v115
	v_exp_f32_e32 v104, v104
	v_exp_f32_e32 v105, v105
	v_exp_f32_e32 v135, v135
	v_exp_f32_e32 v156, v156
	v_exp_f32_e32 v106, v106
	v_exp_f32_e32 v107, v107
	v_exp_f32_e32 v157, v157
	v_exp_f32_e32 v158, v158
	v_add_f32_e32 v104, 1.0, v104
	v_add_f32_e32 v105, 1.0, v105
	v_add_f32_e32 v135, 1.0, v135
	v_add_f32_e32 v156, 1.0, v156
	v_add_f32_e32 v159, 1.0, v106
	v_add_f32_e32 v160, 1.0, v107
	v_add_f32_e32 v161, 1.0, v157
	v_add_f32_e32 v162, 1.0, v158
	v_rcp_f32_e32 v104, v104
	v_rcp_f32_e32 v105, v105
	v_rcp_f32_e32 v106, v135
	v_rcp_f32_e32 v107, v156
	v_rcp_f32_e32 v156, v159
	v_rcp_f32_e32 v157, v160
	v_rcp_f32_e32 v158, v161
	v_rcp_f32_e32 v159, v162
	v_lshlrev_b32_e32 v116, 16, v110
	v_and_b32_e32 v117, 0xffff0000, v110
	v_lshlrev_b32_e32 v110, 16, v111
	v_and_b32_e32 v111, 0xffff0000, v111
	v_pk_mul_f32 v[104:105], v[104:105], v[116:117]
	v_pk_mul_f32 v[106:107], v[106:107], v[118:119]
	v_pk_mul_f32 v[110:111], v[156:157], v[110:111]
	v_pk_mul_f32 v[114:115], v[158:159], v[114:115]
	v_pk_mul_f32 v[104:105], v[106:107], v[104:105]
	v_pk_mul_f32 v[106:107], v[114:115], v[110:111]
	v_cvt_pk_bf16_f32 v104, v104, v105
	v_cvt_pk_bf16_f32 v105, v106, v107
	global_store_dwordx2 v[136:137], v[104:105], off offset:96
	v_lshl_add_u64 v[104:105], s[12:13], 0, v[120:121]
	global_load_dwordx2 v[110:111], v[122:123], off
	global_load_dwordx2 v[118:119], v[104:105], off
	s_nop 0
	global_load_dwordx4 v[104:107], v[128:129], off
	v_lshlrev_b64 v[114:115], 11, v[138:139]
	v_lshl_add_u64 v[120:121], s[14:15], 0, v[114:115]
	v_mfma_f32_16x16x32_bf16 v[114:117], v[60:63], v[100:103], v[92:95]
	v_lshl_add_u64 v[122:123], v[108:109], 0, v[132:133]
	s_waitcnt vmcnt(1)
	v_lshlrev_b32_e32 v136, 16, v118
	v_mfma_f32_16x16x32_bf16 v[114:117], v[56:59], v[96:99], v[114:117]
	v_and_b32_e32 v137, 0xffff0000, v118
	v_lshlrev_b32_e32 v118, 16, v119
	v_and_b32_e32 v119, 0xffff0000, v119
	v_lshlrev_b64 v[94:95], 1, v[122:123]
	v_lshlrev_b32_e32 v122, 16, v110
	s_waitcnt vmcnt(0)
; DI void st_bf4(bf16_t* p, float a, float b, float c, float d) { uint2 v; v.x = pack2(a, b); v.y = pack2(c, d); *(uint2*)p = v; }
; DI float sigmoidf_(float x) { return __builtin_amdgcn_rcpf(1.0f + __expf(-x)); }
; DI float siluf_(float x) { return x * sigmoidf_(x); }
; DI void phase_g2(const Params& p, const Sub& s, char* lds_all) {
;     ...
;       [&](int row, int col) { const size_t o = (size_t)row * D + col; Ld2 r; const uint2 a = *(const uint2*)(A + o), b = *(const uint2*)(z + o);
;         r.a.x = __uint_as_float(a.x); r.a.y = __uint_as_float(a.y); r.a.z = __uint_as_float(b.x); r.a.w = __uint_as_float(b.y); r.b = *(const float4*)(p.s5_b_glu + col); return r; },
;       [&](int row, int col, f32x4 v, const Ld2& l2) {
;         uint4 ld; ld.x = __float_as_uint(l2.a.x); ld.y = __float_as_uint(l2.a.y); ld.z = __float_as_uint(l2.a.z); ld.w = __float_as_uint(l2.a.w);
;         const size_t o = (size_t)row * D + col;
;         const float y0 = __uint_as_float(ld.x << 16), y1 = __uint_as_float(ld.x & 0xffff0000u), y2_ = __uint_as_float(ld.y << 16), y3 = __uint_as_float(ld.y & 0xffff0000u);
;         const float z0 = __uint_as_float(ld.z << 16), z1 = __uint_as_float(ld.z & 0xffff0000u), z2 = __uint_as_float(ld.w << 16), z3 = __uint_as_float(ld.w & 0xffff0000u);
;         const float4 b4 = l2.b;
;         st_bf4(y2 + o, y0 * sigmoidf_(v[0] + b4.x) * siluf_(z0), y1 * sigmoidf_(v[1] + b4.y) * siluf_(z1),
;                y2_ * sigmoidf_(v[2] + b4.z) * siluf_(z2), y3 * sigmoidf_(v[3] + b4.w) * siluf_(z3));
	s_nop 1
	v_add_f32_e32 v104, v114, v104
	v_add_f32_e32 v105, v115, v105
	v_add_f32_e32 v106, v116, v106
	v_add_f32_e32 v107, v117, v107
	v_mul_f32_e32 v104, 0xbfb8aa3b, v104
	v_mul_f32_e32 v105, 0xbfb8aa3b, v105
	v_mul_f32_e32 v114, 0xbfb8aa3b, v136
	v_mul_f32_e32 v115, 0xbfb8aa3b, v137
	v_mul_f32_e32 v106, 0xbfb8aa3b, v106
	v_mul_f32_e32 v107, 0xbfb8aa3b, v107
	v_mul_f32_e32 v116, 0xbfb8aa3b, v118
	v_mul_f32_e32 v117, 0xbfb8aa3b, v119
	v_exp_f32_e32 v104, v104
	v_exp_f32_e32 v105, v105
	v_exp_f32_e32 v114, v114
	v_exp_f32_e32 v115, v115
	v_exp_f32_e32 v106, v106
	v_exp_f32_e32 v107, v107
	v_exp_f32_e32 v116, v116
	v_exp_f32_e32 v117, v117
	v_add_f32_e32 v104, 1.0, v104
	v_add_f32_e32 v105, 1.0, v105
	v_add_f32_e32 v114, 1.0, v114
	v_add_f32_e32 v115, 1.0, v115
	v_add_f32_e32 v135, 1.0, v106
	v_add_f32_e32 v138, 1.0, v107
	v_add_f32_e32 v116, 1.0, v116
	v_add_f32_e32 v117, 1.0, v117
	v_rcp_f32_e32 v104, v104
	v_rcp_f32_e32 v105, v105
	v_rcp_f32_e32 v106, v114
	v_rcp_f32_e32 v107, v115
	v_rcp_f32_e32 v114, v135
	v_rcp_f32_e32 v115, v138
	v_rcp_f32_e32 v116, v116
	v_rcp_f32_e32 v117, v117
	v_and_b32_e32 v123, 0xffff0000, v110
	v_lshlrev_b32_e32 v110, 16, v111
	v_and_b32_e32 v111, 0xffff0000, v111
	v_pk_mul_f32 v[104:105], v[104:105], v[122:123]
	v_pk_mul_f32 v[106:107], v[106:107], v[136:137]
	v_pk_mul_f32 v[110:111], v[114:115], v[110:111]
	v_pk_mul_f32 v[114:115], v[116:117], v[118:119]
	v_pk_mul_f32 v[104:105], v[106:107], v[104:105]
	v_pk_mul_f32 v[106:107], v[114:115], v[110:111]
	v_lshl_add_u64 v[92:93], v[120:121], 0, v[124:125]
	v_cvt_pk_bf16_f32 v104, v104, v105
	v_cvt_pk_bf16_f32 v105, v106, v107
	v_lshl_add_u64 v[120:121], s[10:11], 0, v[94:95]
	global_store_dwordx2 v[92:93], v[104:105], off
	v_lshl_add_u64 v[94:95], s[12:13], 0, v[94:95]
	global_load_dwordx2 v[110:111], v[120:121], off
	s_nop 0
	global_load_dwordx2 v[94:95], v[94:95], off
	s_nop 0
	global_load_dwordx4 v[104:107], v[128:129], off offset:64
	v_mfma_f32_16x16x32_bf16 v[88:91], v[44:47], v[96:99], v[88:91]
	v_lshl_add_u64 v[114:115], v[108:109], 0, v[126:127]
	v_lshlrev_b64 v[114:115], 1, v[114:115]
	v_lshl_add_u64 v[116:117], s[10:11], 0, v[114:115]
	v_mfma_f32_16x16x32_bf16 v[84:87], v[40:43], v[100:103], v[84:87]
	s_waitcnt vmcnt(1)
	v_lshlrev_b32_e32 v120, 16, v94
	v_and_b32_e32 v121, 0xffff0000, v94
	v_lshlrev_b32_e32 v94, 16, v95
	v_and_b32_e32 v95, 0xffff0000, v95
	s_waitcnt vmcnt(0)
	v_add_f32_e32 v88, v88, v104
	v_add_f32_e32 v89, v89, v105
	v_add_f32_e32 v90, v90, v106
	v_add_f32_e32 v91, v91, v107
	v_mul_f32_e32 v88, 0xbfb8aa3b, v88
	v_mul_f32_e32 v89, 0xbfb8aa3b, v89
	v_mul_f32_e32 v104, 0xbfb8aa3b, v120
	v_mul_f32_e32 v105, 0xbfb8aa3b, v121
	v_mul_f32_e32 v90, 0xbfb8aa3b, v90
	v_mul_f32_e32 v91, 0xbfb8aa3b, v91
	v_mul_f32_e32 v106, 0xbfb8aa3b, v94
	v_mul_f32_e32 v107, 0xbfb8aa3b, v95
	v_exp_f32_e32 v88, v88
	v_exp_f32_e32 v89, v89
	v_exp_f32_e32 v104, v104
	v_exp_f32_e32 v105, v105
	v_exp_f32_e32 v90, v90
	v_exp_f32_e32 v91, v91
	v_exp_f32_e32 v106, v106
	v_exp_f32_e32 v107, v107
	v_add_f32_e32 v88, 1.0, v88
	v_add_f32_e32 v89, 1.0, v89
	v_add_f32_e32 v104, 1.0, v104
	v_add_f32_e32 v105, 1.0, v105
	v_add_f32_e32 v122, 1.0, v90
	v_add_f32_e32 v123, 1.0, v91
	v_add_f32_e32 v106, 1.0, v106
	v_add_f32_e32 v107, 1.0, v107
	v_rcp_f32_e32 v88, v88
	v_rcp_f32_e32 v89, v89
	v_rcp_f32_e32 v90, v104
	v_rcp_f32_e32 v91, v105
	v_rcp_f32_e32 v104, v122
	v_rcp_f32_e32 v105, v123
	v_rcp_f32_e32 v106, v106
	v_rcp_f32_e32 v107, v107
	v_lshlrev_b32_e32 v118, 16, v110
	v_and_b32_e32 v119, 0xffff0000, v110
	v_lshlrev_b32_e32 v110, 16, v111
	v_and_b32_e32 v111, 0xffff0000, v111
	v_pk_mul_f32 v[88:89], v[88:89], v[118:119]
	v_pk_mul_f32 v[90:91], v[90:91], v[120:121]
	v_pk_mul_f32 v[104:105], v[104:105], v[110:111]
	v_pk_mul_f32 v[94:95], v[106:107], v[94:95]
	v_pk_mul_f32 v[88:89], v[90:91], v[88:89]
	v_pk_mul_f32 v[90:91], v[94:95], v[104:105]
	v_cvt_pk_bf16_f32 v88, v88, v89
	v_cvt_pk_bf16_f32 v89, v90, v91
	global_store_dwordx2 v[92:93], v[88:89], off offset:32
	v_lshl_add_u64 v[88:89], s[12:13], 0, v[114:115]
	global_load_dwordx2 v[94:95], v[116:117], off
	global_load_dwordx2 v[104:105], v[88:89], off
	s_nop 0
	global_load_dwordx4 v[88:91], v[128:129], off offset:128
	v_mfma_f32_16x16x32_bf16 v[84:87], v[36:39], v[96:99], v[84:87]
	v_lshl_add_u64 v[106:107], v[108:109], 0, v[112:113]
	v_lshlrev_b64 v[106:107], 1, v[106:107]
	v_lshl_add_u64 v[108:109], s[10:11], 0, v[106:107]
	v_mfma_f32_16x16x32_bf16 v[80:83], v[24:27], v[100:103], v[80:83]
	s_waitcnt vmcnt(1)
	v_lshlrev_b32_e32 v114, 16, v104
	v_and_b32_e32 v115, 0xffff0000, v104
	v_lshlrev_b32_e32 v104, 16, v105
	v_and_b32_e32 v105, 0xffff0000, v105
	s_waitcnt vmcnt(0)
; DI void st_bf4(bf16_t* p, float a, float b, float c, float d) { uint2 v; v.x = pack2(a, b); v.y = pack2(c, d); *(uint2*)p = v; }
; DI float sigmoidf_(float x) { return __builtin_amdgcn_rcpf(1.0f + __expf(-x)); }
; DI float siluf_(float x) { return x * sigmoidf_(x); }
; DI void phase_g2(const Params& p, const Sub& s, char* lds_all) {
;     ...
;       [&](int row, int col) { const size_t o = (size_t)row * D + col; Ld2 r; const uint2 a = *(const uint2*)(A + o), b = *(const uint2*)(z + o);
;         r.a.x = __uint_as_float(a.x); r.a.y = __uint_as_float(a.y); r.a.z = __uint_as_float(b.x); r.a.w = __uint_as_float(b.y); r.b = *(const float4*)(p.s5_b_glu + col); return r; },
;       [&](int row, int col, f32x4 v, const Ld2& l2) {
;         uint4 ld; ld.x = __float_as_uint(l2.a.x); ld.y = __float_as_uint(l2.a.y); ld.z = __float_as_uint(l2.a.z); ld.w = __float_as_uint(l2.a.w);
;         const size_t o = (size_t)row * D + col;
;         const float y0 = __uint_as_float(ld.x << 16), y1 = __uint_as_float(ld.x & 0xffff0000u), y2_ = __uint_as_float(ld.y << 16), y3 = __uint_as_float(ld.y & 0xffff0000u);
;         const float z0 = __uint_as_float(ld.z << 16), z1 = __uint_as_float(ld.z & 0xffff0000u), z2 = __uint_as_float(ld.w << 16), z3 = __uint_as_float(ld.w & 0xffff0000u);
;         const float4 b4 = l2.b;
;         st_bf4(y2 + o, y0 * sigmoidf_(v[0] + b4.x) * siluf_(z0), y1 * sigmoidf_(v[1] + b4.y) * siluf_(z1),
;                y2_ * sigmoidf_(v[2] + b4.z) * siluf_(z2), y3 * sigmoidf_(v[3] + b4.w) * siluf_(z3));
	v_add_f32_e32 v84, v84, v88
	v_add_f32_e32 v85, v85, v89
	v_add_f32_e32 v86, v86, v90
	v_add_f32_e32 v87, v87, v91
	v_mul_f32_e32 v84, 0xbfb8aa3b, v84
	v_mul_f32_e32 v85, 0xbfb8aa3b, v85
	v_mul_f32_e32 v88, 0xbfb8aa3b, v114
	v_mul_f32_e32 v89, 0xbfb8aa3b, v115
	v_mul_f32_e32 v86, 0xbfb8aa3b, v86
	v_mul_f32_e32 v87, 0xbfb8aa3b, v87
	v_mul_f32_e32 v90, 0xbfb8aa3b, v104
	v_mul_f32_e32 v91, 0xbfb8aa3b, v105
	v_exp_f32_e32 v84, v84
	v_exp_f32_e32 v85, v85
	v_exp_f32_e32 v88, v88
	v_exp_f32_e32 v89, v89
	v_exp_f32_e32 v86, v86
	v_exp_f32_e32 v87, v87
	v_exp_f32_e32 v90, v90
	v_exp_f32_e32 v91, v91
	v_add_f32_e32 v84, 1.0, v84
	v_add_f32_e32 v85, 1.0, v85
	v_add_f32_e32 v88, 1.0, v88
	v_add_f32_e32 v89, 1.0, v89
	v_add_f32_e32 v116, 1.0, v86
	v_add_f32_e32 v117, 1.0, v87
	v_add_f32_e32 v90, 1.0, v90
	v_add_f32_e32 v91, 1.0, v91
	v_rcp_f32_e32 v84, v84
	v_rcp_f32_e32 v85, v85
	v_rcp_f32_e32 v86, v88
	v_rcp_f32_e32 v87, v89
	v_rcp_f32_e32 v88, v116
	v_rcp_f32_e32 v89, v117
	v_rcp_f32_e32 v90, v90
	v_rcp_f32_e32 v91, v91
	v_lshlrev_b32_e32 v110, 16, v94
	v_and_b32_e32 v111, 0xffff0000, v94
	v_lshlrev_b32_e32 v94, 16, v95
	v_and_b32_e32 v95, 0xffff0000, v95
	v_pk_mul_f32 v[84:85], v[84:85], v[110:111]
	v_pk_mul_f32 v[86:87], v[86:87], v[114:115]
	v_pk_mul_f32 v[88:89], v[88:89], v[94:95]
	v_pk_mul_f32 v[90:91], v[90:91], v[104:105]
	v_pk_mul_f32 v[84:85], v[86:87], v[84:85]
	v_pk_mul_f32 v[86:87], v[90:91], v[88:89]
	v_cvt_pk_bf16_f32 v84, v84, v85
	v_cvt_pk_bf16_f32 v85, v86, v87
	global_store_dwordx2 v[92:93], v[84:85], off offset:64
	v_lshl_add_u64 v[84:85], s[12:13], 0, v[106:107]
	global_load_dwordx2 v[90:91], v[108:109], off
	global_load_dwordx2 v[94:95], v[84:85], off
	global_load_dwordx4 v[86:89], v[128:129], off offset:192
	v_mfma_f32_16x16x32_bf16 v[80:83], v[16:19], v[96:99], v[80:83]
	v_or_b32_e32 v104, 32, v134
	v_ashrrev_i32_e32 v105, 31, v104
	v_lshlrev_b64 v[84:85], 10, v[104:105]
	v_lshl_add_u64 v[100:101], v[84:85], 0, v[130:131]
	v_lshlrev_b64 v[100:101], 1, v[100:101]
	v_lshl_add_u64 v[102:103], s[10:11], 0, v[100:101]
	v_mfma_f32_16x16x32_bf16 v[64:67], v[52:55], v[76:79], v[64:67]
	s_waitcnt vmcnt(1)
	v_lshlrev_b32_e32 v98, 16, v94
	v_and_b32_e32 v99, 0xffff0000, v94
	v_lshlrev_b32_e32 v94, 16, v95
	v_and_b32_e32 v95, 0xffff0000, v95
	s_waitcnt vmcnt(0)
	v_add_f32_e32 v80, v80, v86
	v_add_f32_e32 v81, v81, v87
	v_add_f32_e32 v82, v82, v88
	v_add_f32_e32 v83, v83, v89
	v_mul_f32_e32 v80, 0xbfb8aa3b, v80
	v_mul_f32_e32 v81, 0xbfb8aa3b, v81
	v_mul_f32_e32 v86, 0xbfb8aa3b, v98
	v_mul_f32_e32 v87, 0xbfb8aa3b, v99
	v_mul_f32_e32 v82, 0xbfb8aa3b, v82
	v_mul_f32_e32 v83, 0xbfb8aa3b, v83
	v_mul_f32_e32 v88, 0xbfb8aa3b, v94
	v_mul_f32_e32 v89, 0xbfb8aa3b, v95
	v_exp_f32_e32 v80, v80
	v_exp_f32_e32 v81, v81
	v_exp_f32_e32 v86, v86
	v_exp_f32_e32 v87, v87
	v_exp_f32_e32 v82, v82
	v_exp_f32_e32 v83, v83
	v_exp_f32_e32 v88, v88
	v_exp_f32_e32 v89, v89
	v_add_f32_e32 v80, 1.0, v80
	v_add_f32_e32 v81, 1.0, v81
	v_add_f32_e32 v86, 1.0, v86
	v_add_f32_e32 v87, 1.0, v87
	v_add_f32_e32 v106, 1.0, v82
	v_add_f32_e32 v107, 1.0, v83
	v_add_f32_e32 v88, 1.0, v88
	v_add_f32_e32 v89, 1.0, v89
	v_rcp_f32_e32 v80, v80
	v_rcp_f32_e32 v81, v81
	v_rcp_f32_e32 v82, v86
	v_rcp_f32_e32 v83, v87
	v_rcp_f32_e32 v86, v106
	v_rcp_f32_e32 v87, v107
	v_rcp_f32_e32 v88, v88
	v_rcp_f32_e32 v89, v89
	v_lshlrev_b32_e32 v96, 16, v90
	v_and_b32_e32 v97, 0xffff0000, v90
	v_lshlrev_b32_e32 v90, 16, v91
	v_and_b32_e32 v91, 0xffff0000, v91
	v_pk_mul_f32 v[80:81], v[80:81], v[96:97]
	v_pk_mul_f32 v[82:83], v[82:83], v[98:99]
	v_pk_mul_f32 v[86:87], v[86:87], v[90:91]
	v_pk_mul_f32 v[88:89], v[88:89], v[94:95]
	v_pk_mul_f32 v[80:81], v[82:83], v[80:81]
	v_pk_mul_f32 v[82:83], v[88:89], v[86:87]
	v_cvt_pk_bf16_f32 v80, v80, v81
	v_cvt_pk_bf16_f32 v81, v82, v83
	global_store_dwordx2 v[92:93], v[80:81], off offset:96
	v_lshl_add_u64 v[86:87], s[12:13], 0, v[100:101]
	global_load_dwordx2 v[90:91], v[102:103], off
	global_load_dwordx2 v[92:93], v[86:87], off
	global_load_dwordx4 v[80:83], v[128:129], off
	v_lshlrev_b64 v[86:87], 11, v[104:105]
	v_lshl_add_u64 v[94:95], s[14:15], 0, v[86:87]
	v_mfma_f32_16x16x32_bf16 v[86:89], v[60:63], v[76:79], v[68:71]
	v_lshl_add_u64 v[96:97], v[84:85], 0, v[132:133]
	s_waitcnt vmcnt(1)
	v_lshlrev_b32_e32 v98, 16, v92
	v_mfma_f32_16x16x32_bf16 v[86:89], v[56:59], v[72:75], v[86:89]
	v_and_b32_e32 v99, 0xffff0000, v92
	v_lshlrev_b32_e32 v92, 16, v93
	v_and_b32_e32 v93, 0xffff0000, v93
	v_lshlrev_b64 v[70:71], 1, v[96:97]
	v_lshlrev_b32_e32 v96, 16, v90
	s_waitcnt vmcnt(0)
	s_nop 1
	v_add_f32_e32 v80, v86, v80
	v_add_f32_e32 v81, v87, v81
	v_add_f32_e32 v82, v88, v82
	v_add_f32_e32 v83, v89, v83
	v_mul_f32_e32 v80, 0xbfb8aa3b, v80
	v_mul_f32_e32 v81, 0xbfb8aa3b, v81
	v_mul_f32_e32 v86, 0xbfb8aa3b, v98
	v_mul_f32_e32 v87, 0xbfb8aa3b, v99
	v_mul_f32_e32 v82, 0xbfb8aa3b, v82
	v_mul_f32_e32 v83, 0xbfb8aa3b, v83
	v_mul_f32_e32 v88, 0xbfb8aa3b, v92
	v_mul_f32_e32 v89, 0xbfb8aa3b, v93
	v_exp_f32_e32 v80, v80
	v_exp_f32_e32 v81, v81
	v_exp_f32_e32 v86, v86
	v_exp_f32_e32 v87, v87
	v_exp_f32_e32 v82, v82
	v_exp_f32_e32 v83, v83
	v_exp_f32_e32 v88, v88
	v_exp_f32_e32 v89, v89
	v_add_f32_e32 v80, 1.0, v80
	v_add_f32_e32 v81, 1.0, v81
	v_add_f32_e32 v86, 1.0, v86
	v_add_f32_e32 v87, 1.0, v87
	v_add_f32_e32 v100, 1.0, v82
	v_add_f32_e32 v101, 1.0, v83
	v_add_f32_e32 v88, 1.0, v88
	v_add_f32_e32 v89, 1.0, v89
	v_rcp_f32_e32 v80, v80
	v_rcp_f32_e32 v81, v81
	v_rcp_f32_e32 v82, v86
	v_rcp_f32_e32 v83, v87
	v_rcp_f32_e32 v86, v100
	v_rcp_f32_e32 v87, v101
	v_rcp_f32_e32 v88, v88
	v_rcp_f32_e32 v89, v89
	v_and_b32_e32 v97, 0xffff0000, v90
	v_lshlrev_b32_e32 v90, 16, v91
	v_and_b32_e32 v91, 0xffff0000, v91
	v_pk_mul_f32 v[80:81], v[80:81], v[96:97]
	v_pk_mul_f32 v[82:83], v[82:83], v[98:99]
	v_pk_mul_f32 v[86:87], v[86:87], v[90:91]
	v_pk_mul_f32 v[88:89], v[88:89], v[92:93]
	v_pk_mul_f32 v[80:81], v[82:83], v[80:81]
	v_pk_mul_f32 v[82:83], v[88:89], v[86:87]
	v_lshl_add_u64 v[68:69], v[94:95], 0, v[124:125]
	v_cvt_pk_bf16_f32 v80, v80, v81
	v_cvt_pk_bf16_f32 v81, v82, v83
	v_lshl_add_u64 v[94:95], s[10:11], 0, v[70:71]
	global_store_dwordx2 v[68:69], v[80:81], off
	v_lshl_add_u64 v[70:71], s[12:13], 0, v[70:71]
	global_load_dwordx2 v[86:87], v[94:95], off
	global_load_dwordx2 v[88:89], v[70:71], off
	global_load_dwordx4 v[80:83], v[128:129], off offset:64
	v_mfma_f32_16x16x32_bf16 v[64:67], v[44:47], v[72:75], v[64:67]
	v_lshl_add_u64 v[70:71], v[84:85], 0, v[126:127]
	v_lshlrev_b64 v[70:71], 1, v[70:71]
	v_lshl_add_u64 v[90:91], s[10:11], 0, v[70:71]
	v_lshl_add_u64 v[70:71], s[12:13], 0, v[70:71]
	v_mfma_f32_16x16x32_bf16 v[48:51], v[40:43], v[76:79], v[48:51]
	s_waitcnt vmcnt(1)
; DI void st_bf4(bf16_t* p, float a, float b, float c, float d) { uint2 v; v.x = pack2(a, b); v.y = pack2(c, d); *(uint2*)p = v; }
; DI float sigmoidf_(float x) { return __builtin_amdgcn_rcpf(1.0f + __expf(-x)); }
; DI float siluf_(float x) { return x * sigmoidf_(x); }
; DI void phase_g2(const Params& p, const Sub& s, char* lds_all) {
;     ...
;       [&](int row, int col) { const size_t o = (size_t)row * D + col; Ld2 r; const uint2 a = *(const uint2*)(A + o), b = *(const uint2*)(z + o);
;         r.a.x = __uint_as_float(a.x); r.a.y = __uint_as_float(a.y); r.a.z = __uint_as_float(b.x); r.a.w = __uint_as_float(b.y); r.b = *(const float4*)(p.s5_b_glu + col); return r; },
;       [&](int row, int col, f32x4 v, const Ld2& l2) {
;         uint4 ld; ld.x = __float_as_uint(l2.a.x); ld.y = __float_as_uint(l2.a.y); ld.z = __float_as_uint(l2.a.z); ld.w = __float_as_uint(l2.a.w);
;         const size_t o = (size_t)row * D + col;
;         const float y0 = __uint_as_float(ld.x << 16), y1 = __uint_as_float(ld.x & 0xffff0000u), y2_ = __uint_as_float(ld.y << 16), y3 = __uint_as_float(ld.y & 0xffff0000u);
;         const float z0 = __uint_as_float(ld.z << 16), z1 = __uint_as_float(ld.z & 0xffff0000u), z2 = __uint_as_float(ld.w << 16), z3 = __uint_as_float(ld.w & 0xffff0000u);
;         const float4 b4 = l2.b;
;         st_bf4(y2 + o, y0 * sigmoidf_(v[0] + b4.x) * siluf_(z0), y1 * sigmoidf_(v[1] + b4.y) * siluf_(z1),
;                y2_ * sigmoidf_(v[2] + b4.z) * siluf_(z2), y3 * sigmoidf_(v[3] + b4.w) * siluf_(z3));
	v_lshlrev_b32_e32 v94, 16, v88
	v_and_b32_e32 v95, 0xffff0000, v88
	v_lshlrev_b32_e32 v88, 16, v89
	v_and_b32_e32 v89, 0xffff0000, v89
	s_waitcnt vmcnt(0)
	v_add_f32_e32 v64, v64, v80
	v_add_f32_e32 v65, v65, v81
	v_add_f32_e32 v66, v66, v82
	v_add_f32_e32 v67, v67, v83
	v_mul_f32_e32 v64, 0xbfb8aa3b, v64
	v_mul_f32_e32 v65, 0xbfb8aa3b, v65
	v_mul_f32_e32 v80, 0xbfb8aa3b, v94
	v_mul_f32_e32 v81, 0xbfb8aa3b, v95
	v_mul_f32_e32 v66, 0xbfb8aa3b, v66
	v_mul_f32_e32 v67, 0xbfb8aa3b, v67
	v_mul_f32_e32 v82, 0xbfb8aa3b, v88
	v_mul_f32_e32 v83, 0xbfb8aa3b, v89
	v_exp_f32_e32 v64, v64
	v_exp_f32_e32 v65, v65
	v_exp_f32_e32 v80, v80
	v_exp_f32_e32 v81, v81
	v_exp_f32_e32 v66, v66
	v_exp_f32_e32 v67, v67
	v_exp_f32_e32 v82, v82
	v_exp_f32_e32 v83, v83
	v_add_f32_e32 v64, 1.0, v64
	v_add_f32_e32 v65, 1.0, v65
	v_add_f32_e32 v80, 1.0, v80
	v_add_f32_e32 v81, 1.0, v81
	v_add_f32_e32 v96, 1.0, v66
	v_add_f32_e32 v97, 1.0, v67
	v_add_f32_e32 v82, 1.0, v82
	v_add_f32_e32 v83, 1.0, v83
	v_rcp_f32_e32 v64, v64
	v_rcp_f32_e32 v65, v65
	v_rcp_f32_e32 v66, v80
	v_rcp_f32_e32 v67, v81
	v_rcp_f32_e32 v80, v96
	v_rcp_f32_e32 v81, v97
	v_rcp_f32_e32 v82, v82
	v_rcp_f32_e32 v83, v83
	v_lshlrev_b32_e32 v92, 16, v86
	v_and_b32_e32 v93, 0xffff0000, v86
	v_lshlrev_b32_e32 v86, 16, v87
	v_and_b32_e32 v87, 0xffff0000, v87
	v_pk_mul_f32 v[64:65], v[64:65], v[92:93]
	v_pk_mul_f32 v[66:67], v[66:67], v[94:95]
	v_pk_mul_f32 v[80:81], v[80:81], v[86:87]
	v_pk_mul_f32 v[82:83], v[82:83], v[88:89]
	v_pk_mul_f32 v[64:65], v[66:67], v[64:65]
	v_pk_mul_f32 v[66:67], v[82:83], v[80:81]
	v_cvt_pk_bf16_f32 v64, v64, v65
	v_cvt_pk_bf16_f32 v65, v66, v67
	global_store_dwordx2 v[68:69], v[64:65], off offset:32
	global_load_dwordx2 v[80:81], v[90:91], off
	global_load_dwordx2 v[82:83], v[70:71], off
	s_nop 0
	global_load_dwordx4 v[64:67], v[128:129], off offset:128
	v_mfma_f32_16x16x32_bf16 v[48:51], v[36:39], v[72:75], v[48:51]
	v_lshl_add_u64 v[70:71], v[84:85], 0, v[112:113]
	v_lshlrev_b64 v[70:71], 1, v[70:71]
	v_lshl_add_u64 v[84:85], s[10:11], 0, v[70:71]
	v_mfma_f32_16x16x32_bf16 v[32:35], v[24:27], v[76:79], v[32:35]
	s_waitcnt vmcnt(1)
	v_lshlrev_b32_e32 v88, 16, v82
	v_and_b32_e32 v89, 0xffff0000, v82
	v_lshlrev_b32_e32 v82, 16, v83
	v_and_b32_e32 v83, 0xffff0000, v83
	s_waitcnt vmcnt(0)
	v_add_f32_e32 v48, v48, v64
	v_add_f32_e32 v49, v49, v65
	v_add_f32_e32 v50, v50, v66
	v_add_f32_e32 v51, v51, v67
	v_mul_f32_e32 v48, 0xbfb8aa3b, v48
	v_mul_f32_e32 v49, 0xbfb8aa3b, v49
	v_mul_f32_e32 v64, 0xbfb8aa3b, v88
	v_mul_f32_e32 v65, 0xbfb8aa3b, v89
	v_mul_f32_e32 v50, 0xbfb8aa3b, v50
	v_mul_f32_e32 v51, 0xbfb8aa3b, v51
	v_mul_f32_e32 v66, 0xbfb8aa3b, v82
	v_mul_f32_e32 v67, 0xbfb8aa3b, v83
	v_exp_f32_e32 v48, v48
	v_exp_f32_e32 v49, v49
	v_exp_f32_e32 v64, v64
	v_exp_f32_e32 v65, v65
	v_exp_f32_e32 v50, v50
	v_exp_f32_e32 v51, v51
	v_exp_f32_e32 v66, v66
	v_exp_f32_e32 v67, v67
	v_add_f32_e32 v48, 1.0, v48
	v_add_f32_e32 v49, 1.0, v49
	v_add_f32_e32 v64, 1.0, v64
	v_add_f32_e32 v65, 1.0, v65
	v_add_f32_e32 v90, 1.0, v50
	v_add_f32_e32 v91, 1.0, v51
	v_add_f32_e32 v66, 1.0, v66
	v_add_f32_e32 v67, 1.0, v67
	v_rcp_f32_e32 v48, v48
	v_rcp_f32_e32 v49, v49
	v_rcp_f32_e32 v50, v64
	v_rcp_f32_e32 v51, v65
	v_rcp_f32_e32 v64, v90
	v_rcp_f32_e32 v65, v91
	v_rcp_f32_e32 v66, v66
	v_rcp_f32_e32 v67, v67
	v_lshlrev_b32_e32 v86, 16, v80
	v_and_b32_e32 v87, 0xffff0000, v80
	v_lshlrev_b32_e32 v80, 16, v81
	v_and_b32_e32 v81, 0xffff0000, v81
	v_pk_mul_f32 v[48:49], v[48:49], v[86:87]
	v_pk_mul_f32 v[50:51], v[50:51], v[88:89]
	v_pk_mul_f32 v[64:65], v[64:65], v[80:81]
	v_pk_mul_f32 v[66:67], v[66:67], v[82:83]
	v_pk_mul_f32 v[48:49], v[50:51], v[48:49]
	v_pk_mul_f32 v[50:51], v[66:67], v[64:65]
	v_cvt_pk_bf16_f32 v48, v48, v49
	v_cvt_pk_bf16_f32 v49, v50, v51
	global_store_dwordx2 v[68:69], v[48:49], off offset:64
	v_lshl_add_u64 v[48:49], s[12:13], 0, v[70:71]
	global_load_dwordx2 v[50:51], v[84:85], off
	global_load_dwordx2 v[70:71], v[48:49], off
	global_load_dwordx4 v[64:67], v[128:129], off offset:192
	v_mfma_f32_16x16x32_bf16 v[32:35], v[16:19], v[72:75], v[32:35]
	v_or_b32_e32 v80, 48, v134
	v_ashrrev_i32_e32 v81, 31, v80
	v_lshlrev_b64 v[48:49], 10, v[80:81]
	v_lshl_add_u64 v[76:77], v[48:49], 0, v[130:131]
	v_lshlrev_b64 v[76:77], 1, v[76:77]
	v_lshl_add_u64 v[78:79], s[10:11], 0, v[76:77]
	v_mfma_f32_16x16x32_bf16 v[60:63], v[60:63], v[28:31], v[12:15]
	s_waitcnt vmcnt(1)
	v_lshlrev_b32_e32 v74, 16, v70
	v_and_b32_e32 v75, 0xffff0000, v70
	v_lshlrev_b32_e32 v70, 16, v71
	v_and_b32_e32 v71, 0xffff0000, v71
	s_waitcnt vmcnt(0)
; DI void st_bf4(bf16_t* p, float a, float b, float c, float d) { uint2 v; v.x = pack2(a, b); v.y = pack2(c, d); *(uint2*)p = v; }
; DI float sigmoidf_(float x) { return __builtin_amdgcn_rcpf(1.0f + __expf(-x)); }
; DI float siluf_(float x) { return x * sigmoidf_(x); }
; DI void phase_g2(const Params& p, const Sub& s, char* lds_all) {
;     ...
;       [&](int row, int col) { const size_t o = (size_t)row * D + col; Ld2 r; const uint2 a = *(const uint2*)(A + o), b = *(const uint2*)(z + o);
;         r.a.x = __uint_as_float(a.x); r.a.y = __uint_as_float(a.y); r.a.z = __uint_as_float(b.x); r.a.w = __uint_as_float(b.y); r.b = *(const float4*)(p.s5_b_glu + col); return r; },
;       [&](int row, int col, f32x4 v, const Ld2& l2) {
;         uint4 ld; ld.x = __float_as_uint(l2.a.x); ld.y = __float_as_uint(l2.a.y); ld.z = __float_as_uint(l2.a.z); ld.w = __float_as_uint(l2.a.w);
;         const size_t o = (size_t)row * D + col;
;         const float y0 = __uint_as_float(ld.x << 16), y1 = __uint_as_float(ld.x & 0xffff0000u), y2_ = __uint_as_float(ld.y << 16), y3 = __uint_as_float(ld.y & 0xffff0000u);
;         const float z0 = __uint_as_float(ld.z << 16), z1 = __uint_as_float(ld.z & 0xffff0000u), z2 = __uint_as_float(ld.w << 16), z3 = __uint_as_float(ld.w & 0xffff0000u);
;         const float4 b4 = l2.b;
;         st_bf4(y2 + o, y0 * sigmoidf_(v[0] + b4.x) * siluf_(z0), y1 * sigmoidf_(v[1] + b4.y) * siluf_(z1),
;                y2_ * sigmoidf_(v[2] + b4.z) * siluf_(z2), y3 * sigmoidf_(v[3] + b4.w) * siluf_(z3));
	v_add_f32_e32 v32, v32, v64
	v_add_f32_e32 v33, v33, v65
	v_add_f32_e32 v34, v34, v66
	v_add_f32_e32 v35, v35, v67
	v_mul_f32_e32 v32, 0xbfb8aa3b, v32
	v_mul_f32_e32 v33, 0xbfb8aa3b, v33
	v_mul_f32_e32 v64, 0xbfb8aa3b, v74
	v_mul_f32_e32 v65, 0xbfb8aa3b, v75
	v_mul_f32_e32 v34, 0xbfb8aa3b, v34
	v_mul_f32_e32 v35, 0xbfb8aa3b, v35
	v_mul_f32_e32 v66, 0xbfb8aa3b, v70
	v_mul_f32_e32 v67, 0xbfb8aa3b, v71
	v_exp_f32_e32 v32, v32
	v_exp_f32_e32 v33, v33
	v_exp_f32_e32 v64, v64
	v_exp_f32_e32 v65, v65
	v_exp_f32_e32 v34, v34
	v_exp_f32_e32 v35, v35
	v_exp_f32_e32 v66, v66
	v_exp_f32_e32 v67, v67
	v_add_f32_e32 v32, 1.0, v32
	v_add_f32_e32 v33, 1.0, v33
	v_add_f32_e32 v64, 1.0, v64
	v_add_f32_e32 v65, 1.0, v65
	v_add_f32_e32 v82, 1.0, v34
	v_add_f32_e32 v83, 1.0, v35
	v_add_f32_e32 v66, 1.0, v66
	v_add_f32_e32 v67, 1.0, v67
	v_rcp_f32_e32 v32, v32
	v_rcp_f32_e32 v33, v33
	v_rcp_f32_e32 v34, v64
	v_rcp_f32_e32 v35, v65
	v_rcp_f32_e32 v64, v82
	v_rcp_f32_e32 v65, v83
	v_rcp_f32_e32 v66, v66
	v_rcp_f32_e32 v67, v67
	v_lshlrev_b32_e32 v72, 16, v50
	v_and_b32_e32 v73, 0xffff0000, v50
	v_lshlrev_b32_e32 v50, 16, v51
	v_and_b32_e32 v51, 0xffff0000, v51
	v_pk_mul_f32 v[32:33], v[32:33], v[72:73]
	v_pk_mul_f32 v[34:35], v[34:35], v[74:75]
	v_pk_mul_f32 v[50:51], v[64:65], v[50:51]
	v_pk_mul_f32 v[64:65], v[66:67], v[70:71]
	v_pk_mul_f32 v[32:33], v[34:35], v[32:33]
	v_pk_mul_f32 v[34:35], v[64:65], v[50:51]
	v_cvt_pk_bf16_f32 v32, v32, v33
	v_cvt_pk_bf16_f32 v33, v34, v35
	global_store_dwordx2 v[68:69], v[32:33], off offset:96
	v_lshl_add_u64 v[64:65], s[12:13], 0, v[76:77]
	global_load_dwordx2 v[50:51], v[78:79], off
	global_load_dwordx2 v[66:67], v[64:65], off
	global_load_dwordx4 v[32:35], v[128:129], off
	v_mfma_f32_16x16x32_bf16 v[56:59], v[56:59], v[20:23], v[60:63]
	v_lshl_add_u64 v[68:69], v[48:49], 0, v[132:133]
	v_lshlrev_b64 v[14:15], 1, v[68:69]
	v_lshlrev_b64 v[64:65], 11, v[80:81]
	v_lshl_add_u64 v[64:65], s[14:15], 0, v[64:65]
	v_lshl_add_u64 v[12:13], v[64:65], 0, v[124:125]
	v_lshl_add_u64 v[64:65], s[10:11], 0, v[14:15]
	v_lshl_add_u64 v[14:15], s[12:13], 0, v[14:15]
	v_mfma_f32_16x16x32_bf16 v[8:11], v[52:55], v[28:31], v[8:11]
	s_waitcnt vmcnt(1)
	v_lshlrev_b32_e32 v62, 16, v66
	v_and_b32_e32 v63, 0xffff0000, v66
	v_lshlrev_b32_e32 v66, 16, v67
	v_and_b32_e32 v67, 0xffff0000, v67
	s_waitcnt vmcnt(0)
	v_add_f32_e32 v32, v56, v32
	v_add_f32_e32 v33, v57, v33
	v_add_f32_e32 v34, v58, v34
	v_add_f32_e32 v35, v59, v35
	v_mul_f32_e32 v32, 0xbfb8aa3b, v32
	v_mul_f32_e32 v33, 0xbfb8aa3b, v33
	v_mul_f32_e32 v56, 0xbfb8aa3b, v62
	v_mul_f32_e32 v57, 0xbfb8aa3b, v63
	v_mul_f32_e32 v34, 0xbfb8aa3b, v34
	v_mul_f32_e32 v35, 0xbfb8aa3b, v35
	v_mul_f32_e32 v58, 0xbfb8aa3b, v66
	v_mul_f32_e32 v59, 0xbfb8aa3b, v67
	v_exp_f32_e32 v32, v32
	v_exp_f32_e32 v33, v33
	v_exp_f32_e32 v56, v56
	v_exp_f32_e32 v57, v57
	v_exp_f32_e32 v34, v34
	v_exp_f32_e32 v35, v35
	v_exp_f32_e32 v58, v58
	v_exp_f32_e32 v59, v59
	v_add_f32_e32 v32, 1.0, v32
	v_add_f32_e32 v33, 1.0, v33
	v_add_f32_e32 v56, 1.0, v56
	v_add_f32_e32 v57, 1.0, v57
	v_add_f32_e32 v68, 1.0, v34
	v_add_f32_e32 v69, 1.0, v35
	v_add_f32_e32 v58, 1.0, v58
	v_add_f32_e32 v59, 1.0, v59
	v_rcp_f32_e32 v32, v32
	v_rcp_f32_e32 v33, v33
	v_rcp_f32_e32 v34, v56
	v_rcp_f32_e32 v35, v57
	v_rcp_f32_e32 v56, v68
	v_rcp_f32_e32 v57, v69
	v_rcp_f32_e32 v58, v58
	v_rcp_f32_e32 v59, v59
	v_lshlrev_b32_e32 v60, 16, v50
	v_and_b32_e32 v61, 0xffff0000, v50
	v_lshlrev_b32_e32 v50, 16, v51
	v_and_b32_e32 v51, 0xffff0000, v51
	v_pk_mul_f32 v[32:33], v[32:33], v[60:61]
	v_pk_mul_f32 v[34:35], v[34:35], v[62:63]
	v_pk_mul_f32 v[50:51], v[56:57], v[50:51]
	v_pk_mul_f32 v[56:57], v[58:59], v[66:67]
	v_pk_mul_f32 v[32:33], v[34:35], v[32:33]
	v_pk_mul_f32 v[34:35], v[56:57], v[50:51]
	v_cvt_pk_bf16_f32 v32, v32, v33
	v_cvt_pk_bf16_f32 v33, v34, v35
	global_store_dwordx2 v[12:13], v[32:33], off
	global_load_dwordx2 v[50:51], v[64:65], off
	global_load_dwordx2 v[56:57], v[14:15], off
	s_nop 0
	global_load_dwordx4 v[32:35], v[128:129], off offset:64
	v_mfma_f32_16x16x32_bf16 v[8:11], v[44:47], v[20:23], v[8:11]
	v_lshl_add_u64 v[14:15], v[48:49], 0, v[126:127]
	v_lshlrev_b64 v[14:15], 1, v[14:15]
	v_lshl_add_u64 v[52:53], s[10:11], 0, v[14:15]
	v_lshl_add_u64 v[14:15], s[12:13], 0, v[14:15]
	v_mfma_f32_16x16x32_bf16 v[4:7], v[40:43], v[28:31], v[4:7]
	s_waitcnt vmcnt(2)
	v_lshlrev_b32_e32 v44, 16, v50
	v_and_b32_e32 v45, 0xffff0000, v50
	v_lshlrev_b32_e32 v46, 16, v51
	v_and_b32_e32 v47, 0xffff0000, v51
	s_waitcnt vmcnt(1)
	v_lshlrev_b32_e32 v50, 16, v56
	v_and_b32_e32 v51, 0xffff0000, v56
	v_lshlrev_b32_e32 v54, 16, v57
	v_and_b32_e32 v55, 0xffff0000, v57
	s_waitcnt vmcnt(0)
; DI void st_bf4(bf16_t* p, float a, float b, float c, float d) { uint2 v; v.x = pack2(a, b); v.y = pack2(c, d); *(uint2*)p = v; }
; DI float sigmoidf_(float x) { return __builtin_amdgcn_rcpf(1.0f + __expf(-x)); }
; DI float siluf_(float x) { return x * sigmoidf_(x); }
; DI void phase_g2(const Params& p, const Sub& s, char* lds_all) {
;     ...
;       [&](int row, int col) { const size_t o = (size_t)row * D + col; Ld2 r; const uint2 a = *(const uint2*)(A + o), b = *(const uint2*)(z + o);
;         r.a.x = __uint_as_float(a.x); r.a.y = __uint_as_float(a.y); r.a.z = __uint_as_float(b.x); r.a.w = __uint_as_float(b.y); r.b = *(const float4*)(p.s5_b_glu + col); return r; },
;       [&](int row, int col, f32x4 v, const Ld2& l2) {
;         uint4 ld; ld.x = __float_as_uint(l2.a.x); ld.y = __float_as_uint(l2.a.y); ld.z = __float_as_uint(l2.a.z); ld.w = __float_as_uint(l2.a.w);
;         const size_t o = (size_t)row * D + col;
;         const float y0 = __uint_as_float(ld.x << 16), y1 = __uint_as_float(ld.x & 0xffff0000u), y2_ = __uint_as_float(ld.y << 16), y3 = __uint_as_float(ld.y & 0xffff0000u);
;         const float z0 = __uint_as_float(ld.z << 16), z1 = __uint_as_float(ld.z & 0xffff0000u), z2 = __uint_as_float(ld.w << 16), z3 = __uint_as_float(ld.w & 0xffff0000u);
;         const float4 b4 = l2.b;
;         st_bf4(y2 + o, y0 * sigmoidf_(v[0] + b4.x) * siluf_(z0), y1 * sigmoidf_(v[1] + b4.y) * siluf_(z1),
;                y2_ * sigmoidf_(v[2] + b4.z) * siluf_(z2), y3 * sigmoidf_(v[3] + b4.w) * siluf_(z3));
	v_add_f32_e32 v8, v8, v32
	v_add_f32_e32 v9, v9, v33
	v_add_f32_e32 v10, v10, v34
	v_add_f32_e32 v11, v11, v35
	v_mul_f32_e32 v8, 0xbfb8aa3b, v8
	v_mul_f32_e32 v9, 0xbfb8aa3b, v9
	v_mul_f32_e32 v32, 0xbfb8aa3b, v50
	v_mul_f32_e32 v33, 0xbfb8aa3b, v51
	v_mul_f32_e32 v10, 0xbfb8aa3b, v10
	v_mul_f32_e32 v11, 0xbfb8aa3b, v11
	v_mul_f32_e32 v34, 0xbfb8aa3b, v54
	v_mul_f32_e32 v35, 0xbfb8aa3b, v55
	v_exp_f32_e32 v8, v8
	v_exp_f32_e32 v9, v9
	v_exp_f32_e32 v32, v32
	v_exp_f32_e32 v33, v33
	v_exp_f32_e32 v10, v10
	v_exp_f32_e32 v11, v11
	v_exp_f32_e32 v34, v34
	v_exp_f32_e32 v35, v35
	v_add_f32_e32 v8, 1.0, v8
	v_add_f32_e32 v9, 1.0, v9
	v_add_f32_e32 v32, 1.0, v32
	v_add_f32_e32 v33, 1.0, v33
	v_add_f32_e32 v56, 1.0, v10
	v_add_f32_e32 v57, 1.0, v11
	v_add_f32_e32 v34, 1.0, v34
	v_add_f32_e32 v35, 1.0, v35
	v_rcp_f32_e32 v8, v8
	v_rcp_f32_e32 v9, v9
	v_rcp_f32_e32 v10, v32
	v_rcp_f32_e32 v11, v33
	v_rcp_f32_e32 v32, v56
	v_rcp_f32_e32 v33, v57
	v_rcp_f32_e32 v34, v34
	v_rcp_f32_e32 v35, v35
	v_pk_mul_f32 v[8:9], v[8:9], v[44:45]
	v_pk_mul_f32 v[10:11], v[10:11], v[50:51]
	v_pk_mul_f32 v[32:33], v[32:33], v[46:47]
	v_pk_mul_f32 v[34:35], v[34:35], v[54:55]
	v_pk_mul_f32 v[8:9], v[10:11], v[8:9]
	v_pk_mul_f32 v[10:11], v[34:35], v[32:33]
	v_cvt_pk_bf16_f32 v8, v8, v9
	v_cvt_pk_bf16_f32 v9, v10, v11
	global_store_dwordx2 v[12:13], v[8:9], off offset:32
	global_load_dwordx2 v[32:33], v[52:53], off
	global_load_dwordx2 v[34:35], v[14:15], off
	s_nop 0
	global_load_dwordx4 v[8:11], v[128:129], off offset:128
	v_mfma_f32_16x16x32_bf16 v[4:7], v[36:39], v[20:23], v[4:7]
	v_lshl_add_u64 v[14:15], v[48:49], 0, v[112:113]
	v_lshlrev_b64 v[14:15], 1, v[14:15]
	v_lshl_add_u64 v[40:41], s[10:11], 0, v[14:15]
	v_mfma_f32_16x16x32_bf16 v[0:3], v[24:27], v[28:31], v[0:3]
	s_waitcnt vmcnt(1)
	v_lshlrev_b32_e32 v38, 16, v34
	v_and_b32_e32 v39, 0xffff0000, v34
	v_lshlrev_b32_e32 v34, 16, v35
	v_and_b32_e32 v35, 0xffff0000, v35
	s_waitcnt vmcnt(0)
	v_add_f32_e32 v4, v4, v8
	v_add_f32_e32 v5, v5, v9
	v_add_f32_e32 v6, v6, v10
	v_add_f32_e32 v7, v7, v11
	v_mul_f32_e32 v4, 0xbfb8aa3b, v4
	v_mul_f32_e32 v5, 0xbfb8aa3b, v5
	v_mul_f32_e32 v8, 0xbfb8aa3b, v38
	v_mul_f32_e32 v9, 0xbfb8aa3b, v39
	v_mul_f32_e32 v6, 0xbfb8aa3b, v6
	v_mul_f32_e32 v7, 0xbfb8aa3b, v7
	v_mul_f32_e32 v10, 0xbfb8aa3b, v34
	v_mul_f32_e32 v11, 0xbfb8aa3b, v35
	v_exp_f32_e32 v4, v4
	v_exp_f32_e32 v5, v5
	v_exp_f32_e32 v8, v8
	v_exp_f32_e32 v9, v9
	v_exp_f32_e32 v6, v6
	v_exp_f32_e32 v7, v7
	v_exp_f32_e32 v10, v10
	v_exp_f32_e32 v11, v11
	v_add_f32_e32 v4, 1.0, v4
	v_add_f32_e32 v5, 1.0, v5
	v_add_f32_e32 v8, 1.0, v8
	v_add_f32_e32 v9, 1.0, v9
	v_add_f32_e32 v42, 1.0, v6
	v_add_f32_e32 v43, 1.0, v7
	v_add_f32_e32 v10, 1.0, v10
	v_add_f32_e32 v11, 1.0, v11
	v_rcp_f32_e32 v4, v4
	v_rcp_f32_e32 v5, v5
	v_rcp_f32_e32 v6, v8
	v_rcp_f32_e32 v7, v9
	v_rcp_f32_e32 v8, v42
	v_rcp_f32_e32 v9, v43
	v_rcp_f32_e32 v10, v10
	v_rcp_f32_e32 v11, v11
	v_lshlrev_b32_e32 v36, 16, v32
	v_and_b32_e32 v37, 0xffff0000, v32
	v_lshlrev_b32_e32 v32, 16, v33
	v_and_b32_e32 v33, 0xffff0000, v33
	v_pk_mul_f32 v[4:5], v[4:5], v[36:37]
	v_pk_mul_f32 v[6:7], v[6:7], v[38:39]
	v_pk_mul_f32 v[8:9], v[8:9], v[32:33]
	v_pk_mul_f32 v[10:11], v[10:11], v[34:35]
	v_pk_mul_f32 v[4:5], v[6:7], v[4:5]
	v_pk_mul_f32 v[6:7], v[10:11], v[8:9]
	v_cvt_pk_bf16_f32 v4, v4, v5
	v_cvt_pk_bf16_f32 v5, v6, v7
	global_store_dwordx2 v[12:13], v[4:5], off offset:64
	v_lshl_add_u64 v[4:5], s[12:13], 0, v[14:15]
	global_load_dwordx2 v[8:9], v[40:41], off
	global_load_dwordx2 v[10:11], v[4:5], off
	v_mfma_f32_16x16x32_bf16 v[0:3], v[16:19], v[20:23], v[0:3]
	global_load_dwordx4 v[4:7], v[128:129], off offset:192
	s_waitcnt vmcnt(2)
	v_lshlrev_b32_e32 v14, 16, v8
	s_waitcnt vmcnt(1)
	v_lshlrev_b32_e32 v16, 16, v10
	v_and_b32_e32 v17, 0xffff0000, v10
	v_lshlrev_b32_e32 v10, 16, v11
	v_and_b32_e32 v11, 0xffff0000, v11
	s_waitcnt vmcnt(0)
	v_add_f32_e32 v0, v0, v4
	v_add_f32_e32 v1, v1, v5
	v_add_f32_e32 v2, v2, v6
	v_add_f32_e32 v3, v3, v7
	v_mul_f32_e32 v0, 0xbfb8aa3b, v0
	v_mul_f32_e32 v1, 0xbfb8aa3b, v1
	v_mul_f32_e32 v4, 0xbfb8aa3b, v16
	v_mul_f32_e32 v5, 0xbfb8aa3b, v17
	v_mul_f32_e32 v2, 0xbfb8aa3b, v2
	v_mul_f32_e32 v3, 0xbfb8aa3b, v3
	v_mul_f32_e32 v6, 0xbfb8aa3b, v10
	v_mul_f32_e32 v7, 0xbfb8aa3b, v11
	v_exp_f32_e32 v0, v0
	v_exp_f32_e32 v1, v1
	v_exp_f32_e32 v4, v4
	v_exp_f32_e32 v5, v5
	v_exp_f32_e32 v2, v2
	v_exp_f32_e32 v3, v3
	v_exp_f32_e32 v6, v6
	v_exp_f32_e32 v7, v7
	v_add_f32_e32 v0, 1.0, v0
	v_add_f32_e32 v1, 1.0, v1
	v_add_f32_e32 v4, 1.0, v4
	v_add_f32_e32 v5, 1.0, v5
	v_add_f32_e32 v18, 1.0, v2
	v_add_f32_e32 v19, 1.0, v3
	v_add_f32_e32 v6, 1.0, v6
	v_add_f32_e32 v7, 1.0, v7
	v_rcp_f32_e32 v0, v0
	v_rcp_f32_e32 v1, v1
	v_rcp_f32_e32 v2, v4
	v_rcp_f32_e32 v3, v5
	v_rcp_f32_e32 v4, v18
	v_rcp_f32_e32 v5, v19
	v_rcp_f32_e32 v6, v6
	v_rcp_f32_e32 v7, v7
	v_and_b32_e32 v15, 0xffff0000, v8
	v_lshlrev_b32_e32 v8, 16, v9
	v_and_b32_e32 v9, 0xffff0000, v9
	v_pk_mul_f32 v[0:1], v[0:1], v[14:15]
	v_pk_mul_f32 v[2:3], v[2:3], v[16:17]
	v_pk_mul_f32 v[4:5], v[4:5], v[8:9]
	v_pk_mul_f32 v[6:7], v[6:7], v[10:11]
	v_pk_mul_f32 v[0:1], v[2:3], v[0:1]
	v_pk_mul_f32 v[2:3], v[6:7], v[4:5]
	v_cvt_pk_bf16_f32 v0, v0, v1
	v_cvt_pk_bf16_f32 v1, v2, v3
	global_store_dwordx2 v[12:13], v[0:1], off offset:96

; #define MFMA16(a, b, c) __builtin_amdgcn_mfma_f32_16x16x32_bf16((a), (b), (c), 0, 0, 0)
; #define LAS __attribute__((address_space(3)))
; template <class FA, class FB, class FL, class FS>
; DI void gemm_tile(char* lds, int ksteps, int rot, FA fa, FB fb, FL fl, FS fs) {
;     ...
;   for (int ks = 0; ks < ksteps; ++ks) {
;     const int cur = ks & 1;
;     if (ks + 1 < ksteps) {
;       int kn = ks + 1 + rot; if (kn >= ksteps) kn -= ksteps;
;       LAS char* dst = l3 + (cur ^ 1) * 32768;
; #pragma unroll
;       for (int i = 0; i < 4; ++i) {
;         const int id = tid + i * 256, r = id >> 3, c = (id & 7) ^ (r & 7);
;         __builtin_amdgcn_global_load_lds((const unsigned*)fa(r, kn * 8 + c), (LAS unsigned*)(dst + id * 16), 16, 0, 0);
;         __builtin_amdgcn_global_load_lds((const unsigned*)fb(r, kn * 8 + c), (LAS unsigned*)(dst + 16384 + id * 16), 16, 0, 0);
;       }
;     }
;     const char* A = lds + cur * 32768;
;     const char* B = A + 16384;
; #pragma unroll
;     for (int kk = 0; kk < 2; ++kk) {
;       bf16x8 af[4], bq[4];
; #pragma unroll
;       for (int m = 0; m < 4; ++m) af[m] = ldfrag(A, 128, wr * 64 + m * 16 + fr, kk * 4 + fq);
; #pragma unroll
;       for (int n = 0; n < 4; ++n) bq[n] = ldfrag(B, 128, wc * 64 + n * 16 + fr, kk * 4 + fq);
; #pragma unroll
;       for (int m = 0; m < 4; ++m)
; #pragma unroll
;         for (int n = 0; n < 4; ++n) acc[m][n] = MFMA16(bq[n], af[m], acc[m][n]);
;     }
;     asm volatile("s_waitcnt vmcnt(0)" ::: "memory");
;     __syncthreads();
.LBB0_1541:
	s_and_b32 s2, s4, 0x8000
	s_xor_b32 s3, s2, 0x8000
	v_add_u32_e32 v89, s2, v84
	v_add_u32_e32 v106, s3, v84
	v_add_u32_e32 v107, v89, v85
	v_add_u32_e32 v108, v106, v76
	v_add_u32_e32 v114, v107, v88
	v_add_u32_e32 v111, v107, v86
	v_readfirstlane_b32 s2, v108
	v_add_u32_e32 v107, 0x4000, v108
	v_lshl_add_u64 v[90:91], v[68:69], 0, s[0:1]
	v_add_u32_e32 v109, v106, v77
	v_readfirstlane_b32 s7, v107
	s_mov_b32 m0, s2
	v_lshl_add_u64 v[92:93], v[70:71], 0, s[0:1]
	v_readfirstlane_b32 s3, v109
	v_add_u32_e32 v108, 0x4000, v109
	global_load_lds_dwordx4 v[90:91], off
	s_mov_b32 m0, s7
	v_lshl_add_u64 v[94:95], v[64:65], 0, s[0:1]
	v_add_u32_e32 v110, v106, v78
	v_readfirstlane_b32 s18, v108
	global_load_lds_dwordx4 v[92:93], off
	s_mov_b32 m0, s3
	v_lshl_add_u64 v[96:97], v[66:67], 0, s[0:1]
	v_readfirstlane_b32 s5, v110
	v_add_u32_e32 v109, 0x4000, v110
	global_load_lds_dwordx4 v[94:95], off
	s_mov_b32 m0, s18
	v_lshl_add_u64 v[98:99], v[56:57], 0, s[0:1]
	v_add_u32_e32 v106, v106, v79
	v_readfirstlane_b32 s19, v109
	global_load_lds_dwordx4 v[96:97], off
	s_mov_b32 m0, s5
	v_lshl_add_u64 v[100:101], v[58:59], 0, s[0:1]
	v_readfirstlane_b32 s6, v106
	v_add_u32_e32 v106, 0x4000, v106
	global_load_lds_dwordx4 v[98:99], off
	s_mov_b32 m0, s19
	v_lshl_add_u64 v[102:103], v[52:53], 0, s[0:1]
	v_readfirstlane_b32 s20, v106
	global_load_lds_dwordx4 v[100:101], off
	s_mov_b32 m0, s6
	v_lshl_add_u64 v[104:105], v[54:55], 0, s[0:1]
	global_load_lds_dwordx4 v[102:103], off
	s_mov_b32 m0, s20
	v_add_u32_e32 v89, v89, v87
	global_load_lds_dwordx4 v[104:105], off
	ds_read_b128 v[90:93], v111 offset:16384
	ds_read_b128 v[94:97], v111 offset:18432
	ds_read_b128 v[98:101], v114
	ds_read_b128 v[102:105], v114 offset:2048
	ds_read_b128 v[106:109], v111 offset:20480
	ds_read_b128 v[110:113], v111 offset:22528
	s_waitcnt lgkmcnt(0)
	v_mfma_f32_16x16x32_bf16 v[80:83], v[90:93], v[98:101], v[80:83]
	s_add_i32 s4, s4, 0x8000
	s_add_u32 s0, s0, 0x80
	s_addc_u32 s1, s1, 0
	v_mfma_f32_16x16x32_bf16 v[72:75], v[94:97], v[98:101], v[72:75]
	s_cmpk_lg_i32 s0, 0x780
	v_mfma_f32_16x16x32_bf16 v[60:63], v[106:109], v[98:101], v[60:63]
	v_mfma_f32_16x16x32_bf16 v[48:51], v[110:113], v[98:101], v[48:51]
	v_mfma_f32_16x16x32_bf16 v[44:47], v[90:93], v[102:105], v[44:47]
	v_mfma_f32_16x16x32_bf16 v[40:43], v[94:97], v[102:105], v[40:43]
	v_mfma_f32_16x16x32_bf16 v[36:39], v[106:109], v[102:105], v[36:39]
	v_mfma_f32_16x16x32_bf16 v[32:35], v[110:113], v[102:105], v[32:35]
	ds_read_b128 v[98:101], v114 offset:4096
	ds_read_b128 v[102:105], v114 offset:6144
	v_add_u32_e32 v114, v89, v88
	v_add_u32_e32 v89, v89, v86
	s_waitcnt lgkmcnt(1)
	v_mfma_f32_16x16x32_bf16 v[28:31], v[90:93], v[98:101], v[28:31]
	v_mfma_f32_16x16x32_bf16 v[24:27], v[94:97], v[98:101], v[24:27]
	v_mfma_f32_16x16x32_bf16 v[20:23], v[106:109], v[98:101], v[20:23]
	v_mfma_f32_16x16x32_bf16 v[12:15], v[110:113], v[98:101], v[12:15]
	s_waitcnt lgkmcnt(0)
	v_mfma_f32_16x16x32_bf16 v[8:11], v[90:93], v[102:105], v[8:11]
	v_mfma_f32_16x16x32_bf16 v[4:7], v[94:97], v[102:105], v[4:7]
	ds_read_b128 v[90:93], v89 offset:16384
	ds_read_b128 v[94:97], v89 offset:18432
	v_mfma_f32_16x16x32_bf16 v[16:19], v[106:109], v[102:105], v[16:19]
	v_mfma_f32_16x16x32_bf16 v[0:3], v[110:113], v[102:105], v[0:3]
	ds_read_b128 v[98:101], v114
	ds_read_b128 v[102:105], v114 offset:2048
	ds_read_b128 v[106:109], v89 offset:20480
	ds_read_b128 v[110:113], v89 offset:22528
	s_waitcnt lgkmcnt(3)
	v_mfma_f32_16x16x32_bf16 v[80:83], v[90:93], v[98:101], v[80:83]
	v_mfma_f32_16x16x32_bf16 v[72:75], v[94:97], v[98:101], v[72:75]
	s_waitcnt lgkmcnt(1)
	v_mfma_f32_16x16x32_bf16 v[60:63], v[106:109], v[98:101], v[60:63]
	s_waitcnt lgkmcnt(0)
	v_mfma_f32_16x16x32_bf16 v[48:51], v[110:113], v[98:101], v[48:51]
	v_mfma_f32_16x16x32_bf16 v[44:47], v[90:93], v[102:105], v[44:47]
	v_mfma_f32_16x16x32_bf16 v[40:43], v[94:97], v[102:105], v[40:43]
	v_mfma_f32_16x16x32_bf16 v[36:39], v[106:109], v[102:105], v[36:39]
	v_mfma_f32_16x16x32_bf16 v[32:35], v[110:113], v[102:105], v[32:35]
	ds_read_b128 v[98:101], v114 offset:4096
	ds_read_b128 v[102:105], v114 offset:6144
	s_waitcnt vmcnt(0)
	s_waitcnt lgkmcnt(0)
	v_mfma_f32_16x16x32_bf16 v[28:31], v[90:93], v[98:101], v[28:31]
	s_barrier
	v_mfma_f32_16x16x32_bf16 v[24:27], v[94:97], v[98:101], v[24:27]
	v_mfma_f32_16x16x32_bf16 v[20:23], v[106:109], v[98:101], v[20:23]
	v_mfma_f32_16x16x32_bf16 v[12:15], v[110:113], v[98:101], v[12:15]
	v_mfma_f32_16x16x32_bf16 v[8:11], v[90:93], v[102:105], v[8:11]
	v_mfma_f32_16x16x32_bf16 v[4:7], v[94:97], v[102:105], v[4:7]
	v_mfma_f32_16x16x32_bf16 v[16:19], v[106:109], v[102:105], v[16:19]
	v_mfma_f32_16x16x32_bf16 v[0:3], v[110:113], v[102:105], v[0:3]
	s_cbranch_scc1 .LBB0_1541
; DI float4 ldnt4(const float* p) { const f32x4 v = __builtin_nontemporal_load((const f32x4*)p); float4 r; r.x = v[0]; r.y = v[1]; r.z = v[2]; r.w = v[3]; return r; }
; #define MFMA16(a, b, c) __builtin_amdgcn_mfma_f32_16x16x32_bf16((a), (b), (c), 0, 0, 0)
; DI void st_bf4(bf16_t* p, float a, float b, float c, float d) { uint2 v; v.x = pack2(a, b); v.y = pack2(c, d); *(uint2*)p = v; }
; template <class FA, class FB, class FL, class FS>
; DI void gemm_tile(char* lds, int ksteps, int rot, FA fa, FB fb, FL fl, FS fs) {
;     ...
; #pragma unroll
;     for (int kk = 0; kk < 2; ++kk) {
;       bf16x8 af[4], bq[4];
; #pragma unroll
;       for (int m = 0; m < 4; ++m) af[m] = ldfrag(A, 128, wr * 64 + m * 16 + fr, kk * 4 + fq);
; #pragma unroll
;       for (int n = 0; n < 4; ++n) bq[n] = ldfrag(B, 128, wc * 64 + n * 16 + fr, kk * 4 + fq);
; #pragma unroll
;       for (int m = 0; m < 4; ++m)
; #pragma unroll
;         for (int n = 0; n < 4; ++n) acc[m][n] = MFMA16(bq[n], af[m], acc[m][n]);
; DI void phase_gout(const Params& p, const Sub& s, char* lds_all, int layer, const bf16_t* A, const bf16_t* Bt) {
;     ...
;       [&](int row, int col) {
;         const bf16_t* x1b = (const bf16_t*)p.out;
;         float4 x4;
;         if (layer == 0) x4 = ldnt4(xrow(p, row) + col);
;         else ld_bf4(x1b + (size_t)row * D + col, x4.x, x4.y, x4.z, x4.w);
;         Ld2 r; r.a = x4; r.b = *(const float4*)(mod + (size_t)(row_bi(row) * 2 + layer) * 3072 + 2048 + col);
;         return r;
;       },
;       [&](int row, int col, f32x4 v, const Ld2& l2) {
;         const float4 x4 = l2.a, g4 = l2.b;
;         bf16_t* x1b = (bf16_t*)p.out;
;         bf16_t* x2b = (bf16_t*)(p.ws + W_SLOT3);
;         st_bf4((layer == 0 ? x1b : x2b) + (size_t)row * D + col, x4.x + g4.x * v[0], x4.y + g4.y * v[1], x4.z + g4.z * v[2], x4.w + g4.w * v[3]);
	v_lshlrev_b32_e32 v125, 6, v125
	v_lshlrev_b32_e32 v121, 6, v121
	v_lshlrev_b32_e32 v123, 2, v123
	v_or3_b32 v122, v125, v122, v124
	s_mov_b32 s2, 0x10000
	v_add_u32_e32 v56, v84, v87
	v_add_u32_e32 v89, v84, v85
	v_or3_b32 v164, v123, v121, v120
	v_add_u32_e32 v125, 0xffff0000, v122
	v_ashrrev_i32_e32 v123, 31, v122
	v_cmp_gt_i32_e32 vcc, s2, v122
	v_add_u32_e32 v57, v56, v86
	v_add_u32_e32 v87, v56, v88
	v_add_u32_e32 v90, v89, v86
	v_add_u32_e32 v126, v89, v88
	v_cndmask_b32_e32 v121, 0, v123, vcc
	v_cndmask_b32_e32 v120, v125, v122, vcc
	v_mov_b32_e32 v174, s15
	v_mov_b32_e32 v175, s13
	v_mov_b32_e32 v176, s14
	v_mov_b32_e32 v177, s12
	v_ashrrev_i32_e32 v178, 13, v124
	v_lshrrev_b32_e32 v124, 4, v125
	s_add_u32 s0, s10, 0x1080000
	ds_read_b128 v[52:55], v57 offset:55296
	ds_read_b128 v[64:67], v57 offset:53248
	ds_read_b128 v[68:71], v57 offset:51200
	ds_read_b128 v[76:79], v57 offset:49152
	ds_read_b128 v[56:59], v87 offset:38912
	ds_read_b128 v[92:95], v87 offset:36864
	ds_read_b128 v[112:115], v87 offset:34816
	ds_read_b128 v[128:131], v87 offset:32768
	ds_read_b128 v[84:87], v90 offset:55296
	ds_read_b128 v[96:99], v90 offset:53248
	ds_read_b128 v[100:103], v90 offset:51200
	ds_read_b128 v[104:107], v90 offset:49152
	ds_read_b128 v[88:91], v126 offset:38912
	ds_read_b128 v[108:111], v126 offset:36864
	ds_read_b128 v[116:119], v126 offset:34816
	ds_read_b128 v[132:135], v126 offset:32768
	v_cndmask_b32_e32 v127, v174, v175, vcc
	v_cndmask_b32_e32 v126, v176, v177, vcc
	v_lshlrev_b64 v[120:121], 12, v[120:121]
	v_ashrrev_i32_e32 v165, 31, v164
	v_add_u32_e32 v124, 8, v124
	s_addc_u32 s1, s11, 0
	v_lshl_add_u64 v[126:127], v[126:127], 0, v[120:121]
	v_lshlrev_b64 v[120:121], 2, v[164:165]
	v_cndmask_b32_e32 v124, v124, v178, vcc
	v_lshl_add_u64 v[166:167], v[126:127], 0, v[120:121]
	v_lshlrev_b32_e32 v126, 1, v124
	s_movk_i32 s3, 0x3000
	v_mov_b64_e32 v[124:125], s[0:1]
	v_mad_i64_i32 v[126:127], s[0:1], v126, s3, v[124:125]
	s_mov_b64 s[0:1], 0x2000
	s_nop 0
	v_lshl_add_u64 v[168:169], v[126:127], 0, s[0:1]
	v_lshl_add_u64 v[126:127], v[168:169], 0, v[120:121]
	s_waitcnt vmcnt(0)
	s_waitcnt lgkmcnt(0)
	s_barrier
	global_load_dwordx4 v[136:139], v[166:167], off nt
	global_load_dwordx4 v[156:159], v[126:127], off
	v_lshlrev_b64 v[160:161], 11, v[122:123]
	v_lshl_add_u64 v[172:173], s[8:9], 0, v[160:161]
	v_mfma_f32_16x16x32_bf16 v[160:163], v[104:107], v[132:135], v[80:83]
	v_or_b32_e32 v170, 16, v164
	v_lshlrev_b64 v[126:127], 1, v[164:165]
	v_ashrrev_i32_e32 v171, 31, v170
	v_mfma_f32_16x16x32_bf16 v[160:163], v[76:79], v[128:131], v[160:163]
	v_lshl_add_u64 v[82:83], v[172:173], 0, v[126:127]
	v_lshlrev_b64 v[80:81], 2, v[170:171]
	v_lshl_add_u64 v[170:171], v[168:169], 0, v[80:81]
	v_mfma_f32_16x16x32_bf16 v[48:51], v[84:87], v[132:135], v[48:51]
	v_mfma_f32_16x16x32_bf16 v[48:51], v[52:55], v[128:131], v[48:51]
	s_waitcnt vmcnt(0)
	s_nop 1
	v_pk_fma_f32 v[136:137], v[160:161], v[156:157], v[136:137]
	v_pk_fma_f32 v[138:139], v[162:163], v[158:159], v[138:139]
	v_cvt_pk_bf16_f32 v136, v136, v137
	v_cvt_pk_bf16_f32 v137, v138, v139
	global_store_dwordx2 v[82:83], v[136:137], off
	global_load_dwordx4 v[136:139], v[166:167], off offset:64 nt
	s_nop 0
	global_load_dwordx4 v[156:159], v[170:171], off
	v_mfma_f32_16x16x32_bf16 v[160:163], v[100:103], v[132:135], v[72:75]
	v_or_b32_e32 v170, 32, v164
	v_ashrrev_i32_e32 v171, 31, v170
	v_mfma_f32_16x16x32_bf16 v[160:163], v[68:71], v[128:131], v[160:163]
	v_lshlrev_b64 v[72:73], 2, v[170:171]
	v_lshl_add_u64 v[74:75], v[168:169], 0, v[72:73]
	v_mfma_f32_16x16x32_bf16 v[44:47], v[104:107], v[116:119], v[44:47]
	v_mfma_f32_16x16x32_bf16 v[44:47], v[76:79], v[112:115], v[44:47]
	s_waitcnt vmcnt(0)
	s_nop 2
	v_pk_fma_f32 v[136:137], v[160:161], v[156:157], v[136:137]
	v_pk_fma_f32 v[138:139], v[162:163], v[158:159], v[138:139]
	v_cvt_pk_bf16_f32 v136, v136, v137
	v_cvt_pk_bf16_f32 v137, v138, v139
	global_store_dwordx2 v[82:83], v[136:137], off offset:32
	global_load_dwordx4 v[136:139], v[166:167], off offset:128 nt
	s_nop 0
	global_load_dwordx4 v[156:159], v[74:75], off
	v_mfma_f32_16x16x32_bf16 v[160:163], v[96:99], v[132:135], v[60:63]
	v_or_b32_e32 v74, 48, v164
	v_ashrrev_i32_e32 v75, 31, v74
	v_mfma_f32_16x16x32_bf16 v[160:163], v[64:67], v[128:131], v[160:163]
	v_lshlrev_b64 v[60:61], 2, v[74:75]
	v_lshl_add_u64 v[62:63], v[168:169], 0, v[60:61]
	v_mfma_f32_16x16x32_bf16 v[40:43], v[100:103], v[116:119], v[40:43]
	v_mfma_f32_16x16x32_bf16 v[40:43], v[68:71], v[112:115], v[40:43]
	s_waitcnt vmcnt(0)
	s_nop 2
	v_pk_fma_f32 v[74:75], v[160:161], v[156:157], v[136:137]
	v_pk_fma_f32 v[136:137], v[162:163], v[158:159], v[138:139]
	v_cvt_pk_bf16_f32 v74, v74, v75
	v_cvt_pk_bf16_f32 v75, v136, v137
	global_store_dwordx2 v[82:83], v[74:75], off offset:64
	global_load_dwordx4 v[136:139], v[166:167], off offset:192 nt
	global_load_dwordx4 v[156:159], v[62:63], off
	v_add_u32_e32 v74, 0xffff0010, v122
	v_or_b32_e32 v62, 16, v122
	v_lshrrev_b32_e32 v123, 4, v74
	v_ashrrev_i32_e32 v63, 31, v62
	v_cmp_gt_i32_e32 vcc, s2, v62
	v_add_u32_e32 v123, 8, v123
	v_mfma_f32_16x16x32_bf16 v[36:39], v[96:99], v[116:119], v[36:39]
	v_cndmask_b32_e32 v75, 0, v63, vcc
	v_cndmask_b32_e32 v74, v74, v62, vcc
	v_cndmask_b32_e32 v123, v123, v178, vcc
	v_cndmask_b32_e32 v161, v174, v175, vcc
	v_cndmask_b32_e32 v160, v176, v177, vcc
	v_lshlrev_b64 v[74:75], 12, v[74:75]
	v_lshlrev_b32_e32 v123, 1, v123
	v_lshl_add_u64 v[74:75], v[160:161], 0, v[74:75]
	v_mad_i64_i32 v[132:133], s[4:5], v123, s3, v[124:125]
	v_lshl_add_u64 v[74:75], v[74:75], 0, v[120:121]
	v_lshl_add_u64 v[132:133], v[132:133], 0, s[0:1]
	v_lshl_add_u64 v[134:135], v[132:133], 0, v[120:121]
	v_lshlrev_b64 v[62:63], 11, v[62:63]
	v_lshl_add_u64 v[62:63], s[8:9], 0, v[62:63]
	v_lshl_add_u64 v[62:63], v[62:63], 0, v[126:127]
	v_mfma_f32_16x16x32_bf16 v[36:39], v[64:67], v[112:115], v[36:39]
	s_waitcnt vmcnt(0)
; DI float4 ldnt4(const float* p) { const f32x4 v = __builtin_nontemporal_load((const f32x4*)p); float4 r; r.x = v[0]; r.y = v[1]; r.z = v[2]; r.w = v[3]; return r; }
; DI void st_bf4(bf16_t* p, float a, float b, float c, float d) { uint2 v; v.x = pack2(a, b); v.y = pack2(c, d); *(uint2*)p = v; }
; DI void phase_gout(const Params& p, const Sub& s, char* lds_all, int layer, const bf16_t* A, const bf16_t* Bt) {
;     ...
;       [&](int row, int col) {
;         const bf16_t* x1b = (const bf16_t*)p.out;
;         float4 x4;
;         if (layer == 0) x4 = ldnt4(xrow(p, row) + col);
;         else ld_bf4(x1b + (size_t)row * D + col, x4.x, x4.y, x4.z, x4.w);
;         Ld2 r; r.a = x4; r.b = *(const float4*)(mod + (size_t)(row_bi(row) * 2 + layer) * 3072 + 2048 + col);
;         return r;
;       },
;       [&](int row, int col, f32x4 v, const Ld2& l2) {
;         const float4 x4 = l2.a, g4 = l2.b;
;         bf16_t* x1b = (bf16_t*)p.out;
;         bf16_t* x2b = (bf16_t*)(p.ws + W_SLOT3);
;         st_bf4((layer == 0 ? x1b : x2b) + (size_t)row * D + col, x4.x + g4.x * v[0], x4.y + g4.y * v[1], x4.z + g4.z * v[2], x4.w + g4.w * v[3]);
	v_pk_fma_f32 v[48:49], v[48:49], v[156:157], v[136:137]
	v_pk_fma_f32 v[50:51], v[50:51], v[158:159], v[138:139]
	v_cvt_pk_bf16_f32 v48, v48, v49
	v_cvt_pk_bf16_f32 v49, v50, v51
	global_store_dwordx2 v[82:83], v[48:49], off offset:96
	global_load_dwordx4 v[48:51], v[74:75], off nt
	s_nop 0
	global_load_dwordx4 v[128:131], v[134:135], off
	v_lshl_add_u64 v[82:83], v[132:133], 0, v[80:81]
	v_mfma_f32_16x16x32_bf16 v[32:35], v[84:87], v[116:119], v[32:35]
	s_waitcnt vmcnt(0)
	v_pk_fma_f32 v[44:45], v[44:45], v[128:129], v[48:49]
	v_pk_fma_f32 v[46:47], v[46:47], v[130:131], v[50:51]
	v_cvt_pk_bf16_f32 v44, v44, v45
	v_cvt_pk_bf16_f32 v45, v46, v47
	global_store_dwordx2 v[62:63], v[44:45], off
	global_load_dwordx4 v[44:47], v[74:75], off offset:64 nt
	s_nop 0
	global_load_dwordx4 v[48:51], v[82:83], off
	v_lshl_add_u64 v[82:83], v[132:133], 0, v[72:73]
	v_mfma_f32_16x16x32_bf16 v[32:35], v[52:55], v[112:115], v[32:35]
	s_waitcnt vmcnt(0)
	v_pk_fma_f32 v[40:41], v[40:41], v[48:49], v[44:45]
	v_pk_fma_f32 v[42:43], v[42:43], v[50:51], v[46:47]
	v_cvt_pk_bf16_f32 v40, v40, v41
	v_cvt_pk_bf16_f32 v41, v42, v43
	global_store_dwordx2 v[62:63], v[40:41], off offset:32
	global_load_dwordx4 v[40:43], v[74:75], off offset:128 nt
	s_nop 0
	global_load_dwordx4 v[44:47], v[82:83], off
	v_lshl_add_u64 v[48:49], v[132:133], 0, v[60:61]
	v_mfma_f32_16x16x32_bf16 v[28:31], v[104:107], v[108:111], v[28:31]
	s_waitcnt vmcnt(0)
	v_pk_fma_f32 v[36:37], v[36:37], v[44:45], v[40:41]
	v_pk_fma_f32 v[38:39], v[38:39], v[46:47], v[42:43]
	v_cvt_pk_bf16_f32 v36, v36, v37
	v_cvt_pk_bf16_f32 v37, v38, v39
	global_store_dwordx2 v[62:63], v[36:37], off offset:64
	global_load_dwordx4 v[36:39], v[74:75], off offset:192 nt
	s_nop 0
	global_load_dwordx4 v[40:43], v[48:49], off
	v_or_b32_e32 v44, 32, v122
	v_add_u32_e32 v46, 0xffff0020, v122
	v_ashrrev_i32_e32 v45, 31, v44
	v_lshrrev_b32_e32 v50, 4, v46
	v_cmp_gt_i32_e32 vcc, s2, v44
	v_add_u32_e32 v50, 8, v50
	v_mfma_f32_16x16x32_bf16 v[28:31], v[76:79], v[92:95], v[28:31]
	v_cndmask_b32_e32 v47, 0, v45, vcc
	v_cndmask_b32_e32 v46, v46, v44, vcc
	v_cndmask_b32_e32 v49, v174, v175, vcc
	v_cndmask_b32_e32 v48, v176, v177, vcc
	v_lshlrev_b64 v[46:47], 12, v[46:47]
	v_cndmask_b32_e32 v50, v50, v178, vcc
	v_lshl_add_u64 v[46:47], v[48:49], 0, v[46:47]
	v_lshlrev_b32_e32 v48, 1, v50
	v_mad_i64_i32 v[48:49], s[4:5], v48, s3, v[124:125]
	v_lshl_add_u64 v[46:47], v[46:47], 0, v[120:121]
	v_lshl_add_u64 v[48:49], v[48:49], 0, s[0:1]
	v_lshl_add_u64 v[50:51], v[48:49], 0, v[120:121]
	v_mfma_f32_16x16x32_bf16 v[24:27], v[100:103], v[108:111], v[24:27]
	s_waitcnt vmcnt(0)
	v_pk_fma_f32 v[32:33], v[32:33], v[40:41], v[36:37]
	v_pk_fma_f32 v[34:35], v[34:35], v[42:43], v[38:39]
	v_cvt_pk_bf16_f32 v32, v32, v33
	v_cvt_pk_bf16_f32 v33, v34, v35
	global_store_dwordx2 v[62:63], v[32:33], off offset:96
	global_load_dwordx4 v[32:35], v[46:47], off nt
	s_nop 0
	global_load_dwordx4 v[36:39], v[50:51], off
	v_lshlrev_b64 v[40:41], 11, v[44:45]
	v_lshl_add_u64 v[40:41], s[8:9], 0, v[40:41]
	v_lshl_add_u64 v[40:41], v[40:41], 0, v[126:127]
	v_lshl_add_u64 v[42:43], v[48:49], 0, v[80:81]
	v_mfma_f32_16x16x32_bf16 v[24:27], v[68:71], v[92:95], v[24:27]
	s_waitcnt vmcnt(0)
	v_pk_fma_f32 v[28:29], v[28:29], v[36:37], v[32:33]
	v_pk_fma_f32 v[30:31], v[30:31], v[38:39], v[34:35]
	v_cvt_pk_bf16_f32 v28, v28, v29
	v_cvt_pk_bf16_f32 v29, v30, v31
	global_store_dwordx2 v[40:41], v[28:29], off
	global_load_dwordx4 v[28:31], v[46:47], off offset:64 nt
	s_nop 0
	global_load_dwordx4 v[32:35], v[42:43], off
	v_lshl_add_u64 v[36:37], v[48:49], 0, v[72:73]
	v_mfma_f32_16x16x32_bf16 v[20:23], v[96:99], v[108:111], v[20:23]
	s_waitcnt vmcnt(0)
; DI float4 ldnt4(const float* p) { const f32x4 v = __builtin_nontemporal_load((const f32x4*)p); float4 r; r.x = v[0]; r.y = v[1]; r.z = v[2]; r.w = v[3]; return r; }
; DI void st_bf4(bf16_t* p, float a, float b, float c, float d) { uint2 v; v.x = pack2(a, b); v.y = pack2(c, d); *(uint2*)p = v; }
; DI void phase_gout(const Params& p, const Sub& s, char* lds_all, int layer, const bf16_t* A, const bf16_t* Bt) {
;     ...
;       [&](int row, int col) {
;         const bf16_t* x1b = (const bf16_t*)p.out;
;         float4 x4;
;         if (layer == 0) x4 = ldnt4(xrow(p, row) + col);
;         else ld_bf4(x1b + (size_t)row * D + col, x4.x, x4.y, x4.z, x4.w);
;         Ld2 r; r.a = x4; r.b = *(const float4*)(mod + (size_t)(row_bi(row) * 2 + layer) * 3072 + 2048 + col);
;         return r;
;       },
;       [&](int row, int col, f32x4 v, const Ld2& l2) {
;         const float4 x4 = l2.a, g4 = l2.b;
;         bf16_t* x1b = (bf16_t*)p.out;
;         bf16_t* x2b = (bf16_t*)(p.ws + W_SLOT3);
;         st_bf4((layer == 0 ? x1b : x2b) + (size_t)row * D + col, x4.x + g4.x * v[0], x4.y + g4.y * v[1], x4.z + g4.z * v[2], x4.w + g4.w * v[3]);
	v_pk_fma_f32 v[24:25], v[24:25], v[32:33], v[28:29]
	v_pk_fma_f32 v[26:27], v[26:27], v[34:35], v[30:31]
	v_cvt_pk_bf16_f32 v24, v24, v25
	v_cvt_pk_bf16_f32 v25, v26, v27
	global_store_dwordx2 v[40:41], v[24:25], off offset:32
	global_load_dwordx4 v[24:27], v[46:47], off offset:128 nt
	s_nop 0
	global_load_dwordx4 v[28:31], v[36:37], off
	v_mfma_f32_16x16x32_bf16 v[20:23], v[64:67], v[92:95], v[20:23]
	v_lshl_add_u64 v[32:33], v[48:49], 0, v[60:61]
	v_mfma_f32_16x16x32_bf16 v[12:15], v[84:87], v[108:111], v[12:15]
	v_mfma_f32_16x16x32_bf16 v[12:15], v[52:55], v[92:95], v[12:15]
	s_waitcnt vmcnt(0)
	s_nop 3
	v_pk_fma_f32 v[20:21], v[20:21], v[28:29], v[24:25]
	v_pk_fma_f32 v[22:23], v[22:23], v[30:31], v[26:27]
	v_cvt_pk_bf16_f32 v20, v20, v21
	v_cvt_pk_bf16_f32 v21, v22, v23
	global_store_dwordx2 v[40:41], v[20:21], off offset:64
	global_load_dwordx4 v[20:23], v[46:47], off offset:192 nt
	s_nop 0
	global_load_dwordx4 v[24:27], v[32:33], off
	v_or_b32_e32 v28, 48, v122
	v_add_u32_e32 v30, 0xffff0030, v122
	v_ashrrev_i32_e32 v29, 31, v28
	v_lshrrev_b32_e32 v34, 4, v30
	v_cmp_gt_i32_e32 vcc, s2, v28
	v_add_u32_e32 v34, 8, v34
	v_mfma_f32_16x16x32_bf16 v[8:11], v[104:107], v[88:91], v[8:11]
	v_cndmask_b32_e32 v31, 0, v29, vcc
	v_cndmask_b32_e32 v30, v30, v28, vcc
	v_cndmask_b32_e32 v33, v174, v175, vcc
	v_cndmask_b32_e32 v32, v176, v177, vcc
	v_lshlrev_b64 v[30:31], 12, v[30:31]
	v_cndmask_b32_e32 v34, v34, v178, vcc
	v_lshl_add_u64 v[30:31], v[32:33], 0, v[30:31]
	v_lshlrev_b32_e32 v32, 1, v34
	v_mad_i64_i32 v[32:33], s[2:3], v32, s3, v[124:125]
	v_lshl_add_u64 v[30:31], v[30:31], 0, v[120:121]
	v_lshl_add_u64 v[32:33], v[32:33], 0, s[0:1]
	v_lshl_add_u64 v[34:35], v[32:33], 0, v[120:121]
	v_mfma_f32_16x16x32_bf16 v[8:11], v[76:79], v[56:59], v[8:11]
	s_waitcnt vmcnt(0)
	v_pk_fma_f32 v[12:13], v[12:13], v[24:25], v[20:21]
	v_pk_fma_f32 v[14:15], v[14:15], v[26:27], v[22:23]
	v_cvt_pk_bf16_f32 v12, v12, v13
	v_cvt_pk_bf16_f32 v13, v14, v15
	global_store_dwordx2 v[40:41], v[12:13], off offset:96
	global_load_dwordx4 v[12:15], v[30:31], off nt
	s_nop 0
	global_load_dwordx4 v[20:23], v[34:35], off
	v_lshlrev_b64 v[24:25], 11, v[28:29]
	v_lshl_add_u64 v[24:25], s[8:9], 0, v[24:25]
	v_lshl_add_u64 v[24:25], v[24:25], 0, v[126:127]
	v_lshl_add_u64 v[26:27], v[32:33], 0, v[80:81]
	v_mfma_f32_16x16x32_bf16 v[4:7], v[100:103], v[88:91], v[4:7]
	s_waitcnt vmcnt(0)
	v_pk_fma_f32 v[8:9], v[8:9], v[20:21], v[12:13]
	v_pk_fma_f32 v[10:11], v[10:11], v[22:23], v[14:15]
	v_cvt_pk_bf16_f32 v8, v8, v9
	v_cvt_pk_bf16_f32 v9, v10, v11
	global_store_dwordx2 v[24:25], v[8:9], off
	global_load_dwordx4 v[8:11], v[30:31], off offset:64 nt
	s_nop 0
	global_load_dwordx4 v[12:15], v[26:27], off
	v_mfma_f32_16x16x32_bf16 v[4:7], v[68:71], v[56:59], v[4:7]
	v_lshl_add_u64 v[20:21], v[32:33], 0, v[72:73]
	v_mfma_f32_16x16x32_bf16 v[16:19], v[96:99], v[88:91], v[16:19]
	v_mfma_f32_16x16x32_bf16 v[0:3], v[84:87], v[88:91], v[0:3]
	s_waitcnt vmcnt(0)
	s_nop 3
	v_pk_fma_f32 v[4:5], v[4:5], v[12:13], v[8:9]
	v_pk_fma_f32 v[6:7], v[6:7], v[14:15], v[10:11]
	v_cvt_pk_bf16_f32 v4, v4, v5
	v_cvt_pk_bf16_f32 v5, v6, v7
	global_store_dwordx2 v[24:25], v[4:5], off offset:32
	global_load_dwordx4 v[4:7], v[30:31], off offset:128 nt
	s_nop 0
	global_load_dwordx4 v[8:11], v[20:21], off
	v_mfma_f32_16x16x32_bf16 v[12:15], v[64:67], v[56:59], v[16:19]
	v_lshl_add_u64 v[20:21], v[32:33], 0, v[60:61]
	v_mfma_f32_16x16x32_bf16 v[0:3], v[52:55], v[56:59], v[0:3]
	s_waitcnt vmcnt(0)
	s_nop 4
	v_pk_fma_f32 v[4:5], v[12:13], v[8:9], v[4:5]
	v_pk_fma_f32 v[6:7], v[14:15], v[10:11], v[6:7]
	v_cvt_pk_bf16_f32 v4, v4, v5
	v_cvt_pk_bf16_f32 v5, v6, v7
	global_store_dwordx2 v[24:25], v[4:5], off offset:64
	global_load_dwordx4 v[4:7], v[30:31], off offset:192 nt
	s_nop 0
	global_load_dwordx4 v[8:11], v[20:21], off
	s_waitcnt vmcnt(0)
	v_pk_fma_f32 v[0:1], v[0:1], v[8:9], v[4:5]
	v_pk_fma_f32 v[2:3], v[2:3], v[10:11], v[6:7]
	v_cvt_pk_bf16_f32 v0, v0, v1
	v_cvt_pk_bf16_f32 v1, v2, v3
	global_store_dwordx2 v[24:25], v[0:1], off offset:96

; #define MFMA16(a, b, c) __builtin_amdgcn_mfma_f32_16x16x32_bf16((a), (b), (c), 0, 0, 0)
; #define LAS __attribute__((address_space(3)))
; template <class FA, class FB, class FL, class FS>
; DI void gemm_tile(char* lds, int ksteps, int rot, FA fa, FB fb, FL fl, FS fs) {
;     ...
;   for (int ks = 0; ks < ksteps; ++ks) {
;     const int cur = ks & 1;
;     if (ks + 1 < ksteps) {
;       int kn = ks + 1 + rot; if (kn >= ksteps) kn -= ksteps;
;       LAS char* dst = l3 + (cur ^ 1) * 32768;
; #pragma unroll
;       for (int i = 0; i < 4; ++i) {
;         const int id = tid + i * 256, r = id >> 3, c = (id & 7) ^ (r & 7);
;         __builtin_amdgcn_global_load_lds((const unsigned*)fa(r, kn * 8 + c), (LAS unsigned*)(dst + id * 16), 16, 0, 0);
;         __builtin_amdgcn_global_load_lds((const unsigned*)fb(r, kn * 8 + c), (LAS unsigned*)(dst + 16384 + id * 16), 16, 0, 0);
;       }
;     }
;     const char* A = lds + cur * 32768;
;     const char* B = A + 16384;
; #pragma unroll
;     for (int kk = 0; kk < 2; ++kk) {
;       bf16x8 af[4], bq[4];
; #pragma unroll
;       for (int m = 0; m < 4; ++m) af[m] = ldfrag(A, 128, wr * 64 + m * 16 + fr, kk * 4 + fq);
; #pragma unroll
;       for (int n = 0; n < 4; ++n) bq[n] = ldfrag(B, 128, wc * 64 + n * 16 + fr, kk * 4 + fq);
; #pragma unroll
;       for (int m = 0; m < 4; ++m)
; #pragma unroll
;         for (int n = 0; n < 4; ++n) acc[m][n] = MFMA16(bq[n], af[m], acc[m][n]);
;     }
;     asm volatile("s_waitcnt vmcnt(0)" ::: "memory");
;     __syncthreads();
.LBB0_1584:
	s_and_b32 s2, s4, 0x8000
	s_xor_b32 s3, s2, 0x8000
	v_add_u32_e32 v95, s2, v84
	v_add_u32_e32 v112, s3, v84
	v_add_u32_e32 v113, v95, v94
	v_add_u32_e32 v114, v112, v85
	v_add_u32_e32 v120, v113, v89
	v_add_u32_e32 v117, v113, v91
	v_readfirstlane_b32 s2, v114
	v_add_u32_e32 v113, 0x4000, v114
	v_lshl_add_u64 v[96:97], v[76:77], 0, s[0:1]
	v_add_u32_e32 v115, v112, v88
	v_readfirstlane_b32 s7, v113
	s_mov_b32 m0, s2
	v_lshl_add_u64 v[98:99], v[78:79], 0, s[0:1]
	v_readfirstlane_b32 s3, v115
	v_add_u32_e32 v114, 0x4000, v115
	global_load_lds_dwordx4 v[96:97], off
	s_mov_b32 m0, s7
	v_lshl_add_u64 v[100:101], v[72:73], 0, s[0:1]
	v_add_u32_e32 v116, v112, v90
	v_readfirstlane_b32 s8, v114
	global_load_lds_dwordx4 v[98:99], off
	s_mov_b32 m0, s3
	v_lshl_add_u64 v[102:103], v[74:75], 0, s[0:1]
	v_readfirstlane_b32 s5, v116
	v_add_u32_e32 v115, 0x4000, v116
	global_load_lds_dwordx4 v[100:101], off
	s_mov_b32 m0, s8
	v_lshl_add_u64 v[104:105], v[68:69], 0, s[0:1]
	v_add_u32_e32 v112, v112, v93
	v_readfirstlane_b32 s9, v115
	global_load_lds_dwordx4 v[102:103], off
	s_mov_b32 m0, s5
	v_lshl_add_u64 v[106:107], v[70:71], 0, s[0:1]
	v_readfirstlane_b32 s6, v112
	v_add_u32_e32 v112, 0x4000, v112
	global_load_lds_dwordx4 v[104:105], off
	s_mov_b32 m0, s9
	v_lshl_add_u64 v[108:109], v[64:65], 0, s[0:1]
	v_readfirstlane_b32 s10, v112
	global_load_lds_dwordx4 v[106:107], off
	s_mov_b32 m0, s6
	v_lshl_add_u64 v[110:111], v[66:67], 0, s[0:1]
	global_load_lds_dwordx4 v[108:109], off
	s_mov_b32 m0, s10
	v_add_u32_e32 v95, v95, v92
	global_load_lds_dwordx4 v[110:111], off
	ds_read_b128 v[96:99], v117 offset:16384
	ds_read_b128 v[100:103], v117 offset:18432
	ds_read_b128 v[104:107], v120
	ds_read_b128 v[108:111], v120 offset:2048
	ds_read_b128 v[112:115], v117 offset:20480
	ds_read_b128 v[116:119], v117 offset:22528
	s_waitcnt lgkmcnt(0)
	v_mfma_f32_16x16x32_bf16 v[60:63], v[96:99], v[104:107], v[60:63]
	s_add_i32 s4, s4, 0x8000
	s_add_u32 s0, s0, 0x80
	s_addc_u32 s1, s1, 0
	v_mfma_f32_16x16x32_bf16 v[56:59], v[100:103], v[104:107], v[56:59]
	s_cmpk_lg_i32 s0, 0x780
	v_mfma_f32_16x16x32_bf16 v[52:55], v[112:115], v[104:107], v[52:55]
	v_mfma_f32_16x16x32_bf16 v[44:47], v[116:119], v[104:107], v[44:47]
	v_mfma_f32_16x16x32_bf16 v[40:43], v[96:99], v[108:111], v[40:43]
	v_mfma_f32_16x16x32_bf16 v[36:39], v[100:103], v[108:111], v[36:39]
	v_mfma_f32_16x16x32_bf16 v[32:35], v[112:115], v[108:111], v[32:35]
	v_mfma_f32_16x16x32_bf16 v[28:31], v[116:119], v[108:111], v[28:31]
	ds_read_b128 v[104:107], v120 offset:4096
	ds_read_b128 v[108:111], v120 offset:6144
	v_add_u32_e32 v120, v95, v89
	v_add_u32_e32 v95, v95, v91
	s_waitcnt lgkmcnt(1)
	v_mfma_f32_16x16x32_bf16 v[24:27], v[96:99], v[104:107], v[24:27]
	v_mfma_f32_16x16x32_bf16 v[20:23], v[100:103], v[104:107], v[20:23]
	v_mfma_f32_16x16x32_bf16 v[16:19], v[112:115], v[104:107], v[16:19]
	v_mfma_f32_16x16x32_bf16 v[12:15], v[116:119], v[104:107], v[12:15]
	s_waitcnt lgkmcnt(0)
	v_mfma_f32_16x16x32_bf16 v[8:11], v[96:99], v[108:111], v[8:11]
	v_mfma_f32_16x16x32_bf16 v[4:7], v[100:103], v[108:111], v[4:7]
	ds_read_b128 v[96:99], v95 offset:16384
	ds_read_b128 v[100:103], v95 offset:18432
	v_mfma_f32_16x16x32_bf16 v[48:51], v[112:115], v[108:111], v[48:51]
	v_mfma_f32_16x16x32_bf16 v[0:3], v[116:119], v[108:111], v[0:3]
	ds_read_b128 v[104:107], v120
	ds_read_b128 v[108:111], v120 offset:2048
	ds_read_b128 v[112:115], v95 offset:20480
	ds_read_b128 v[116:119], v95 offset:22528
	s_waitcnt lgkmcnt(3)
	v_mfma_f32_16x16x32_bf16 v[60:63], v[96:99], v[104:107], v[60:63]
	v_mfma_f32_16x16x32_bf16 v[56:59], v[100:103], v[104:107], v[56:59]
	s_waitcnt lgkmcnt(1)
	v_mfma_f32_16x16x32_bf16 v[52:55], v[112:115], v[104:107], v[52:55]
	s_waitcnt lgkmcnt(0)
	v_mfma_f32_16x16x32_bf16 v[44:47], v[116:119], v[104:107], v[44:47]
	v_mfma_f32_16x16x32_bf16 v[40:43], v[96:99], v[108:111], v[40:43]
	v_mfma_f32_16x16x32_bf16 v[36:39], v[100:103], v[108:111], v[36:39]
	v_mfma_f32_16x16x32_bf16 v[32:35], v[112:115], v[108:111], v[32:35]
	v_mfma_f32_16x16x32_bf16 v[28:31], v[116:119], v[108:111], v[28:31]
	ds_read_b128 v[104:107], v120 offset:4096
	ds_read_b128 v[108:111], v120 offset:6144
	s_waitcnt vmcnt(0)
	s_waitcnt lgkmcnt(0)
	v_mfma_f32_16x16x32_bf16 v[24:27], v[96:99], v[104:107], v[24:27]
	s_barrier
; #define MFMA16(a, b, c) __builtin_amdgcn_mfma_f32_16x16x32_bf16((a), (b), (c), 0, 0, 0)
; DI void st_bf4(bf16_t* p, float a, float b, float c, float d) { uint2 v; v.x = pack2(a, b); v.y = pack2(c, d); *(uint2*)p = v; }
; template <class FA, class FB, class FL, class FS>
; DI void gemm_tile(char* lds, int ksteps, int rot, FA fa, FB fb, FL fl, FS fs) {
;     ...
; #pragma unroll
;     for (int kk = 0; kk < 2; ++kk) {
;       bf16x8 af[4], bq[4];
; #pragma unroll
;       for (int m = 0; m < 4; ++m) af[m] = ldfrag(A, 128, wr * 64 + m * 16 + fr, kk * 4 + fq);
; #pragma unroll
;       for (int n = 0; n < 4; ++n) bq[n] = ldfrag(B, 128, wc * 64 + n * 16 + fr, kk * 4 + fq);
; #pragma unroll
;       for (int m = 0; m < 4; ++m)
; #pragma unroll
;         for (int n = 0; n < 4; ++n) acc[m][n] = MFMA16(bq[n], af[m], acc[m][n]);
;     }
;     asm volatile("s_waitcnt vmcnt(0)" ::: "memory");
;     __syncthreads();
; DI void phase_g4(const Params& p, const Sub& s, char* lds_all) {
;     ...
;       [&](int row, int col, f32x4 v, const NoLoad&) {
;         if (col < 2048) {
;           st_bf4(qkv + (size_t)row * 2048 + col, v[0], v[1], v[2], v[3]);
;           if (row < MP) { const int l = row & 8191; if (l >= 8189) *(f32x4*)(p.out + O_CONV_P + ((size_t)(row >> 13) * 3 + (l - 8189)) * 2048 + col) = v; }
;           else { const int l = (row - MP) & 15; if (l >= 13) *(f32x4*)(p.out + O_CONV_S + ((size_t)((row - MP) >> 4) * 3 + (l - 13)) * 2048 + col) = v; }
;         } else if (col < 3072) st_bf4(z1 + (size_t)row * D + (col - 2048), v[0], v[1], v[2], v[3]);
;         else if (col < 3088) *(f32x4*)(ba + (size_t)row * 16 + (col - 3072)) = v;
	v_mfma_f32_16x16x32_bf16 v[20:23], v[100:103], v[104:107], v[20:23]
	v_mfma_f32_16x16x32_bf16 v[16:19], v[112:115], v[104:107], v[16:19]
	v_mfma_f32_16x16x32_bf16 v[12:15], v[116:119], v[104:107], v[12:15]
	v_mfma_f32_16x16x32_bf16 v[8:11], v[96:99], v[108:111], v[8:11]
	v_mfma_f32_16x16x32_bf16 v[4:7], v[100:103], v[108:111], v[4:7]
	v_mfma_f32_16x16x32_bf16 v[48:51], v[112:115], v[108:111], v[48:51]
	v_mfma_f32_16x16x32_bf16 v[0:3], v[116:119], v[108:111], v[0:3]
	s_cbranch_scc1 .LBB0_1584
	v_add_u32_e32 v68, v84, v94
	v_add_u32_e32 v85, v68, v91
	ds_read_b128 v[64:67], v85 offset:49152
	ds_read_b128 v[72:75], v85 offset:51200
	ds_read_b128 v[76:79], v85 offset:53248
	ds_read_b128 v[94:97], v85 offset:55296
	v_add_u32_e32 v88, v68, v89
	ds_read_b128 v[68:71], v88 offset:32768
	v_add_u32_e32 v84, v84, v92
	v_add_u32_e32 v85, v84, v91
	v_add_u32_e32 v84, v84, v89
	s_waitcnt lgkmcnt(0)
	v_mfma_f32_16x16x32_bf16 v[60:63], v[64:67], v[68:71], v[60:63]
	s_add_u32 s24, s22, 0x11900000
	s_addc_u32 s25, s23, 0
	s_add_u32 s26, s22, 0x9880000
	v_mfma_f32_16x16x32_bf16 v[56:59], v[72:75], v[68:71], v[56:59]
	s_addc_u32 s27, s23, 0
	s_add_u32 s22, s22, 0x1110000
	s_movk_i32 s0, 0x7ff
	v_mfma_f32_16x16x32_bf16 v[52:55], v[76:79], v[68:71], v[52:55]
	s_addc_u32 s23, s23, 0
	v_mfma_f32_16x16x32_bf16 v[44:47], v[94:97], v[68:71], v[44:47]
	ds_read_b128 v[68:71], v88 offset:34816
	s_waitcnt lgkmcnt(0)
	v_mfma_f32_16x16x32_bf16 v[40:43], v[64:67], v[68:71], v[40:43]
	v_mfma_f32_16x16x32_bf16 v[36:39], v[72:75], v[68:71], v[36:39]
	v_mfma_f32_16x16x32_bf16 v[32:35], v[76:79], v[68:71], v[32:35]
	v_mfma_f32_16x16x32_bf16 v[28:31], v[94:97], v[68:71], v[28:31]
	ds_read_b128 v[68:71], v88 offset:36864
	s_waitcnt lgkmcnt(0)
	v_mfma_f32_16x16x32_bf16 v[24:27], v[64:67], v[68:71], v[24:27]
	v_mfma_f32_16x16x32_bf16 v[20:23], v[72:75], v[68:71], v[20:23]
	v_mfma_f32_16x16x32_bf16 v[16:19], v[76:79], v[68:71], v[16:19]
	v_mfma_f32_16x16x32_bf16 v[12:15], v[94:97], v[68:71], v[12:15]
	ds_read_b128 v[68:71], v88 offset:38912
	ds_read_b128 v[88:91], v85 offset:55296
	s_waitcnt lgkmcnt(1)
	v_mfma_f32_16x16x32_bf16 v[8:11], v[64:67], v[68:71], v[8:11]
	v_mfma_f32_16x16x32_bf16 v[4:7], v[72:75], v[68:71], v[4:7]
	ds_read_b128 v[72:75], v85 offset:49152
	v_mfma_f32_16x16x32_bf16 v[64:67], v[76:79], v[68:71], v[48:51]
	ds_read_b128 v[76:79], v85 offset:53248
	v_mfma_f32_16x16x32_bf16 v[0:3], v[94:97], v[68:71], v[0:3]
	ds_read_b128 v[68:71], v85 offset:51200
	ds_read_b128 v[48:51], v84 offset:32768
	ds_read_b128 v[92:95], v84 offset:34816
	s_waitcnt lgkmcnt(1)
	v_mfma_f32_16x16x32_bf16 v[60:63], v[72:75], v[48:51], v[60:63]
	ds_read_b128 v[96:99], v84 offset:38912
	v_mfma_f32_16x16x32_bf16 v[56:59], v[68:71], v[48:51], v[56:59]
	v_mfma_f32_16x16x32_bf16 v[52:55], v[76:79], v[48:51], v[52:55]
	v_mfma_f32_16x16x32_bf16 v[48:51], v[88:91], v[48:51], v[44:47]
	s_waitcnt lgkmcnt(1)
	v_mfma_f32_16x16x32_bf16 v[44:47], v[72:75], v[92:95], v[40:43]
	v_mfma_f32_16x16x32_bf16 v[40:43], v[68:71], v[92:95], v[36:39]
	v_mfma_f32_16x16x32_bf16 v[36:39], v[76:79], v[92:95], v[32:35]
	v_mfma_f32_16x16x32_bf16 v[32:35], v[88:91], v[92:95], v[28:31]
	ds_read_b128 v[92:95], v84 offset:36864
	s_waitcnt vmcnt(0)
	s_waitcnt lgkmcnt(0)
	v_mfma_f32_16x16x32_bf16 v[28:31], v[72:75], v[92:95], v[24:27]
	s_barrier
	v_mfma_f32_16x16x32_bf16 v[24:27], v[68:71], v[92:95], v[20:23]
	v_mfma_f32_16x16x32_bf16 v[20:23], v[76:79], v[92:95], v[16:19]
	v_mfma_f32_16x16x32_bf16 v[16:19], v[88:91], v[92:95], v[12:15]
	v_mfma_f32_16x16x32_bf16 v[12:15], v[72:75], v[96:99], v[8:11]
	v_mfma_f32_16x16x32_bf16 v[8:11], v[68:71], v[96:99], v[4:7]
	v_lshlrev_b32_e32 v69, 6, v83
	v_lshlrev_b32_e32 v70, 2, v86
	v_lshlrev_b32_e32 v68, 6, v87
	v_mfma_f32_16x16x32_bf16 v[4:7], v[76:79], v[96:99], v[64:67]
	v_mfma_f32_16x16x32_bf16 v[0:3], v[88:91], v[96:99], v[0:3]
	s_nop 1
	v_or3_b32 v64, v70, v69, v82
	v_or3_b32 v66, v68, v81, v80
	v_cmp_lt_i32_e64 s[14:15], s0, v64
	s_and_saveexec_b64 s[0:1], s[14:15]
	s_xor_b64 s[0:1], exec, s[0:1]
	s_cbranch_execz .LBB0_1593
	s_movk_i32 s2, 0xbff
	v_cmp_lt_u32_e32 vcc, s2, v82
	s_and_saveexec_b64 s[2:3], vcc
	s_xor_b64 s[2:3], exec, s[2:3]
	s_cbranch_execz .LBB0_1590
	s_movk_i32 s4, 0xc10
	v_cmp_gt_u32_e32 vcc, s4, v64
	s_and_saveexec_b64 s[4:5], vcc
	s_cbranch_execz .LBB0_1589
	v_ashrrev_i32_e32 v67, 31, v66
	v_lshlrev_b64 v[68:69], 6, v[66:67]
	v_lshl_add_u64 v[68:69], s[22:23], 0, v[68:69]
	v_mov_b32_e32 v65, 0
	v_lshl_add_u64 v[68:69], v[64:65], 2, v[68:69]
	v_add_co_u32_e32 v68, vcc, 0xffffd000, v68
	s_nop 1
	v_addc_co_u32_e32 v69, vcc, -1, v69, vcc
	global_store_dwordx4 v[68:69], v[60:63], off

; #define MFMA16(a, b, c) __builtin_amdgcn_mfma_f32_16x16x32_bf16((a), (b), (c), 0, 0, 0)
; #define LAS __attribute__((address_space(3)))
; template <class FA, class FB, class FL, class FS>
; DI void gemm_tile(char* lds, int ksteps, int rot, FA fa, FB fb, FL fl, FS fs) {
;     ...
;   for (int ks = 0; ks < ksteps; ++ks) {
;     const int cur = ks & 1;
;     if (ks + 1 < ksteps) {
;       int kn = ks + 1 + rot; if (kn >= ksteps) kn -= ksteps;
;       LAS char* dst = l3 + (cur ^ 1) * 32768;
; #pragma unroll
;       for (int i = 0; i < 4; ++i) {
;         const int id = tid + i * 256, r = id >> 3, c = (id & 7) ^ (r & 7);
;         __builtin_amdgcn_global_load_lds((const unsigned*)fa(r, kn * 8 + c), (LAS unsigned*)(dst + id * 16), 16, 0, 0);
;         __builtin_amdgcn_global_load_lds((const unsigned*)fb(r, kn * 8 + c), (LAS unsigned*)(dst + 16384 + id * 16), 16, 0, 0);
;       }
;     }
;     const char* A = lds + cur * 32768;
;     const char* B = A + 16384;
; #pragma unroll
;     for (int kk = 0; kk < 2; ++kk) {
;       bf16x8 af[4], bq[4];
; #pragma unroll
;       for (int m = 0; m < 4; ++m) af[m] = ldfrag(A, 128, wr * 64 + m * 16 + fr, kk * 4 + fq);
; #pragma unroll
;       for (int n = 0; n < 4; ++n) bq[n] = ldfrag(B, 128, wc * 64 + n * 16 + fr, kk * 4 + fq);
; #pragma unroll
;       for (int m = 0; m < 4; ++m)
; #pragma unroll
;         for (int n = 0; n < 4; ++n) acc[m][n] = MFMA16(bq[n], af[m], acc[m][n]);
;     }
;     asm volatile("s_waitcnt vmcnt(0)" ::: "memory");
;     __syncthreads();
.LBB0_1952:
	s_and_b32 s2, s4, 0x8000
	s_xor_b32 s3, s2, 0x8000
	v_add_u32_e32 v105, s2, v72
	v_add_u32_e32 v100, s3, v72
	v_add_u32_e32 v101, v105, v73
	v_add_u32_e32 v102, v100, v68
	v_add_u32_e32 v114, v101, v104
	v_add_u32_e32 v112, v101, v74
	v_readfirstlane_b32 s2, v102
	v_add_u32_e32 v101, 0x4000, v102
	v_lshl_add_u64 v[80:81], v[64:65], 0, s[0:1]
	v_add_u32_e32 v103, v100, v69
	v_readfirstlane_b32 s7, v101
	s_mov_b32 m0, s2
	v_lshl_add_u64 v[82:83], v[66:67], 0, s[0:1]
	v_readfirstlane_b32 s3, v103
	v_add_u32_e32 v102, 0x4000, v103
	global_load_lds_dwordx4 v[80:81], off
	s_mov_b32 m0, s7
	v_lshl_add_u64 v[84:85], v[60:61], 0, s[0:1]
	v_add_u32_e32 v106, v100, v70
	v_readfirstlane_b32 s14, v102
	global_load_lds_dwordx4 v[82:83], off
	s_mov_b32 m0, s3
	v_lshl_add_u64 v[86:87], v[62:63], 0, s[0:1]
	v_readfirstlane_b32 s5, v106
	v_add_u32_e32 v103, 0x4000, v106
	global_load_lds_dwordx4 v[84:85], off
	s_mov_b32 m0, s14
	v_lshl_add_u64 v[88:89], v[56:57], 0, s[0:1]
	v_add_u32_e32 v100, v100, v71
	v_readfirstlane_b32 s15, v103
	global_load_lds_dwordx4 v[86:87], off
	s_mov_b32 m0, s5
	v_lshl_add_u64 v[90:91], v[58:59], 0, s[0:1]
	v_readfirstlane_b32 s6, v100
	v_add_u32_e32 v100, 0x4000, v100
	global_load_lds_dwordx4 v[88:89], off
	s_mov_b32 m0, s15
	v_lshl_add_u64 v[96:97], v[52:53], 0, s[0:1]
	v_readfirstlane_b32 s16, v100
	global_load_lds_dwordx4 v[90:91], off
	s_mov_b32 m0, s6
	v_lshl_add_u64 v[98:99], v[54:55], 0, s[0:1]
	global_load_lds_dwordx4 v[96:97], off
	s_mov_b32 m0, s16
	s_add_i32 s4, s4, 0x8000
	global_load_lds_dwordx4 v[98:99], off
	ds_read_b128 v[80:83], v112 offset:16384
	ds_read_b128 v[84:87], v112 offset:18432
	ds_read_b128 v[88:91], v114
	ds_read_b128 v[96:99], v114 offset:2048
	s_waitcnt lgkmcnt(0)
	v_mfma_f32_16x16x32_bf16 v[100:103], v[80:83], v[88:91], v[108:111]
	s_nop 2
	ds_read_b128 v[106:109], v112 offset:20480
	ds_read_b128 v[110:113], v112 offset:22528
	s_add_u32 s0, s0, 0x80
	v_mfma_f32_16x16x32_bf16 v[92:95], v[84:87], v[88:91], v[92:95]
	s_addc_u32 s1, s1, 0
	s_cmpk_lg_i32 s0, 0x780
	s_waitcnt lgkmcnt(1)
	v_mfma_f32_16x16x32_bf16 v[76:79], v[106:109], v[88:91], v[76:79]
	s_waitcnt lgkmcnt(0)
	v_mfma_f32_16x16x32_bf16 v[48:51], v[110:113], v[88:91], v[48:51]
	v_mfma_f32_16x16x32_bf16 v[44:47], v[80:83], v[96:99], v[44:47]
	v_mfma_f32_16x16x32_bf16 v[40:43], v[84:87], v[96:99], v[40:43]
	v_mfma_f32_16x16x32_bf16 v[36:39], v[106:109], v[96:99], v[36:39]
	v_mfma_f32_16x16x32_bf16 v[32:35], v[110:113], v[96:99], v[32:35]
	ds_read_b128 v[88:91], v114 offset:4096
	ds_read_b128 v[96:99], v114 offset:6144
	s_waitcnt lgkmcnt(1)
	v_mfma_f32_16x16x32_bf16 v[28:31], v[80:83], v[88:91], v[28:31]
	s_waitcnt lgkmcnt(0)
	v_mfma_f32_16x16x32_bf16 v[12:15], v[80:83], v[96:99], v[12:15]
	v_add_u32_e32 v80, v105, v75
	v_add_u32_e32 v105, v80, v104
	v_add_u32_e32 v114, v80, v74
	v_mfma_f32_16x16x32_bf16 v[24:27], v[84:87], v[88:91], v[24:27]
	v_mfma_f32_16x16x32_bf16 v[20:23], v[106:109], v[88:91], v[20:23]
	v_mfma_f32_16x16x32_bf16 v[16:19], v[110:113], v[88:91], v[16:19]
	v_mfma_f32_16x16x32_bf16 v[4:7], v[84:87], v[96:99], v[4:7]
	ds_read_b128 v[80:83], v114 offset:16384
	ds_read_b128 v[84:87], v114 offset:18432
	v_mfma_f32_16x16x32_bf16 v[8:11], v[106:109], v[96:99], v[8:11]
	v_mfma_f32_16x16x32_bf16 v[0:3], v[110:113], v[96:99], v[0:3]
	ds_read_b128 v[88:91], v105
	ds_read_b128 v[96:99], v105 offset:2048
	s_waitcnt lgkmcnt(1)
	v_mfma_f32_16x16x32_bf16 v[108:111], v[80:83], v[88:91], v[100:103]
	s_nop 2
	ds_read_b128 v[100:103], v114 offset:20480
	ds_read_b128 v[112:115], v114 offset:22528
	v_mfma_f32_16x16x32_bf16 v[92:95], v[84:87], v[88:91], v[92:95]
	s_waitcnt lgkmcnt(1)
	v_mfma_f32_16x16x32_bf16 v[76:79], v[100:103], v[88:91], v[76:79]
	s_waitcnt lgkmcnt(0)
	v_mfma_f32_16x16x32_bf16 v[48:51], v[112:115], v[88:91], v[48:51]
	v_mfma_f32_16x16x32_bf16 v[44:47], v[80:83], v[96:99], v[44:47]
	v_mfma_f32_16x16x32_bf16 v[40:43], v[84:87], v[96:99], v[40:43]
	v_mfma_f32_16x16x32_bf16 v[36:39], v[100:103], v[96:99], v[36:39]
	v_mfma_f32_16x16x32_bf16 v[32:35], v[112:115], v[96:99], v[32:35]
	ds_read_b128 v[88:91], v105 offset:4096
	ds_read_b128 v[96:99], v105 offset:6144
	s_waitcnt vmcnt(0)
	s_waitcnt lgkmcnt(0)
	v_mfma_f32_16x16x32_bf16 v[28:31], v[80:83], v[88:91], v[28:31]
	s_barrier
	v_mfma_f32_16x16x32_bf16 v[24:27], v[84:87], v[88:91], v[24:27]
	v_mfma_f32_16x16x32_bf16 v[20:23], v[100:103], v[88:91], v[20:23]
	v_mfma_f32_16x16x32_bf16 v[16:19], v[112:115], v[88:91], v[16:19]
	v_mfma_f32_16x16x32_bf16 v[12:15], v[80:83], v[96:99], v[12:15]
	v_mfma_f32_16x16x32_bf16 v[4:7], v[84:87], v[96:99], v[4:7]
	v_mfma_f32_16x16x32_bf16 v[8:11], v[100:103], v[96:99], v[8:11]
	v_mfma_f32_16x16x32_bf16 v[0:3], v[112:115], v[96:99], v[0:3]
	s_cbranch_scc1 .LBB0_1952
; DI float4 ldnt4(const float* p) { const f32x4 v = __builtin_nontemporal_load((const f32x4*)p); float4 r; r.x = v[0]; r.y = v[1]; r.z = v[2]; r.w = v[3]; return r; }
; DI void st_bf4(bf16_t* p, float a, float b, float c, float d) { uint2 v; v.x = pack2(a, b); v.y = pack2(c, d); *(uint2*)p = v; }
; template <class FA, class FB, class FL, class FS>
; DI void gemm_tile(char* lds, int ksteps, int rot, FA fa, FB fb, FL fl, FS fs) {
;     ...
;   decltype(fl(0, 0)) ld[4][4];
; #pragma unroll
;   for (int m = 0; m < 4; ++m)
; #pragma unroll
;     for (int n = 0; n < 4; ++n) ld[m][n] = fl(wr * 64 + m * 16 + fr, wc * 64 + n * 16 + 4 * fq);
; #pragma unroll
;   for (int m = 0; m < 4; ++m)
; #pragma unroll
;     for (int n = 0; n < 4; ++n) fs(wr * 64 + m * 16 + fr, wc * 64 + n * 16 + 4 * fq, acc[m][n], ld[m][n]);
; DI void phase_gout(const Params& p, const Sub& s, char* lds_all, int layer, const bf16_t* A, const bf16_t* Bt) {
;     ...
;       [&](int row, int col) {
;         const bf16_t* x1b = (const bf16_t*)p.out;
;         float4 x4;
;         if (layer == 0) x4 = ldnt4(xrow(p, row) + col);
;         else ld_bf4(x1b + (size_t)row * D + col, x4.x, x4.y, x4.z, x4.w);
;         Ld2 r; r.a = x4; r.b = *(const float4*)(mod + (size_t)(row_bi(row) * 2 + layer) * 3072 + 2048 + col);
;         return r;
;       },
;       [&](int row, int col, f32x4 v, const Ld2& l2) {
;         const float4 x4 = l2.a, g4 = l2.b;
;         bf16_t* x1b = (bf16_t*)p.out;
;         bf16_t* x2b = (bf16_t*)(p.ws + W_SLOT3);
;         st_bf4((layer == 0 ? x1b : x2b) + (size_t)row * D + col, x4.x + g4.x * v[0], x4.y + g4.y * v[1], x4.z + g4.z * v[2], x4.w + g4.w * v[3]);
;       });
	v_lshlrev_b32_e32 v125, 6, v125
	v_lshlrev_b32_e32 v121, 6, v121
	v_lshlrev_b32_e32 v123, 2, v123
	v_or3_b32 v122, v125, v122, v124
	v_or3_b32 v140, v123, v121, v120
	v_ashrrev_i32_e32 v123, 31, v122
	v_lshlrev_b64 v[142:143], 11, v[122:123]
	v_add_u32_e32 v123, 0xffff0000, v122
	v_add_u32_e32 v56, v72, v75
	v_add_u32_e32 v64, v72, v73
	s_mov_b32 s4, 0x10000
	v_lshrrev_b32_e32 v123, 4, v123
	s_add_u32 s0, s10, 0x1080000
	v_add_u32_e32 v57, v56, v74
	v_add_u32_e32 v60, v56, v104
	v_add_u32_e32 v65, v64, v74
	v_add_u32_e32 v126, v64, v104
	v_ashrrev_i32_e32 v141, 31, v140
	v_ashrrev_i32_e32 v158, 13, v124
	v_add_u32_e32 v123, 8, v123
	v_cmp_gt_i32_e32 vcc, s4, v122
	s_addc_u32 s1, s11, 0
	ds_read_b128 v[52:55], v57 offset:55296
	ds_read_b128 v[68:71], v57 offset:53248
	ds_read_b128 v[80:83], v57 offset:51200
	ds_read_b128 v[88:91], v57 offset:49152
	ds_read_b128 v[56:59], v60 offset:38912
	ds_read_b128 v[100:103], v60 offset:36864
	ds_read_b128 v[112:115], v60 offset:34816
	ds_read_b128 v[128:131], v60 offset:32768
	ds_read_b128 v[60:63], v65 offset:55296
	ds_read_b128 v[72:75], v65 offset:53248
	ds_read_b128 v[84:87], v65 offset:51200
	ds_read_b128 v[96:99], v65 offset:49152
	ds_read_b128 v[64:67], v126 offset:38912
	ds_read_b128 v[104:107], v126 offset:36864
	ds_read_b128 v[116:119], v126 offset:34816
	ds_read_b128 v[132:135], v126 offset:32768
	v_lshl_add_u64 v[126:127], s[8:9], 0, v[142:143]
	v_lshlrev_b64 v[120:121], 1, v[140:141]
	v_cndmask_b32_e32 v123, v123, v158, vcc
	v_lshl_add_u64 v[144:145], v[126:127], 0, v[120:121]
	v_lshl_or_b32 v123, v123, 1, 1
	s_movk_i32 s5, 0x3000
	v_mov_b64_e32 v[126:127], s[0:1]
	v_mad_i64_i32 v[124:125], s[0:1], v123, s5, v[126:127]
	s_mov_b64 s[0:1], 0x2000
	s_nop 0
	v_lshl_add_u64 v[152:153], v[124:125], 0, s[0:1]
	v_lshlrev_b64 v[124:125], 2, v[140:141]
	s_waitcnt vmcnt(0)
	s_waitcnt lgkmcnt(0)
	s_barrier
	global_load_dwordx2 v[150:151], v[144:145], off
	v_lshl_add_u64 v[136:137], v[152:153], 0, v[124:125]
	global_load_dwordx4 v[136:139], v[136:137], off
	v_mfma_f32_16x16x32_bf16 v[108:111], v[96:99], v[132:135], v[108:111]
	s_add_u32 s2, s10, 0x19980000
	s_addc_u32 s3, s11, 0
	v_or_b32_e32 v154, 16, v140
	v_mfma_f32_16x16x32_bf16 v[108:111], v[88:91], v[128:131], v[108:111]
	v_lshl_add_u64 v[142:143], s[2:3], 0, v[142:143]
	v_ashrrev_i32_e32 v155, 31, v154
	v_lshl_add_u64 v[142:143], v[142:143], 0, v[120:121]
	v_mfma_f32_16x16x32_bf16 v[92:95], v[84:87], v[132:135], v[92:95]
	s_waitcnt vmcnt(1)
	v_lshlrev_b32_e32 v156, 16, v150
	v_and_b32_e32 v157, 0xffff0000, v150
	v_lshlrev_b32_e32 v150, 16, v151
	v_and_b32_e32 v151, 0xffff0000, v151
	s_waitcnt vmcnt(0)
	v_pk_fma_f32 v[108:109], v[108:109], v[136:137], v[156:157]
	v_pk_fma_f32 v[110:111], v[110:111], v[138:139], v[150:151]
	v_cvt_pk_bf16_f32 v108, v108, v109
	v_cvt_pk_bf16_f32 v109, v110, v111
	global_store_dwordx2 v[142:143], v[108:109], off
	v_lshlrev_b64 v[108:109], 2, v[154:155]
	global_load_dwordx2 v[110:111], v[144:145], off offset:32
	v_lshl_add_u64 v[136:137], v[152:153], 0, v[108:109]
	global_load_dwordx4 v[136:139], v[136:137], off
	v_mfma_f32_16x16x32_bf16 v[92:95], v[80:83], v[128:131], v[92:95]
	v_or_b32_e32 v150, 32, v140
	v_ashrrev_i32_e32 v151, 31, v150
	s_waitcnt vmcnt(1)
	v_lshlrev_b32_e32 v154, 16, v110
	v_and_b32_e32 v155, 0xffff0000, v110
	v_lshlrev_b32_e32 v110, 16, v111
	v_and_b32_e32 v111, 0xffff0000, v111
	s_waitcnt vmcnt(0)
	v_pk_fma_f32 v[92:93], v[92:93], v[136:137], v[154:155]
	v_pk_fma_f32 v[94:95], v[94:95], v[138:139], v[110:111]
	v_cvt_pk_bf16_f32 v92, v92, v93
	v_cvt_pk_bf16_f32 v93, v94, v95
	global_store_dwordx2 v[142:143], v[92:93], off offset:32
	v_lshlrev_b64 v[92:93], 2, v[150:151]
	global_load_dwordx2 v[94:95], v[144:145], off offset:64
	v_lshl_add_u64 v[110:111], v[152:153], 0, v[92:93]
	global_load_dwordx4 v[136:139], v[110:111], off
	v_mfma_f32_16x16x32_bf16 v[76:79], v[72:75], v[132:135], v[76:79]
	v_or_b32_e32 v110, 48, v140
	v_ashrrev_i32_e32 v111, 31, v110
	s_waitcnt vmcnt(1)
	v_lshlrev_b32_e32 v140, 16, v94
	v_mfma_f32_16x16x32_bf16 v[76:79], v[68:71], v[128:131], v[76:79]
	v_and_b32_e32 v141, 0xffff0000, v94
	v_lshlrev_b32_e32 v94, 16, v95
	v_and_b32_e32 v95, 0xffff0000, v95
	v_mfma_f32_16x16x32_bf16 v[48:51], v[60:63], v[132:135], v[48:51]
	v_mfma_f32_16x16x32_bf16 v[48:51], v[52:55], v[128:131], v[48:51]
	s_waitcnt vmcnt(0)
	s_nop 1
	v_pk_fma_f32 v[76:77], v[76:77], v[136:137], v[140:141]
	v_pk_fma_f32 v[78:79], v[78:79], v[138:139], v[94:95]
	v_cvt_pk_bf16_f32 v76, v76, v77
	v_cvt_pk_bf16_f32 v77, v78, v79
	global_store_dwordx2 v[142:143], v[76:77], off offset:64
	v_lshlrev_b64 v[76:77], 2, v[110:111]
	global_load_dwordx2 v[78:79], v[144:145], off offset:96
	v_lshl_add_u64 v[94:95], v[152:153], 0, v[76:77]
	global_load_dwordx4 v[136:139], v[94:95], off
	v_or_b32_e32 v94, 16, v122
	v_add_u32_e32 v110, 0xffff0010, v122
	v_ashrrev_i32_e32 v95, 31, v94
	v_lshrrev_b32_e32 v123, 4, v110
	v_lshlrev_b64 v[110:111], 11, v[94:95]
	v_add_u32_e32 v95, 8, v123
	v_cmp_gt_i32_e32 vcc, s4, v94
	v_lshl_add_u64 v[140:141], s[8:9], 0, v[110:111]
	v_mfma_f32_16x16x32_bf16 v[44:47], v[96:99], v[116:119], v[44:47]
	v_cndmask_b32_e32 v123, v95, v158, vcc
	v_lshl_or_b32 v123, v123, 1, 1
	v_mad_i64_i32 v[132:133], s[6:7], v123, s5, v[126:127]
	v_lshl_add_u64 v[94:95], v[140:141], 0, v[120:121]
	v_mfma_f32_16x16x32_bf16 v[44:47], v[88:91], v[112:115], v[44:47]
	v_lshl_add_u64 v[110:111], s[2:3], 0, v[110:111]
	v_lshl_add_u64 v[110:111], v[110:111], 0, v[120:121]
	s_waitcnt vmcnt(1)
	v_lshlrev_b32_e32 v128, 16, v78
	v_and_b32_e32 v129, 0xffff0000, v78
	v_lshlrev_b32_e32 v78, 16, v79
	v_and_b32_e32 v79, 0xffff0000, v79
	s_waitcnt vmcnt(0)
; DI float4 ldnt4(const float* p) { const f32x4 v = __builtin_nontemporal_load((const f32x4*)p); float4 r; r.x = v[0]; r.y = v[1]; r.z = v[2]; r.w = v[3]; return r; }
; DI void st_bf4(bf16_t* p, float a, float b, float c, float d) { uint2 v; v.x = pack2(a, b); v.y = pack2(c, d); *(uint2*)p = v; }
; template <class FA, class FB, class FL, class FS>
; DI void gemm_tile(char* lds, int ksteps, int rot, FA fa, FB fb, FL fl, FS fs) {
;     ...
;   decltype(fl(0, 0)) ld[4][4];
; #pragma unroll
;   for (int m = 0; m < 4; ++m)
; #pragma unroll
;     for (int n = 0; n < 4; ++n) ld[m][n] = fl(wr * 64 + m * 16 + fr, wc * 64 + n * 16 + 4 * fq);
; #pragma unroll
;   for (int m = 0; m < 4; ++m)
; #pragma unroll
;     for (int n = 0; n < 4; ++n) fs(wr * 64 + m * 16 + fr, wc * 64 + n * 16 + 4 * fq, acc[m][n], ld[m][n]);
; DI void phase_gout(const Params& p, const Sub& s, char* lds_all, int layer, const bf16_t* A, const bf16_t* Bt) {
;     ...
;       [&](int row, int col) {
;         const bf16_t* x1b = (const bf16_t*)p.out;
;         float4 x4;
;         if (layer == 0) x4 = ldnt4(xrow(p, row) + col);
;         else ld_bf4(x1b + (size_t)row * D + col, x4.x, x4.y, x4.z, x4.w);
;         Ld2 r; r.a = x4; r.b = *(const float4*)(mod + (size_t)(row_bi(row) * 2 + layer) * 3072 + 2048 + col);
;         return r;
;       },
;       [&](int row, int col, f32x4 v, const Ld2& l2) {
;         const float4 x4 = l2.a, g4 = l2.b;
;         bf16_t* x1b = (bf16_t*)p.out;
;         bf16_t* x2b = (bf16_t*)(p.ws + W_SLOT3);
;         st_bf4((layer == 0 ? x1b : x2b) + (size_t)row * D + col, x4.x + g4.x * v[0], x4.y + g4.y * v[1], x4.z + g4.z * v[2], x4.w + g4.w * v[3]);
;       });
	v_pk_fma_f32 v[48:49], v[48:49], v[136:137], v[128:129]
	v_pk_fma_f32 v[50:51], v[50:51], v[138:139], v[78:79]
	v_cvt_pk_bf16_f32 v48, v48, v49
	v_cvt_pk_bf16_f32 v49, v50, v51
	global_store_dwordx2 v[142:143], v[48:49], off offset:96
	v_lshl_add_u64 v[128:129], v[132:133], 0, s[0:1]
	global_load_dwordx2 v[78:79], v[94:95], off
	v_lshl_add_u64 v[48:49], v[128:129], 0, v[124:125]
	global_load_dwordx4 v[48:51], v[48:49], off
	v_mfma_f32_16x16x32_bf16 v[40:43], v[84:87], v[116:119], v[40:43]
	s_waitcnt vmcnt(1)
	v_lshlrev_b32_e32 v130, 16, v78
	v_and_b32_e32 v131, 0xffff0000, v78
	v_lshlrev_b32_e32 v78, 16, v79
	v_and_b32_e32 v79, 0xffff0000, v79
	s_waitcnt vmcnt(0)
	v_pk_fma_f32 v[44:45], v[44:45], v[48:49], v[130:131]
	v_pk_fma_f32 v[46:47], v[46:47], v[50:51], v[78:79]
	v_cvt_pk_bf16_f32 v44, v44, v45
	v_cvt_pk_bf16_f32 v45, v46, v47
	global_store_dwordx2 v[110:111], v[44:45], off
	global_load_dwordx2 v[48:49], v[94:95], off offset:32
	v_lshl_add_u64 v[44:45], v[128:129], 0, v[108:109]
	global_load_dwordx4 v[44:47], v[44:45], off
	v_mfma_f32_16x16x32_bf16 v[40:43], v[80:83], v[112:115], v[40:43]
	s_waitcnt vmcnt(1)
	v_lshlrev_b32_e32 v50, 16, v48
	v_and_b32_e32 v51, 0xffff0000, v48
	v_lshlrev_b32_e32 v48, 16, v49
	v_and_b32_e32 v49, 0xffff0000, v49
	s_waitcnt vmcnt(0)
	s_nop 1
	v_pk_fma_f32 v[40:41], v[40:41], v[44:45], v[50:51]
	v_pk_fma_f32 v[42:43], v[42:43], v[46:47], v[48:49]
	v_cvt_pk_bf16_f32 v40, v40, v41
	v_cvt_pk_bf16_f32 v41, v42, v43
	global_store_dwordx2 v[110:111], v[40:41], off offset:32
	global_load_dwordx2 v[44:45], v[94:95], off offset:64
	v_lshl_add_u64 v[40:41], v[128:129], 0, v[92:93]
	global_load_dwordx4 v[40:43], v[40:41], off
	v_mfma_f32_16x16x32_bf16 v[36:39], v[72:75], v[116:119], v[36:39]
	s_waitcnt vmcnt(1)
	v_lshlrev_b32_e32 v46, 16, v44
	v_mfma_f32_16x16x32_bf16 v[36:39], v[68:71], v[112:115], v[36:39]
	v_and_b32_e32 v47, 0xffff0000, v44
	v_lshlrev_b32_e32 v44, 16, v45
	v_and_b32_e32 v45, 0xffff0000, v45
	v_mfma_f32_16x16x32_bf16 v[32:35], v[60:63], v[116:119], v[32:35]
	v_mfma_f32_16x16x32_bf16 v[32:35], v[52:55], v[112:115], v[32:35]
	s_waitcnt vmcnt(0)
	s_nop 1
	v_pk_fma_f32 v[36:37], v[36:37], v[40:41], v[46:47]
	v_pk_fma_f32 v[38:39], v[38:39], v[42:43], v[44:45]
	v_cvt_pk_bf16_f32 v36, v36, v37
	v_cvt_pk_bf16_f32 v37, v38, v39
	global_store_dwordx2 v[110:111], v[36:37], off offset:64
	global_load_dwordx2 v[40:41], v[94:95], off offset:96
	v_lshl_add_u64 v[36:37], v[128:129], 0, v[76:77]
	global_load_dwordx4 v[36:39], v[36:37], off
	v_or_b32_e32 v42, 32, v122
	v_add_u32_e32 v44, 0xffff0020, v122
	v_ashrrev_i32_e32 v43, 31, v42
	v_lshrrev_b32_e32 v46, 4, v44
	v_lshlrev_b64 v[44:45], 11, v[42:43]
	v_add_u32_e32 v43, 8, v46
	v_cmp_gt_i32_e32 vcc, s4, v42
	v_lshl_add_u64 v[46:47], s[8:9], 0, v[44:45]
	v_mfma_f32_16x16x32_bf16 v[28:31], v[96:99], v[104:107], v[28:31]
	v_cndmask_b32_e32 v48, v43, v158, vcc
	v_lshl_add_u64 v[42:43], v[46:47], 0, v[120:121]
	v_lshl_or_b32 v46, v48, 1, 1
	v_mad_i64_i32 v[46:47], s[6:7], v46, s5, v[126:127]
	v_mfma_f32_16x16x32_bf16 v[28:31], v[88:91], v[100:103], v[28:31]
	s_waitcnt vmcnt(1)
	v_lshlrev_b32_e32 v48, 16, v40
	v_and_b32_e32 v49, 0xffff0000, v40
	v_lshlrev_b32_e32 v40, 16, v41
	v_and_b32_e32 v41, 0xffff0000, v41
	s_waitcnt vmcnt(0)
	v_pk_fma_f32 v[32:33], v[32:33], v[36:37], v[48:49]
	v_pk_fma_f32 v[34:35], v[34:35], v[38:39], v[40:41]
	v_cvt_pk_bf16_f32 v32, v32, v33
	v_cvt_pk_bf16_f32 v33, v34, v35
	global_store_dwordx2 v[110:111], v[32:33], off offset:96
	v_lshl_add_u64 v[38:39], v[46:47], 0, s[0:1]
	global_load_dwordx2 v[36:37], v[42:43], off
	v_lshl_add_u64 v[32:33], v[38:39], 0, v[124:125]
	global_load_dwordx4 v[32:35], v[32:33], off
	v_lshl_add_u64 v[40:41], s[2:3], 0, v[44:45]
	v_lshl_add_u64 v[40:41], v[40:41], 0, v[120:121]
	v_mfma_f32_16x16x32_bf16 v[24:27], v[84:87], v[104:107], v[24:27]
	s_waitcnt vmcnt(1)
	v_lshlrev_b32_e32 v44, 16, v36
	v_and_b32_e32 v45, 0xffff0000, v36
	v_lshlrev_b32_e32 v36, 16, v37
	v_and_b32_e32 v37, 0xffff0000, v37
	s_waitcnt vmcnt(0)
	v_pk_fma_f32 v[28:29], v[28:29], v[32:33], v[44:45]
	v_pk_fma_f32 v[30:31], v[30:31], v[34:35], v[36:37]
	v_cvt_pk_bf16_f32 v28, v28, v29
	v_cvt_pk_bf16_f32 v29, v30, v31
	global_store_dwordx2 v[40:41], v[28:29], off
	global_load_dwordx2 v[32:33], v[42:43], off offset:32
	v_lshl_add_u64 v[28:29], v[38:39], 0, v[108:109]
	global_load_dwordx4 v[28:31], v[28:29], off
	v_mfma_f32_16x16x32_bf16 v[24:27], v[80:83], v[100:103], v[24:27]
	s_waitcnt vmcnt(1)
	v_lshlrev_b32_e32 v34, 16, v32
	v_and_b32_e32 v35, 0xffff0000, v32
	v_lshlrev_b32_e32 v32, 16, v33
	v_and_b32_e32 v33, 0xffff0000, v33
	s_waitcnt vmcnt(0)
; DI float4 ldnt4(const float* p) { const f32x4 v = __builtin_nontemporal_load((const f32x4*)p); float4 r; r.x = v[0]; r.y = v[1]; r.z = v[2]; r.w = v[3]; return r; }
; DI void st_bf4(bf16_t* p, float a, float b, float c, float d) { uint2 v; v.x = pack2(a, b); v.y = pack2(c, d); *(uint2*)p = v; }
; template <class FA, class FB, class FL, class FS>
; DI void gemm_tile(char* lds, int ksteps, int rot, FA fa, FB fb, FL fl, FS fs) {
;     ...
;   decltype(fl(0, 0)) ld[4][4];
; #pragma unroll
;   for (int m = 0; m < 4; ++m)
; #pragma unroll
;     for (int n = 0; n < 4; ++n) ld[m][n] = fl(wr * 64 + m * 16 + fr, wc * 64 + n * 16 + 4 * fq);
; #pragma unroll
;   for (int m = 0; m < 4; ++m)
; #pragma unroll
;     for (int n = 0; n < 4; ++n) fs(wr * 64 + m * 16 + fr, wc * 64 + n * 16 + 4 * fq, acc[m][n], ld[m][n]);
; DI void phase_gout(const Params& p, const Sub& s, char* lds_all, int layer, const bf16_t* A, const bf16_t* Bt) {
;     ...
;       [&](int row, int col) {
;         const bf16_t* x1b = (const bf16_t*)p.out;
;         float4 x4;
;         if (layer == 0) x4 = ldnt4(xrow(p, row) + col);
;         else ld_bf4(x1b + (size_t)row * D + col, x4.x, x4.y, x4.z, x4.w);
;         Ld2 r; r.a = x4; r.b = *(const float4*)(mod + (size_t)(row_bi(row) * 2 + layer) * 3072 + 2048 + col);
;         return r;
;       },
;       [&](int row, int col, f32x4 v, const Ld2& l2) {
;         const float4 x4 = l2.a, g4 = l2.b;
;         bf16_t* x1b = (bf16_t*)p.out;
;         bf16_t* x2b = (bf16_t*)(p.ws + W_SLOT3);
;         st_bf4((layer == 0 ? x1b : x2b) + (size_t)row * D + col, x4.x + g4.x * v[0], x4.y + g4.y * v[1], x4.z + g4.z * v[2], x4.w + g4.w * v[3]);
;       });
	s_nop 1
	v_pk_fma_f32 v[24:25], v[24:25], v[28:29], v[34:35]
	v_pk_fma_f32 v[26:27], v[26:27], v[30:31], v[32:33]
	v_cvt_pk_bf16_f32 v24, v24, v25
	v_cvt_pk_bf16_f32 v25, v26, v27
	global_store_dwordx2 v[40:41], v[24:25], off offset:32
	global_load_dwordx2 v[28:29], v[42:43], off offset:64
	v_lshl_add_u64 v[24:25], v[38:39], 0, v[92:93]
	global_load_dwordx4 v[24:27], v[24:25], off
	v_mfma_f32_16x16x32_bf16 v[20:23], v[72:75], v[104:107], v[20:23]
	s_waitcnt vmcnt(1)
	v_lshlrev_b32_e32 v30, 16, v28
	v_mfma_f32_16x16x32_bf16 v[20:23], v[68:71], v[100:103], v[20:23]
	v_and_b32_e32 v31, 0xffff0000, v28
	v_lshlrev_b32_e32 v28, 16, v29
	v_and_b32_e32 v29, 0xffff0000, v29
	v_mfma_f32_16x16x32_bf16 v[16:19], v[60:63], v[104:107], v[16:19]
	v_mfma_f32_16x16x32_bf16 v[16:19], v[52:55], v[100:103], v[16:19]
	s_waitcnt vmcnt(0)
	s_nop 1
	v_pk_fma_f32 v[20:21], v[20:21], v[24:25], v[30:31]
	v_pk_fma_f32 v[22:23], v[22:23], v[26:27], v[28:29]
	v_cvt_pk_bf16_f32 v20, v20, v21
	v_cvt_pk_bf16_f32 v21, v22, v23
	global_store_dwordx2 v[40:41], v[20:21], off offset:64
	global_load_dwordx2 v[24:25], v[42:43], off offset:96
	v_lshl_add_u64 v[20:21], v[38:39], 0, v[76:77]
	global_load_dwordx4 v[20:23], v[20:21], off
	v_or_b32_e32 v26, 48, v122
	v_add_u32_e32 v28, 0xffff0030, v122
	v_ashrrev_i32_e32 v27, 31, v26
	v_lshrrev_b32_e32 v30, 4, v28
	v_lshlrev_b64 v[28:29], 11, v[26:27]
	v_add_u32_e32 v27, 8, v30
	v_cmp_gt_i32_e32 vcc, s4, v26
	v_lshl_add_u64 v[30:31], s[8:9], 0, v[28:29]
	v_mfma_f32_16x16x32_bf16 v[12:15], v[96:99], v[64:67], v[12:15]
	v_cndmask_b32_e32 v32, v27, v158, vcc
	v_lshl_add_u64 v[26:27], v[30:31], 0, v[120:121]
	v_lshl_or_b32 v30, v32, 1, 1
	v_mad_i64_i32 v[30:31], s[4:5], v30, s5, v[126:127]
	v_mfma_f32_16x16x32_bf16 v[12:15], v[88:91], v[56:59], v[12:15]
	s_waitcnt vmcnt(1)
	v_lshlrev_b32_e32 v32, 16, v24
	v_and_b32_e32 v33, 0xffff0000, v24
	v_lshlrev_b32_e32 v24, 16, v25
	v_and_b32_e32 v25, 0xffff0000, v25
	s_waitcnt vmcnt(0)
	v_pk_fma_f32 v[16:17], v[16:17], v[20:21], v[32:33]
	v_pk_fma_f32 v[18:19], v[18:19], v[22:23], v[24:25]
	v_cvt_pk_bf16_f32 v16, v16, v17
	v_cvt_pk_bf16_f32 v17, v18, v19
	global_store_dwordx2 v[40:41], v[16:17], off offset:96
	v_lshl_add_u64 v[22:23], v[30:31], 0, s[0:1]
	global_load_dwordx2 v[20:21], v[26:27], off
	v_lshl_add_u64 v[16:17], v[22:23], 0, v[124:125]
	global_load_dwordx4 v[16:19], v[16:17], off
	v_lshl_add_u64 v[24:25], s[2:3], 0, v[28:29]
	v_lshl_add_u64 v[24:25], v[24:25], 0, v[120:121]
	v_mfma_f32_16x16x32_bf16 v[4:7], v[84:87], v[64:67], v[4:7]
	s_waitcnt vmcnt(1)
	v_lshlrev_b32_e32 v28, 16, v20
	v_and_b32_e32 v29, 0xffff0000, v20
	v_lshlrev_b32_e32 v20, 16, v21
	v_and_b32_e32 v21, 0xffff0000, v21
	s_waitcnt vmcnt(0)
	v_pk_fma_f32 v[12:13], v[12:13], v[16:17], v[28:29]
	v_pk_fma_f32 v[14:15], v[14:15], v[18:19], v[20:21]
	v_cvt_pk_bf16_f32 v12, v12, v13
	v_cvt_pk_bf16_f32 v13, v14, v15
	global_store_dwordx2 v[24:25], v[12:13], off
	global_load_dwordx2 v[16:17], v[26:27], off offset:32
	v_lshl_add_u64 v[12:13], v[22:23], 0, v[108:109]
	global_load_dwordx4 v[12:15], v[12:13], off
	v_mfma_f32_16x16x32_bf16 v[4:7], v[80:83], v[56:59], v[4:7]
	s_waitcnt vmcnt(1)
	v_lshlrev_b32_e32 v18, 16, v16
	v_and_b32_e32 v19, 0xffff0000, v16
	v_lshlrev_b32_e32 v16, 16, v17
	v_and_b32_e32 v17, 0xffff0000, v17
	s_waitcnt vmcnt(0)
	s_nop 1
	v_pk_fma_f32 v[4:5], v[4:5], v[12:13], v[18:19]
	v_pk_fma_f32 v[6:7], v[6:7], v[14:15], v[16:17]
	v_cvt_pk_bf16_f32 v4, v4, v5
	v_cvt_pk_bf16_f32 v5, v6, v7
	global_store_dwordx2 v[24:25], v[4:5], off offset:32
	global_load_dwordx2 v[12:13], v[26:27], off offset:64
	v_lshl_add_u64 v[14:15], v[22:23], 0, v[92:93]
	v_mfma_f32_16x16x32_bf16 v[4:7], v[72:75], v[64:67], v[8:11]
	s_nop 2
	global_load_dwordx4 v[8:11], v[14:15], off
	v_mfma_f32_16x16x32_bf16 v[4:7], v[68:71], v[56:59], v[4:7]
	s_waitcnt vmcnt(1)
	v_lshlrev_b32_e32 v14, 16, v12
	v_and_b32_e32 v15, 0xffff0000, v12
	v_lshlrev_b32_e32 v12, 16, v13
	v_and_b32_e32 v13, 0xffff0000, v13
	v_mfma_f32_16x16x32_bf16 v[0:3], v[60:63], v[64:67], v[0:3]
	s_waitcnt vmcnt(0)
	s_nop 0
	v_pk_fma_f32 v[4:5], v[4:5], v[8:9], v[14:15]
	v_pk_fma_f32 v[6:7], v[6:7], v[10:11], v[12:13]
	v_cvt_pk_bf16_f32 v4, v4, v5
	v_cvt_pk_bf16_f32 v5, v6, v7
	global_store_dwordx2 v[24:25], v[4:5], off offset:64
	global_load_dwordx2 v[8:9], v[26:27], off offset:96
	v_lshl_add_u64 v[4:5], v[22:23], 0, v[76:77]
	global_load_dwordx4 v[4:7], v[4:5], off
	v_mfma_f32_16x16x32_bf16 v[0:3], v[52:55], v[56:59], v[0:3]
	s_waitcnt vmcnt(1)
	v_lshlrev_b32_e32 v10, 16, v8
	v_and_b32_e32 v11, 0xffff0000, v8
	v_lshlrev_b32_e32 v8, 16, v9
	v_and_b32_e32 v9, 0xffff0000, v9
	s_waitcnt vmcnt(0)
	s_nop 1
	v_pk_fma_f32 v[0:1], v[0:1], v[4:5], v[10:11]
	v_pk_fma_f32 v[2:3], v[2:3], v[6:7], v[8:9]
	v_cvt_pk_bf16_f32 v0, v0, v1
	v_cvt_pk_bf16_f32 v1, v2, v3
	global_store_dwordx2 v[24:25], v[0:1], off offset:96
